# chunk_prep conv inputs staged in LDS by LDS-DMA one unit ahead (24 serialized global loads become ds_read) + mini GEMMs
# speedup vs baseline: 1.0528x; 1.0217x over previous
; #define LAS __attribute__((address_space(3)))
; #define BAR_LDS() do { asm volatile("s_waitcnt lgkmcnt(0)" ::: "memory"); __builtin_amdgcn_s_barrier(); asm volatile("" ::: "memory"); } while (0)
; __device__ __forceinline__ void conv16(const bf16_t* PROJ, const LAS float* cw, int rowbase, int t, int pcol, float (&y)[16]) {
;     u32x4 a[4], b[4];
; #pragma unroll
;     for (int i = 0; i < 4; ++i) {
;         const int tt = t - 3 + i, tc = tt < 0 ? 0 : tt;
;         a[i] = *(const u32x4*)(PROJ + (size_t)(rowbase + tc) * NQ + pcol); b[i] = *(const u32x4*)(PROJ + (size_t)(rowbase + tc) * NQ + pcol + 8);
;     }
; __device__ __forceinline__ void phase_chunk_prep(const Params& p, LAS unsigned char* lds, int wave_s) {
;     ...
;         if (h != cur_h) { cur_h = h;
;             for (int i = tid; i < 1536; i += 512) { const int which = i >> 9, tap = (i >> 7) & 3, dd = i & 127; CW[i] = p.in[11][(size_t)tap * 6144 + which * 2048 + h * 128 + dd]; }
;             BAR_LDS(); }
.LBB0_666:
	s_bfe_u32 s78, s16, 0x40005
	v_mov_b32_e32 v66, v208
	s_cmp_eq_u32 s78, s77
	s_cbranch_scc1 .LBB0_681
	s_lshr_b32 s84, s24, 6
	v_mbcnt_lo_u32_b32 v252, -1, 0
	v_mbcnt_hi_u32_b32 v252, -1, v252
	s_lshl_b32 s85, s16, 2
	s_and_b32 s85, s85, 0xfffff800
	s_lshl_b32 s86, s16, 6
	s_and_b32 s86, s86, 0x7c0
	s_lshl_b32 s94, s78, 8
	s_addk_i32 s94, 0x800
	v_lshrrev_b32_e32 v250, 4, v252
	v_and_b32_e32 v251, 15, v252
	v_lshlrev_b32_e32 v251, 4, v251
	s_add_i32 s95, s86, -3
	s_mul_i32 s85, s85, 0x4800
	s_add_i32 s94, s94, s85
	s_mov_b32 s86, s84
	s_cmp_gt_u32 s86, 16
	s_cselect_b32 s87, 1, 0
	s_cmp_gt_u32 s86, 33
	s_cselect_b32 s88, 1, 0
	s_add_i32 s87, s87, s88
	s_mul_i32 s88, s87, 17
	s_sub_i32 s88, s86, s88
	s_mul_i32 s89, s87, 0x4400
	s_cmp_eq_u32 s87, 2
	s_cselect_b32 s89, 0x1e200, s89
	s_lshl_b32 s90, s88, 10
	s_add_i32 s89, s89, s90
	s_lshl_b32 s91, s87, 12
	s_lshl_b32 s90, s88, 2
	s_add_i32 s90, s90, s95
	v_add_u32_e32 v252, s90, v250
	v_max_i32_e32 v252, 0, v252
	v_mul_u32_u24_e32 v252, 0x4800, v252
	v_add_u32_e32 v252, v252, v251
	s_add_i32 s90, s91, s94
	s_add_u32 s92, s28, s90
	s_addc_u32 s93, s29, 0
	s_mov_b32 m0, s89
	s_nop 0
	global_load_lds_dwordx4 v252, s[92:93]
	s_add_i32 s86, s84, 8
	s_cmp_gt_u32 s86, 16
	s_cselect_b32 s87, 1, 0
	s_cmp_gt_u32 s86, 33
	s_cselect_b32 s88, 1, 0
	s_add_i32 s87, s87, s88
	s_mul_i32 s88, s87, 17
	s_sub_i32 s88, s86, s88
	s_mul_i32 s89, s87, 0x4400
	s_cmp_eq_u32 s87, 2
	s_cselect_b32 s89, 0x1e200, s89
	s_lshl_b32 s90, s88, 10
	s_add_i32 s89, s89, s90
	s_lshl_b32 s91, s87, 12
	s_lshl_b32 s90, s88, 2
	s_add_i32 s90, s90, s95
	v_add_u32_e32 v252, s90, v250
	v_max_i32_e32 v252, 0, v252
	v_mul_u32_u24_e32 v252, 0x4800, v252
	v_add_u32_e32 v252, v252, v251
	s_add_i32 s90, s91, s94
	s_add_u32 s92, s28, s90
	s_addc_u32 s93, s29, 0
	s_mov_b32 m0, s89
	s_nop 0
	global_load_lds_dwordx4 v252, s[92:93]
	s_add_i32 s86, s84, 16
	s_cmp_gt_u32 s86, 16
	s_cselect_b32 s87, 1, 0
	s_cmp_gt_u32 s86, 33
	s_cselect_b32 s88, 1, 0
	s_add_i32 s87, s87, s88
	s_mul_i32 s88, s87, 17
	s_sub_i32 s88, s86, s88
	s_mul_i32 s89, s87, 0x4400
	s_cmp_eq_u32 s87, 2
	s_cselect_b32 s89, 0x1e200, s89
	s_lshl_b32 s90, s88, 10
	s_add_i32 s89, s89, s90
	s_lshl_b32 s91, s87, 12
	s_lshl_b32 s90, s88, 2
	s_add_i32 s90, s90, s95
	v_add_u32_e32 v252, s90, v250
	v_max_i32_e32 v252, 0, v252
	v_mul_u32_u24_e32 v252, 0x4800, v252
	v_add_u32_e32 v252, v252, v251
	s_add_i32 s90, s91, s94
	s_add_u32 s92, s28, s90
	s_addc_u32 s93, s29, 0
	s_mov_b32 m0, s89
	s_nop 0
	global_load_lds_dwordx4 v252, s[92:93]
	s_add_i32 s86, s84, 24
	s_cmp_gt_u32 s86, 16
	s_cselect_b32 s87, 1, 0
	s_cmp_gt_u32 s86, 33
	s_cselect_b32 s88, 1, 0
	s_add_i32 s87, s87, s88
	s_mul_i32 s88, s87, 17
	s_sub_i32 s88, s86, s88
	s_mul_i32 s89, s87, 0x4400
	s_cmp_eq_u32 s87, 2
	s_cselect_b32 s89, 0x1e200, s89
	s_lshl_b32 s90, s88, 10
	s_add_i32 s89, s89, s90
	s_lshl_b32 s91, s87, 12
	s_lshl_b32 s90, s88, 2
	s_add_i32 s90, s90, s95
	v_add_u32_e32 v252, s90, v250
	v_max_i32_e32 v252, 0, v252
	v_mul_u32_u24_e32 v252, 0x4800, v252
	v_add_u32_e32 v252, v252, v251
	s_add_i32 s90, s91, s94
	s_add_u32 s92, s28, s90
	s_addc_u32 s93, s29, 0
	s_mov_b32 m0, s89
	s_nop 0
	global_load_lds_dwordx4 v252, s[92:93]
	s_add_i32 s86, s84, 32
	s_cmp_gt_u32 s86, 16
	s_cselect_b32 s87, 1, 0
	s_cmp_gt_u32 s86, 33
	s_cselect_b32 s88, 1, 0
	s_add_i32 s87, s87, s88
	s_mul_i32 s88, s87, 17
	s_sub_i32 s88, s86, s88
	s_mul_i32 s89, s87, 0x4400
	s_cmp_eq_u32 s87, 2
	s_cselect_b32 s89, 0x1e200, s89
	s_lshl_b32 s90, s88, 10
	s_add_i32 s89, s89, s90
	s_lshl_b32 s91, s87, 12
	s_lshl_b32 s90, s88, 2
	s_add_i32 s90, s90, s95
	v_add_u32_e32 v252, s90, v250
	v_max_i32_e32 v252, 0, v252
	v_mul_u32_u24_e32 v252, 0x4800, v252
	v_add_u32_e32 v252, v252, v251
	s_add_i32 s90, s91, s94
	s_add_u32 s92, s28, s90
	s_addc_u32 s93, s29, 0
	s_mov_b32 m0, s89
	s_nop 0
	global_load_lds_dwordx4 v252, s[92:93]
	s_add_i32 s86, s84, 40
	s_cmp_gt_u32 s86, 16
	s_cselect_b32 s87, 1, 0
	s_cmp_gt_u32 s86, 33
	s_cselect_b32 s88, 1, 0
	s_add_i32 s87, s87, s88
	s_mul_i32 s88, s87, 17
	s_sub_i32 s88, s86, s88
	s_mul_i32 s89, s87, 0x4400
	s_cmp_eq_u32 s87, 2
	s_cselect_b32 s89, 0x1e200, s89
	s_lshl_b32 s90, s88, 10
	s_add_i32 s89, s89, s90
	s_lshl_b32 s91, s87, 12
	s_lshl_b32 s90, s88, 2
	s_add_i32 s90, s90, s95
	v_add_u32_e32 v252, s90, v250
	v_max_i32_e32 v252, 0, v252
	v_mul_u32_u24_e32 v252, 0x4800, v252
	v_add_u32_e32 v252, v252, v251
	s_add_i32 s90, s91, s94
	s_add_u32 s92, s28, s90
	s_addc_u32 s93, s29, 0
	s_mov_b32 m0, s89
	s_nop 0
	global_load_lds_dwordx4 v252, s[92:93]
	s_add_i32 s86, s84, 48
	s_cmp_gt_u32 s86, 50
	s_cbranch_scc1 .Lcpstage_f_end
	s_cmp_gt_u32 s86, 16
	s_cselect_b32 s87, 1, 0
	s_cmp_gt_u32 s86, 33
	s_cselect_b32 s88, 1, 0
	s_add_i32 s87, s87, s88
	s_mul_i32 s88, s87, 17
	s_sub_i32 s88, s86, s88
	s_mul_i32 s89, s87, 0x4400
	s_cmp_eq_u32 s87, 2
	s_cselect_b32 s89, 0x1e200, s89
	s_lshl_b32 s90, s88, 10
	s_add_i32 s89, s89, s90
	s_lshl_b32 s91, s87, 12
	s_lshl_b32 s90, s88, 2
	s_add_i32 s90, s90, s95
	v_add_u32_e32 v252, s90, v250
	v_max_i32_e32 v252, 0, v252
	v_mul_u32_u24_e32 v252, 0x4800, v252
	v_add_u32_e32 v252, v252, v251
	s_add_i32 s90, s91, s94
	s_add_u32 s92, s28, s90
	s_addc_u32 s93, s29, 0
	s_mov_b32 m0, s89
	s_nop 0
	global_load_lds_dwordx4 v252, s[92:93]
.Lcpstage_f_end:
	s_movk_i32 s4, 0x600
	v_cmp_gt_i32_e32 vcc, s4, v66
	s_and_saveexec_b64 s[4:5], vcc
	s_cbranch_execz .LBB0_680
	v_max_i32_e32 v0, 0x400, v66
	v_sub_u32_e32 v0, v0, v66
	v_add_u32_e32 v0, 0x1ff, v0
	s_lshl_b32 s17, s78, 7
	v_and_b32_e32 v4, 0x7f, v66
	v_cmp_lt_u32_e32 vcc, s42, v0
	s_mov_b64 s[34:35], -1
	v_mov_b32_e32 v2, v66
	s_and_saveexec_b64 s[30:31], vcc
	s_cbranch_execz .LBB0_677
	s_waitcnt lgkmcnt(0)
	v_lshrrev_b32_e32 v5, 9, v0
	v_add_u32_e32 v0, -1, v5
	v_add_u32_e32 v67, 0x200, v66
	v_lshrrev_b32_e32 v1, 1, v0
	v_add_u32_e32 v6, 1, v1
	v_cmp_lt_u32_e32 vcc, 5, v0
	v_mov_b32_e32 v9, 0
	v_mov_b64_e32 v[0:1], v[66:67]
	s_and_saveexec_b64 s[34:35], vcc
	s_cbranch_execz .LBB0_673
	v_and_b32_e32 v7, -4, v6
	v_lshl_add_u32 v8, v66, 2, s43
	s_mov_b32 s77, 0
	s_mov_b64 s[36:37], 0
	v_lshlrev_b32_e32 v2, 2, v4
	v_mov_b32_e32 v3, v65
	v_mov_b64_e32 v[0:1], v[66:67]

; #define BAR_LDS() do { asm volatile("s_waitcnt lgkmcnt(0)" ::: "memory"); __builtin_amdgcn_s_barrier(); asm volatile("" ::: "memory"); } while (0)
; __device__ __forceinline__ void phase_chunk_prep(const Params& p, LAS unsigned char* lds, int wave_s) {
;     ...
;             for (int i = tid; i < 1536; i += 512) { const int which = i >> 9, tap = (i >> 7) & 3, dd = i & 127; CW[i] = p.in[11][(size_t)tap * 6144 + which * 2048 + h * 128 + dd]; }
;             BAR_LDS(); }
.LBB0_680:
	s_or_b64 exec, exec, s[4:5]
	s_waitcnt vmcnt(0)
	s_waitcnt lgkmcnt(0)
	s_barrier
	s_mov_b32 s77, s78

; #define LAS __attribute__((address_space(3)))
; __device__ __forceinline__ float bflo(unsigned w) { return __uint_as_float(w << 16); }
; __device__ __forceinline__ float bfhi(unsigned w) { return __uint_as_float(w & 0xffff0000u); }
; __device__ __forceinline__ void conv16(const bf16_t* PROJ, const LAS float* cw, int rowbase, int t, int pcol, float (&y)[16]) {
;     u32x4 a[4], b[4];
; #pragma unroll
;     for (int i = 0; i < 4; ++i) {
;         const int tt = t - 3 + i, tc = tt < 0 ? 0 : tt;
;         a[i] = *(const u32x4*)(PROJ + (size_t)(rowbase + tc) * NQ + pcol); b[i] = *(const u32x4*)(PROJ + (size_t)(rowbase + tc) * NQ + pcol + 8);
;     }
; #pragma unroll
;     for (int j = 0; j < 16; ++j) y[j] = 0.f;
; #pragma unroll
;     for (int i = 0; i < 4; ++i) {
;         const float mk = (t - 3 + i) >= 0 ? 1.f : 0.f;
;         const f32x4 w0 = *(const LAS f32x4*)(cw + i * 128) * mk, w1 = *(const LAS f32x4*)(cw + i * 128 + 4) * mk, w2 = *(const LAS f32x4*)(cw + i * 128 + 8) * mk, w3 = *(const LAS f32x4*)(cw + i * 128 + 12) * mk;
;         y[0] += bflo(a[i].x) * w0.x; y[1] += bfhi(a[i].x) * w0.y; y[2] += bflo(a[i].y) * w0.z; y[3] += bfhi(a[i].y) * w0.w;
;         y[4] += bflo(a[i].z) * w1.x; y[5] += bfhi(a[i].z) * w1.y; y[6] += bflo(a[i].w) * w1.z; y[7] += bfhi(a[i].w) * w1.w;
;         y[8] += bflo(b[i].x) * w2.x; y[9] += bfhi(b[i].x) * w2.y; y[10] += bflo(b[i].y) * w2.z; y[11] += bfhi(b[i].y) * w2.w;
;         y[12] += bflo(b[i].z) * w3.x; y[13] += bfhi(b[i].z) * w3.y; y[14] += bflo(b[i].w) * w3.z; y[15] += bfhi(b[i].w) * w3.w;
;     }
.LBB0_683:
	s_or_b64 exec, exec, s[4:5]
	v_lshrrev_b32_e32 v250, 3, v66
	v_lshlrev_b32_e32 v250, 8, v250
	v_and_b32_e32 v251, 7, v66
	v_lshl_add_u32 v250, v251, 5, v250
	v_add_u32_e32 v251, 0x1e200, v250
	s_ashr_i32 s17, s16, 31
	s_mul_i32 s5, s16, 0xec00
	s_mul_hi_i32 s4, s16, 0xec00
	s_add_u32 s30, s25, s5
	v_ashrrev_i32_e32 v67, 3, v66
	s_addc_u32 s31, s38, s4
	v_add_u32_e32 v90, s35, v67
	v_lshlrev_b32_e32 v0, 4, v66
	s_lshl_b32 s4, s78, 7
	v_and_b32_e32 v209, 0x70, v0
	s_add_i32 s5, s4, 0x400
	v_max_i32_e32 v0, 3, v90
	v_or_b32_e32 v2, s5, v209
	v_add3_u32 v215, s34, -3, v0
	s_waitcnt lgkmcnt(0)
	v_mov_b64_e32 v[4:5], s[28:29]
	v_mad_i64_i32 v[0:1], s[36:37], v215, s50, v[4:5]
	v_lshlrev_b32_e32 v64, 1, v2
	v_lshl_add_u64 v[124:125], v[0:1], 0, v[64:65]
	v_max_i32_e32 v0, 2, v90
	v_add3_u32 v214, s34, -2, v0
	v_mad_i64_i32 v[0:1], s[36:37], v214, s50, v[4:5]
	v_lshl_add_u64 v[2:3], v[0:1], 0, v[64:65]
	v_max_i32_e32 v0, 1, v90
	v_max_i32_e32 v6, 0, v90
	v_add3_u32 v213, s34, -1, v0
	v_add_u32_e32 v212, s34, v6
	s_add_i32 s5, s4, 0xc00
	v_mad_i64_i32 v[0:1], s[36:37], v213, s50, v[4:5]
	v_mad_i64_i32 v[4:5], s[34:35], v212, s50, v[4:5]
	v_or_b32_e32 v6, s5, v209
	v_lshl_add_u64 v[0:1], v[0:1], 0, v[64:65]
	v_lshl_add_u64 v[4:5], v[4:5], 0, v[64:65]
	v_lshlrev_b32_e32 v64, 1, v6
	v_lshl_add_u64 v[26:27], s[28:29], 0, v[64:65]
	v_mad_i64_i32 v[6:7], s[34:35], v215, s50, v[26:27]
	ds_read_b128 v[18:21], v250 offset:17408
	ds_read_b128 v[38:41], v250 offset:17424
	v_lshl_add_u32 v210, v209, 2, 0
	v_cmp_lt_i32_e32 vcc, 2, v90
	v_add_u32_e32 v91, 0x1ca00, v210
	v_add_u32_e32 v108, 0x1d200, v210
	v_cndmask_b32_e64 v10, 0, 1.0, vcc
	v_cmp_lt_i32_e32 vcc, 1, v90
	ds_read_b128 v[12:15], v91
	ds_read_b128 v[22:25], v91 offset:16
	ds_read_b128 v[28:31], v91 offset:32
	ds_read_b128 v[32:35], v91 offset:48
	ds_read_b128 v[42:45], v91 offset:512
	ds_read_b128 v[46:49], v91 offset:528
	ds_read_b128 v[50:53], v91 offset:544
	ds_read_b128 v[54:57], v91 offset:560
	ds_read_b128 v[58:61], v108
	ds_read_b128 v[68:71], v108 offset:16
	ds_read_b128 v[72:75], v108 offset:32
	ds_read_b128 v[76:79], v108 offset:48
	v_cndmask_b32_e64 v8, 0, 1.0, vcc
	s_waitcnt lgkmcnt(0)
	v_pk_mul_f32 v[146:147], v[8:9], v[42:43] op_sel_hi:[0,1]
	v_pk_mul_f32 v[168:169], v[8:9], v[44:45] op_sel_hi:[0,1]
	v_pk_mul_f32 v[176:177], v[8:9], v[46:47] op_sel_hi:[0,1]
	v_pk_mul_f32 v[184:185], v[8:9], v[48:49] op_sel_hi:[0,1]
	ds_read_b128 v[42:45], v108 offset:512
	ds_read_b128 v[46:49], v108 offset:528
	v_pk_mul_f32 v[106:107], v[10:11], v[32:33] op_sel_hi:[0,1]
	v_pk_mul_f32 v[32:33], v[10:11], v[74:75] op_sel_hi:[0,1]
	v_add_u32_e32 v74, 0x1da00, v210
	v_pk_mul_f32 v[126:127], v[10:11], v[14:15] op_sel_hi:[0,1]
	v_pk_mul_f32 v[102:103], v[10:11], v[30:31] op_sel_hi:[0,1]
	v_pk_mul_f32 v[188:189], v[8:9], v[50:51] op_sel_hi:[0,1]
	v_pk_mul_f32 v[192:193], v[8:9], v[52:53] op_sel_hi:[0,1]
	v_pk_mul_f32 v[196:197], v[8:9], v[54:55] op_sel_hi:[0,1]
	v_pk_mul_f32 v[98:99], v[8:9], v[56:57] op_sel_hi:[0,1]
	v_pk_mul_f32 v[88:89], v[10:11], v[60:61] op_sel_hi:[0,1]
	v_pk_mul_f32 v[118:119], v[10:11], v[58:59] op_sel_hi:[0,1]
	ds_read_b128 v[50:53], v108 offset:544
	s_waitcnt lgkmcnt(0)
	v_pk_mul_f32 v[100:101], v[8:9], v[44:45] op_sel_hi:[0,1]
	v_pk_mul_f32 v[132:133], v[8:9], v[42:43] op_sel_hi:[0,1]
	v_pk_mul_f32 v[182:183], v[10:11], v[24:25] op_sel_hi:[0,1]
	v_pk_mul_f32 v[6:7], v[10:11], v[34:35] op_sel_hi:[0,1]
	v_pk_mul_f32 v[84:85], v[8:9], v[50:51] op_sel_hi:[0,1]
	v_pk_mul_f32 v[144:145], v[10:11], v[12:13] op_sel_hi:[0,1]
	v_pk_mul_f32 v[138:139], v[10:11], v[22:23] op_sel_hi:[0,1]
	v_pk_mul_f32 v[120:121], v[10:11], v[28:29] op_sel_hi:[0,1]
	v_pk_mul_f32 v[16:17], v[10:11], v[70:71] op_sel_hi:[0,1]
	v_pk_mul_f32 v[22:23], v[10:11], v[68:69] op_sel_hi:[0,1]
	v_pk_mul_f32 v[12:13], v[10:11], v[72:73] op_sel_hi:[0,1]
	v_pk_mul_f32 v[36:37], v[10:11], v[78:79] op_sel_hi:[0,1]
	v_pk_mul_f32 v[28:29], v[10:11], v[76:77] op_sel_hi:[0,1]
	v_pk_mul_f32 v[68:69], v[8:9], v[52:53] op_sel_hi:[0,1]
	v_cmp_lt_i32_e32 vcc, 0, v90
	s_addk_i32 s4, 0x1400
	s_waitcnt lgkmcnt(0)
	v_lshlrev_b32_e32 v122, 16, v18
	v_lshlrev_b32_e32 v14, 16, v38
	v_and_b32_e32 v15, 0xffff0000, v38
	v_lshlrev_b32_e32 v54, 16, v39
	v_and_b32_e32 v55, 0xffff0000, v39
	v_lshlrev_b32_e32 v30, 16, v40
	v_and_b32_e32 v31, 0xffff0000, v40
	v_lshlrev_b32_e32 v38, 16, v41
	v_and_b32_e32 v39, 0xffff0000, v41
	ds_read_b128 v[40:43], v74
	v_pk_mul_f32 v[110:111], v[8:9], v[46:47] op_sel_hi:[0,1]
	ds_read_b128 v[44:47], v74 offset:16
	ds_read_b128 v[56:59], v74 offset:32
	ds_read_b128 v[60:63], v74 offset:48
	v_and_b32_e32 v123, 0xffff0000, v18
	v_lshlrev_b32_e32 v96, 16, v19
	s_waitcnt lgkmcnt(2)
	v_pk_mul_f32 v[104:105], v[10:11], v[46:47] op_sel_hi:[0,1]
	v_pk_mul_f32 v[130:131], v[10:11], v[44:45] op_sel_hi:[0,1]
	ds_read_b128 v[44:47], v108 offset:560
	v_and_b32_e32 v97, 0xffff0000, v19
	v_lshlrev_b32_e32 v24, 16, v20
	v_and_b32_e32 v25, 0xffff0000, v20
	v_lshlrev_b32_e32 v18, 16, v21
	v_and_b32_e32 v19, 0xffff0000, v21
	v_pk_mul_f32 v[20:21], v[8:9], v[48:49] op_sel_hi:[0,1]
	v_pk_mul_f32 v[148:149], v[10:11], v[42:43] op_sel_hi:[0,1]
	s_waitcnt lgkmcnt(0)
	v_pk_mul_f32 v[42:43], v[8:9], v[46:47] op_sel_hi:[0,1]
	v_pk_mul_f32 v[34:35], v[8:9], v[44:45] op_sel_hi:[0,1]
	ds_read_b128 v[44:47], v74 offset:512
	ds_read_b128 v[48:51], v74 offset:528
	v_pk_mul_f32 v[166:167], v[10:11], v[40:41] op_sel_hi:[0,1]
	v_pk_mul_f32 v[76:77], v[10:11], v[58:59] op_sel_hi:[0,1]
	v_pk_mul_f32 v[86:87], v[10:11], v[56:57] op_sel_hi:[0,1]
	s_waitcnt lgkmcnt(1)
	v_pk_mul_f32 v[156:157], v[8:9], v[46:47] op_sel_hi:[0,1]
	v_pk_mul_f32 v[172:173], v[8:9], v[44:45] op_sel_hi:[0,1]
	s_waitcnt lgkmcnt(0)
; #define LAS __attribute__((address_space(3)))
; __device__ __forceinline__ float bflo(unsigned w) { return __uint_as_float(w << 16); }
; __device__ __forceinline__ float bfhi(unsigned w) { return __uint_as_float(w & 0xffff0000u); }
; __device__ __forceinline__ void conv16(const bf16_t* PROJ, const LAS float* cw, int rowbase, int t, int pcol, float (&y)[16]) {
;     u32x4 a[4], b[4];
; #pragma unroll
;     for (int i = 0; i < 4; ++i) {
;         const int tt = t - 3 + i, tc = tt < 0 ? 0 : tt;
;         a[i] = *(const u32x4*)(PROJ + (size_t)(rowbase + tc) * NQ + pcol); b[i] = *(const u32x4*)(PROJ + (size_t)(rowbase + tc) * NQ + pcol + 8);
;     }
; #pragma unroll
;     for (int j = 0; j < 16; ++j) y[j] = 0.f;
; #pragma unroll
;     for (int i = 0; i < 4; ++i) {
;         const float mk = (t - 3 + i) >= 0 ? 1.f : 0.f;
;         const f32x4 w0 = *(const LAS f32x4*)(cw + i * 128) * mk, w1 = *(const LAS f32x4*)(cw + i * 128 + 4) * mk, w2 = *(const LAS f32x4*)(cw + i * 128 + 8) * mk, w3 = *(const LAS f32x4*)(cw + i * 128 + 12) * mk;
;         y[0] += bflo(a[i].x) * w0.x; y[1] += bfhi(a[i].x) * w0.y; y[2] += bflo(a[i].y) * w0.z; y[3] += bfhi(a[i].y) * w0.w;
;         y[4] += bflo(a[i].z) * w1.x; y[5] += bfhi(a[i].z) * w1.y; y[6] += bflo(a[i].w) * w1.z; y[7] += bfhi(a[i].w) * w1.w;
;         y[8] += bflo(b[i].x) * w2.x; y[9] += bfhi(b[i].x) * w2.y; y[10] += bflo(b[i].y) * w2.z; y[11] += bfhi(b[i].y) * w2.w;
;         y[12] += bflo(b[i].z) * w3.x; y[13] += bfhi(b[i].z) * w3.y; y[14] += bflo(b[i].w) * w3.z; y[15] += bfhi(b[i].w) * w3.w;
;     }
	v_pk_mul_f32 v[116:117], v[8:9], v[50:51] op_sel_hi:[0,1]
	v_pk_mul_f32 v[142:143], v[8:9], v[48:49] op_sel_hi:[0,1]
	ds_read_b128 v[44:47], v74 offset:544
	ds_read_b128 v[48:51], v74 offset:560
	v_pk_mul_f32 v[40:41], v[10:11], v[62:63] op_sel_hi:[0,1]
	v_pk_mul_f32 v[60:61], v[10:11], v[60:61] op_sel_hi:[0,1]
	v_cndmask_b32_e64 v56, 0, 1.0, vcc
	s_waitcnt lgkmcnt(1)
	v_pk_mul_f32 v[80:81], v[8:9], v[46:47] op_sel_hi:[0,1]
	v_pk_mul_f32 v[94:95], v[8:9], v[44:45] op_sel_hi:[0,1]
	s_waitcnt lgkmcnt(0)
	v_pk_mul_f32 v[44:45], v[8:9], v[50:51] op_sel_hi:[0,1]
	v_pk_mul_f32 v[62:63], v[8:9], v[48:49] op_sel_hi:[0,1]
	ds_read_b128 v[8:11], v91 offset:1024
	ds_read_b128 v[46:49], v91 offset:1040
	v_cmp_lt_i32_e32 vcc, -1, v90
	v_pk_fma_f32 v[118:119], v[118:119], v[122:123], 0 op_sel_hi:[1,1,0]
	v_pk_fma_f32 v[12:13], v[12:13], v[14:15], 0 op_sel_hi:[1,1,0]
	s_waitcnt lgkmcnt(1)
	v_pk_mul_f32 v[186:187], v[56:57], v[8:9] op_sel_hi:[0,1]
	v_pk_mul_f32 v[198:199], v[56:57], v[10:11] op_sel_hi:[0,1]
	s_waitcnt lgkmcnt(0)
	v_pk_mul_f32 v[200:201], v[56:57], v[46:47] op_sel_hi:[0,1]
	v_pk_mul_f32 v[204:205], v[56:57], v[48:49] op_sel_hi:[0,1]
	ds_read_b128 v[8:11], v91 offset:1056
	ds_read_b128 v[46:49], v91 offset:1072
	v_cndmask_b32_e64 v64, 0, 1.0, vcc
	v_pk_fma_f32 v[36:37], v[36:37], v[38:39], 0 op_sel_hi:[1,1,0]
	s_waitcnt lgkmcnt(1)
	v_pk_mul_f32 v[232:233], v[56:57], v[8:9] op_sel_hi:[0,1]
	v_pk_mul_f32 v[234:235], v[56:57], v[10:11] op_sel_hi:[0,1]
	s_waitcnt lgkmcnt(0)
	v_pk_mul_f32 v[236:237], v[56:57], v[46:47] op_sel_hi:[0,1]
	v_pk_mul_f32 v[228:229], v[56:57], v[48:49] op_sel_hi:[0,1]
	ds_read_b128 v[8:11], v108 offset:1024
	ds_read_b128 v[46:49], v108 offset:1040
	s_waitcnt lgkmcnt(1)
	v_pk_mul_f32 v[158:159], v[56:57], v[10:11] op_sel_hi:[0,1]
	v_pk_mul_f32 v[170:171], v[56:57], v[8:9] op_sel_hi:[0,1]
	s_waitcnt lgkmcnt(0)
	v_pk_mul_f32 v[114:115], v[56:57], v[48:49] op_sel_hi:[0,1]
	v_pk_mul_f32 v[140:141], v[56:57], v[46:47] op_sel_hi:[0,1]
	ds_read_b128 v[8:11], v108 offset:1056
	ds_read_b128 v[46:49], v108 offset:1072
	s_waitcnt lgkmcnt(1)
	v_pk_mul_f32 v[72:73], v[56:57], v[10:11] op_sel_hi:[0,1]
	v_pk_mul_f32 v[92:93], v[56:57], v[8:9] op_sel_hi:[0,1]
	ds_read_b128 v[8:11], v74 offset:1024
	ds_read_b128 v[50:53], v74 offset:1040
	s_waitcnt lgkmcnt(2)
	v_pk_mul_f32 v[58:59], v[56:57], v[46:47] op_sel_hi:[0,1]
	v_pk_mul_f32 v[48:49], v[56:57], v[48:49] op_sel_hi:[0,1]
	s_waitcnt lgkmcnt(1)
	v_pk_mul_f32 v[164:165], v[56:57], v[10:11] op_sel_hi:[0,1]
	v_pk_mul_f32 v[180:181], v[56:57], v[8:9] op_sel_hi:[0,1]
	s_waitcnt lgkmcnt(0)
	v_pk_mul_f32 v[136:137], v[56:57], v[52:53] op_sel_hi:[0,1]
	v_pk_mul_f32 v[154:155], v[56:57], v[50:51] op_sel_hi:[0,1]
	ds_read_b128 v[8:11], v74 offset:1056
	ds_read_b128 v[50:53], v74 offset:1072
	s_waitcnt lgkmcnt(1)
	v_pk_mul_f32 v[82:83], v[56:57], v[10:11] op_sel_hi:[0,1]
	v_pk_mul_f32 v[112:113], v[56:57], v[8:9] op_sel_hi:[0,1]
	s_waitcnt lgkmcnt(0)
	v_pk_mul_f32 v[46:47], v[56:57], v[52:53] op_sel_hi:[0,1]
	v_pk_mul_f32 v[70:71], v[56:57], v[50:51] op_sel_hi:[0,1]
	ds_read_b128 v[8:11], v91 offset:1536
	ds_read_b128 v[50:53], v91 offset:1552
	s_waitcnt lgkmcnt(1)
	v_pk_mul_f32 v[194:195], v[64:65], v[8:9] op_sel_hi:[0,1]
	v_pk_mul_f32 v[202:203], v[64:65], v[10:11] op_sel_hi:[0,1]
	s_waitcnt lgkmcnt(0)
	v_pk_mul_f32 v[206:207], v[64:65], v[50:51] op_sel_hi:[0,1]
	v_pk_mul_f32 v[238:239], v[64:65], v[52:53] op_sel_hi:[0,1]
	ds_read_b128 v[8:11], v91 offset:1568
	ds_read_b128 v[50:53], v91 offset:1584
	s_waitcnt lgkmcnt(1)
	v_pk_mul_f32 v[240:241], v[64:65], v[8:9] op_sel_hi:[0,1]
	v_pk_mul_f32 v[242:243], v[64:65], v[10:11] op_sel_hi:[0,1]
	s_waitcnt lgkmcnt(0)
	v_pk_mul_f32 v[244:245], v[64:65], v[50:51] op_sel_hi:[0,1]
	v_pk_mul_f32 v[246:247], v[64:65], v[52:53] op_sel_hi:[0,1]
	ds_read_b128 v[8:11], v108 offset:1536
	ds_read_b128 v[50:53], v108 offset:1552
	s_waitcnt lgkmcnt(1)
	v_pk_mul_f32 v[162:163], v[64:65], v[10:11] op_sel_hi:[0,1]
	v_pk_mul_f32 v[178:179], v[64:65], v[8:9] op_sel_hi:[0,1]
	s_waitcnt lgkmcnt(0)
	v_pk_mul_f32 v[134:135], v[64:65], v[52:53] op_sel_hi:[0,1]
	v_pk_mul_f32 v[152:153], v[64:65], v[50:51] op_sel_hi:[0,1]
	ds_read_b128 v[8:11], v108 offset:1568
	ds_read_b128 v[50:53], v108 offset:1584
	s_waitcnt lgkmcnt(1)
	v_pk_mul_f32 v[78:79], v[64:65], v[10:11] op_sel_hi:[0,1]
	v_pk_mul_f32 v[108:109], v[64:65], v[8:9] op_sel_hi:[0,1]
	ds_read_b128 v[8:11], v74 offset:1536
	ds_read_b128 v[216:219], v74 offset:1552
	s_waitcnt lgkmcnt(2)
	v_pk_mul_f32 v[56:57], v[64:65], v[50:51] op_sel_hi:[0,1]
	v_pk_mul_f32 v[52:53], v[64:65], v[52:53] op_sel_hi:[0,1]
	s_waitcnt lgkmcnt(1)
	v_pk_mul_f32 v[174:175], v[64:65], v[10:11] op_sel_hi:[0,1]
	v_pk_mul_f32 v[190:191], v[64:65], v[8:9] op_sel_hi:[0,1]
	s_waitcnt lgkmcnt(0)
	v_pk_mul_f32 v[150:151], v[64:65], v[218:219] op_sel_hi:[0,1]
	v_pk_mul_f32 v[160:161], v[64:65], v[216:217] op_sel_hi:[0,1]
	ds_read_b128 v[8:11], v74 offset:1568
	ds_read_b128 v[216:219], v74 offset:1584
	s_waitcnt lgkmcnt(1)
	v_pk_mul_f32 v[128:129], v[64:65], v[8:9] op_sel_hi:[0,1]
	s_waitcnt lgkmcnt(0)
	v_pk_mul_f32 v[50:51], v[64:65], v[218:219] op_sel_hi:[0,1]
	v_pk_mul_f32 v[74:75], v[64:65], v[216:217] op_sel_hi:[0,1]
	ds_read_b128 v[216:219], v250 offset:16
	v_pk_mul_f32 v[90:91], v[64:65], v[10:11] op_sel_hi:[0,1]
	s_waitcnt lgkmcnt(0)
	v_lshlrev_b32_e32 v8, 16, v219
	v_and_b32_e32 v9, 0xffff0000, v219
	v_pk_fma_f32 v[6:7], v[6:7], v[8:9], 0 op_sel_hi:[1,1,0]
	ds_read_b128 v[220:223], v250 offset:272
	ds_read_b128 v[8:11], v250 offset:256
	s_waitcnt lgkmcnt(0)
; #define LAS __attribute__((address_space(3)))
; __device__ __forceinline__ float bflo(unsigned w) { return __uint_as_float(w << 16); }
; __device__ __forceinline__ float bfhi(unsigned w) { return __uint_as_float(w & 0xffff0000u); }
; __device__ __forceinline__ void conv16(const bf16_t* PROJ, const LAS float* cw, int rowbase, int t, int pcol, float (&y)[16]) {
;     u32x4 a[4], b[4];
; #pragma unroll
;     for (int i = 0; i < 4; ++i) {
;         const int tt = t - 3 + i, tc = tt < 0 ? 0 : tt;
;         a[i] = *(const u32x4*)(PROJ + (size_t)(rowbase + tc) * NQ + pcol); b[i] = *(const u32x4*)(PROJ + (size_t)(rowbase + tc) * NQ + pcol + 8);
;     }
; #pragma unroll
;     for (int j = 0; j < 16; ++j) y[j] = 0.f;
; #pragma unroll
;     for (int i = 0; i < 4; ++i) {
;         const float mk = (t - 3 + i) >= 0 ? 1.f : 0.f;
;         const f32x4 w0 = *(const LAS f32x4*)(cw + i * 128) * mk, w1 = *(const LAS f32x4*)(cw + i * 128 + 4) * mk, w2 = *(const LAS f32x4*)(cw + i * 128 + 8) * mk, w3 = *(const LAS f32x4*)(cw + i * 128 + 12) * mk;
;         y[0] += bflo(a[i].x) * w0.x; y[1] += bfhi(a[i].x) * w0.y; y[2] += bflo(a[i].y) * w0.z; y[3] += bfhi(a[i].y) * w0.w;
;         y[4] += bflo(a[i].z) * w1.x; y[5] += bfhi(a[i].z) * w1.y; y[6] += bflo(a[i].w) * w1.z; y[7] += bfhi(a[i].w) * w1.w;
;         y[8] += bflo(b[i].x) * w2.x; y[9] += bfhi(b[i].x) * w2.y; y[10] += bflo(b[i].y) * w2.z; y[11] += bfhi(b[i].y) * w2.w;
;         y[12] += bflo(b[i].z) * w3.x; y[13] += bfhi(b[i].z) * w3.y; y[14] += bflo(b[i].w) * w3.z; y[15] += bfhi(b[i].w) * w3.w;
;     }
; __device__ __forceinline__ void phase_chunk_prep(const Params& p, LAS unsigned char* lds, int wave_s) {
;     ...
;         conv16(PROJ, CW + seg * 16, rowbase, t, 1024 + h * 128 + seg * 16, q);
;         conv16(PROJ, CW + 512 + seg * 16, rowbase, t, 1024 + 2048 + h * 128 + seg * 16, k);
;         conv16(PROJ, CW + 1024 + seg * 16, rowbase, t, 1024 + 4096 + h * 128 + seg * 16, v);
	v_lshlrev_b32_e32 v2, 16, v223
	v_and_b32_e32 v3, 0xffff0000, v223
	v_pk_fma_f32 v[6:7], v[98:99], v[2:3], v[6:7]
	ds_read_b128 v[224:227], v250 offset:528
	s_nop 0
	ds_read_b128 v[0:3], v250 offset:512
	v_and_b32_e32 v219, 0xffff0000, v222
	s_waitcnt lgkmcnt(0)
	v_lshlrev_b32_e32 v98, 16, v227
	v_and_b32_e32 v99, 0xffff0000, v227
	v_pk_fma_f32 v[98:99], v[228:229], v[98:99], v[6:7]
	ds_read_b128 v[228:231], v250 offset:784
	s_nop 0
	ds_read_b128 v[4:7], v250 offset:768
	s_waitcnt lgkmcnt(0)
	v_lshlrev_b32_e32 v248, 16, v231
	v_and_b32_e32 v249, 0xffff0000, v231
	v_pk_fma_f32 v[98:99], v[246:247], v[248:249], v[98:99]
	v_lshlrev_b32_e32 v246, 16, v218
	v_and_b32_e32 v247, 0xffff0000, v218
	v_pk_fma_f32 v[106:107], v[106:107], v[246:247], 0 op_sel_hi:[1,1,0]
	v_lshlrev_b32_e32 v218, 16, v222
	v_pk_fma_f32 v[106:107], v[196:197], v[218:219], v[106:107]
	v_lshlrev_b32_e32 v196, 16, v226
	v_and_b32_e32 v197, 0xffff0000, v226
	v_pk_fma_f32 v[106:107], v[236:237], v[196:197], v[106:107]
	v_lshlrev_b32_e32 v196, 16, v230
	v_and_b32_e32 v197, 0xffff0000, v230
	v_pk_fma_f32 v[106:107], v[244:245], v[196:197], v[106:107]
	v_lshlrev_b32_e32 v196, 16, v217
	v_and_b32_e32 v197, 0xffff0000, v217
	v_pk_fma_f32 v[102:103], v[102:103], v[196:197], 0 op_sel_hi:[1,1,0]
	v_lshlrev_b32_e32 v196, 16, v221
	v_and_b32_e32 v197, 0xffff0000, v221
	v_pk_fma_f32 v[102:103], v[192:193], v[196:197], v[102:103]
	v_lshlrev_b32_e32 v192, 16, v225
	v_and_b32_e32 v193, 0xffff0000, v225
	v_pk_fma_f32 v[102:103], v[234:235], v[192:193], v[102:103]
	v_lshlrev_b32_e32 v192, 16, v229
	v_and_b32_e32 v193, 0xffff0000, v229
	v_pk_fma_f32 v[102:103], v[242:243], v[192:193], v[102:103]
	v_lshlrev_b32_e32 v192, 16, v216
	v_and_b32_e32 v193, 0xffff0000, v216
	ds_read_b128 v[216:219], v250
	v_lshlrev_b32_e32 v196, 16, v220
	v_and_b32_e32 v197, 0xffff0000, v220
	v_pk_fma_f32 v[120:121], v[120:121], v[192:193], 0 op_sel_hi:[1,1,0]
	s_waitcnt lgkmcnt(0)
	v_lshlrev_b32_e32 v124, 16, v219
	v_and_b32_e32 v125, 0xffff0000, v219
	v_pk_fma_f32 v[124:125], v[182:183], v[124:125], 0 op_sel_hi:[1,1,0]
	v_lshlrev_b32_e32 v182, 16, v11
	v_and_b32_e32 v183, 0xffff0000, v11
	v_pk_fma_f32 v[124:125], v[184:185], v[182:183], v[124:125]
	v_lshlrev_b32_e32 v182, 16, v3
	v_and_b32_e32 v183, 0xffff0000, v3
	v_pk_fma_f32 v[124:125], v[204:205], v[182:183], v[124:125]
	v_lshlrev_b32_e32 v182, 16, v7
	v_and_b32_e32 v183, 0xffff0000, v7
	v_pk_fma_f32 v[124:125], v[238:239], v[182:183], v[124:125]
	v_lshlrev_b32_e32 v182, 16, v218
	v_and_b32_e32 v183, 0xffff0000, v218
	v_pk_fma_f32 v[138:139], v[138:139], v[182:183], 0 op_sel_hi:[1,1,0]
	v_lshlrev_b32_e32 v182, 16, v10
	v_and_b32_e32 v183, 0xffff0000, v10
	v_pk_fma_f32 v[10:11], v[176:177], v[182:183], v[138:139]
	v_lshlrev_b32_e32 v138, 16, v2
	v_and_b32_e32 v139, 0xffff0000, v2
	v_pk_fma_f32 v[2:3], v[200:201], v[138:139], v[10:11]
	v_lshlrev_b32_e32 v10, 16, v6
	v_and_b32_e32 v11, 0xffff0000, v6
	v_pk_fma_f32 v[138:139], v[206:207], v[10:11], v[2:3]
	v_lshlrev_b32_e32 v2, 16, v217
	v_and_b32_e32 v3, 0xffff0000, v217
	v_pk_fma_f32 v[2:3], v[126:127], v[2:3], 0 op_sel_hi:[1,1,0]
	v_lshlrev_b32_e32 v6, 16, v9
	v_and_b32_e32 v7, 0xffff0000, v9
	v_pk_fma_f32 v[2:3], v[168:169], v[6:7], v[2:3]
	v_lshlrev_b32_e32 v6, 16, v1
	v_and_b32_e32 v7, 0xffff0000, v1
	v_pk_fma_f32 v[2:3], v[198:199], v[6:7], v[2:3]
	v_lshlrev_b32_e32 v6, 16, v5
	v_and_b32_e32 v7, 0xffff0000, v5
	v_pk_fma_f32 v[126:127], v[202:203], v[6:7], v[2:3]
	v_lshlrev_b32_e32 v2, 16, v216
	v_and_b32_e32 v3, 0xffff0000, v216
	v_lshlrev_b32_e32 v6, 16, v8
	v_and_b32_e32 v7, 0xffff0000, v8
	v_pk_fma_f32 v[2:3], v[144:145], v[2:3], 0 op_sel_hi:[1,1,0]
	v_pk_fma_f32 v[120:121], v[188:189], v[196:197], v[120:121]
	v_pk_fma_f32 v[2:3], v[146:147], v[6:7], v[2:3]
	v_lshlrev_b32_e32 v6, 16, v0
	v_and_b32_e32 v7, 0xffff0000, v0
	v_pk_fma_f32 v[0:1], v[186:187], v[6:7], v[2:3]
	v_lshlrev_b32_e32 v2, 16, v4
	v_and_b32_e32 v3, 0xffff0000, v4
	v_pk_fma_f32 v[144:145], v[194:195], v[2:3], v[0:1]
	v_or_b32_e32 v0, s4, v209
	v_lshlrev_b32_e32 v64, 1, v0
	v_lshl_add_u64 v[146:147], s[28:29], 0, v[64:65]
	v_mad_i64_i32 v[4:5], s[4:5], v215, s50, v[146:147]
	ds_read_b128 v[0:3], v251
	v_lshlrev_b32_e32 v188, 16, v224
	v_and_b32_e32 v189, 0xffff0000, v224
	v_pk_fma_f32 v[120:121], v[232:233], v[188:189], v[120:121]
	v_lshlrev_b32_e32 v188, 16, v228
	v_and_b32_e32 v189, 0xffff0000, v228
	v_pk_fma_f32 v[120:121], v[240:241], v[188:189], v[120:121]
	v_lshlrev_b32_e32 v64, 1, v209
	s_waitcnt lgkmcnt(0)
	v_lshlrev_b32_e32 v6, 16, v0
	v_and_b32_e32 v7, 0xffff0000, v0
	v_pk_fma_f32 v[166:167], v[166:167], v[6:7], 0 op_sel_hi:[1,1,0]
	v_mad_i64_i32 v[6:7], s[4:5], v214, s50, v[146:147]
	ds_read_b128 v[8:11], v251 offset:256
	v_lshlrev_b32_e32 v0, 16, v1
	v_and_b32_e32 v1, 0xffff0000, v1
	v_pk_fma_f32 v[0:1], v[148:149], v[0:1], 0 op_sel_hi:[1,1,0]
	s_waitcnt lgkmcnt(0)
	v_lshlrev_b32_e32 v168, 16, v8
	v_and_b32_e32 v169, 0xffff0000, v8
	v_pk_fma_f32 v[168:169], v[172:173], v[168:169], v[166:167]
	v_mad_i64_i32 v[166:167], s[4:5], v213, s50, v[146:147]
	ds_read_b128 v[182:185], v251 offset:512
	v_lshlrev_b32_e32 v8, 16, v9
	v_and_b32_e32 v9, 0xffff0000, v9
	v_pk_fma_f32 v[0:1], v[156:157], v[8:9], v[0:1]
	s_waitcnt lgkmcnt(0)
	v_lshlrev_b32_e32 v172, 16, v182
	v_and_b32_e32 v173, 0xffff0000, v182
	v_pk_fma_f32 v[172:173], v[180:181], v[172:173], v[168:169]
	v_mad_i64_i32 v[168:169], s[4:5], v212, s50, v[146:147]
	ds_read_b128 v[186:189], v251 offset:768
	v_lshlrev_b32_e32 v8, 16, v183
	v_and_b32_e32 v9, 0xffff0000, v183
	v_pk_fma_f32 v[0:1], v[164:165], v[8:9], v[0:1]
	s_waitcnt lgkmcnt(0)
; #define LAS __attribute__((address_space(3)))
; __device__ __forceinline__ float bflo(unsigned w) { return __uint_as_float(w << 16); }
; __device__ __forceinline__ float bfhi(unsigned w) { return __uint_as_float(w & 0xffff0000u); }
; __device__ __forceinline__ float siluf_(float x) { return x * __builtin_amdgcn_rcpf(1.0f + __expf(-x)); }
; __device__ __forceinline__ void conv16(const bf16_t* PROJ, const LAS float* cw, int rowbase, int t, int pcol, float (&y)[16]) {
;     u32x4 a[4], b[4];
; #pragma unroll
;     for (int i = 0; i < 4; ++i) {
;         const int tt = t - 3 + i, tc = tt < 0 ? 0 : tt;
;         a[i] = *(const u32x4*)(PROJ + (size_t)(rowbase + tc) * NQ + pcol); b[i] = *(const u32x4*)(PROJ + (size_t)(rowbase + tc) * NQ + pcol + 8);
;     }
; #pragma unroll
;     for (int j = 0; j < 16; ++j) y[j] = 0.f;
; #pragma unroll
;     for (int i = 0; i < 4; ++i) {
;         const float mk = (t - 3 + i) >= 0 ? 1.f : 0.f;
;         const f32x4 w0 = *(const LAS f32x4*)(cw + i * 128) * mk, w1 = *(const LAS f32x4*)(cw + i * 128 + 4) * mk, w2 = *(const LAS f32x4*)(cw + i * 128 + 8) * mk, w3 = *(const LAS f32x4*)(cw + i * 128 + 12) * mk;
;         y[0] += bflo(a[i].x) * w0.x; y[1] += bfhi(a[i].x) * w0.y; y[2] += bflo(a[i].y) * w0.z; y[3] += bfhi(a[i].y) * w0.w;
;         y[4] += bflo(a[i].z) * w1.x; y[5] += bfhi(a[i].z) * w1.y; y[6] += bflo(a[i].w) * w1.z; y[7] += bfhi(a[i].w) * w1.w;
;         y[8] += bflo(b[i].x) * w2.x; y[9] += bfhi(b[i].x) * w2.y; y[10] += bflo(b[i].y) * w2.z; y[11] += bfhi(b[i].y) * w2.w;
;         y[12] += bflo(b[i].z) * w3.x; y[13] += bfhi(b[i].z) * w3.y; y[14] += bflo(b[i].w) * w3.z; y[15] += bfhi(b[i].w) * w3.w;
;     }
; #pragma unroll
;     for (int j = 0; j < 16; ++j) y[j] = siluf_(y[j]);
	v_lshlrev_b32_e32 v146, 16, v186
	v_and_b32_e32 v147, 0xffff0000, v186
	v_pk_fma_f32 v[146:147], v[190:191], v[146:147], v[172:173]
	v_mad_i64_i32 v[172:173], s[4:5], v214, s50, v[26:27]
	ds_read_b128 v[190:193], v250 offset:17664
	v_lshlrev_b32_e32 v8, 16, v187
	v_and_b32_e32 v9, 0xffff0000, v187
	s_waitcnt lgkmcnt(0)
	v_lshlrev_b32_e32 v122, 16, v190
	v_and_b32_e32 v123, 0xffff0000, v190
	v_pk_fma_f32 v[118:119], v[132:133], v[122:123], v[118:119]
	v_mad_i64_i32 v[132:133], s[4:5], v213, s50, v[26:27]
	ds_read_b128 v[194:197], v250 offset:17920
	s_waitcnt lgkmcnt(0)
	v_lshlrev_b32_e32 v122, 16, v194
	v_and_b32_e32 v123, 0xffff0000, v194
	v_pk_fma_f32 v[118:119], v[170:171], v[122:123], v[118:119]
	v_mad_i64_i32 v[170:171], s[4:5], v212, s50, v[26:27]
	ds_read_b128 v[198:201], v250 offset:18176
	v_pk_fma_f32 v[122:123], v[174:175], v[8:9], v[0:1]
	v_pk_fma_f32 v[0:1], v[88:89], v[96:97], 0 op_sel_hi:[1,1,0]
	v_lshlrev_b32_e32 v8, 16, v191
	v_and_b32_e32 v9, 0xffff0000, v191
	v_pk_fma_f32 v[0:1], v[100:101], v[8:9], v[0:1]
	v_lshlrev_b32_e32 v8, 16, v195
	v_and_b32_e32 v9, 0xffff0000, v195
	v_pk_fma_f32 v[0:1], v[158:159], v[8:9], v[0:1]
	s_waitcnt lgkmcnt(0)
	v_lshlrev_b32_e32 v8, 16, v199
	v_and_b32_e32 v9, 0xffff0000, v199
	v_pk_fma_f32 v[88:89], v[162:163], v[8:9], v[0:1]
	v_lshlrev_b32_e32 v0, 16, v2
	v_and_b32_e32 v1, 0xffff0000, v2
	v_pk_fma_f32 v[0:1], v[130:131], v[0:1], 0 op_sel_hi:[1,1,0]
	v_lshlrev_b32_e32 v8, 16, v10
	v_and_b32_e32 v9, 0xffff0000, v10
	v_pk_fma_f32 v[0:1], v[142:143], v[8:9], v[0:1]
	v_lshlrev_b32_e32 v8, 16, v184
	v_and_b32_e32 v9, 0xffff0000, v184
	v_pk_fma_f32 v[0:1], v[154:155], v[8:9], v[0:1]
	v_lshlrev_b32_e32 v8, 16, v188
	v_and_b32_e32 v9, 0xffff0000, v188
	v_pk_fma_f32 v[96:97], v[160:161], v[8:9], v[0:1]
	v_pk_fma_f32 v[0:1], v[22:23], v[24:25], 0 op_sel_hi:[1,1,0]
	v_lshlrev_b32_e32 v8, 16, v192
	v_and_b32_e32 v9, 0xffff0000, v192
	v_pk_fma_f32 v[0:1], v[110:111], v[8:9], v[0:1]
	v_lshlrev_b32_e32 v8, 16, v196
	v_and_b32_e32 v9, 0xffff0000, v196
	v_pk_fma_f32 v[0:1], v[140:141], v[8:9], v[0:1]
	v_lshlrev_b32_e32 v8, 16, v200
	v_and_b32_e32 v9, 0xffff0000, v200
	v_pk_fma_f32 v[100:101], v[152:153], v[8:9], v[0:1]
	v_lshlrev_b32_e32 v0, 16, v3
	v_and_b32_e32 v1, 0xffff0000, v3
	v_lshlrev_b32_e32 v2, 16, v11
	v_and_b32_e32 v3, 0xffff0000, v11
	v_pk_fma_f32 v[0:1], v[104:105], v[0:1], 0 op_sel_hi:[1,1,0]
	ds_read_b128 v[8:11], v251 offset:272
	v_pk_fma_f32 v[0:1], v[116:117], v[2:3], v[0:1]
	v_lshlrev_b32_e32 v2, 16, v185
	v_and_b32_e32 v3, 0xffff0000, v185
	v_pk_fma_f32 v[0:1], v[136:137], v[2:3], v[0:1]
	v_lshlrev_b32_e32 v2, 16, v189
	v_and_b32_e32 v3, 0xffff0000, v189
	v_pk_fma_f32 v[104:105], v[150:151], v[2:3], v[0:1]
	v_lshlrev_b32_e32 v0, 16, v193
	v_and_b32_e32 v1, 0xffff0000, v193
	v_pk_fma_f32 v[2:3], v[16:17], v[18:19], 0 op_sel_hi:[1,1,0]
	v_lshlrev_b32_e32 v26, 16, v198
	v_pk_fma_f32 v[0:1], v[20:21], v[0:1], v[2:3]
	ds_read_b128 v[20:23], v251 offset:16
	v_lshlrev_b32_e32 v2, 16, v197
	ds_read_b128 v[4:7], v251 offset:528
	v_and_b32_e32 v3, 0xffff0000, v197
	v_pk_fma_f32 v[0:1], v[114:115], v[2:3], v[0:1]
	v_lshlrev_b32_e32 v2, 16, v201
	v_and_b32_e32 v3, 0xffff0000, v201
	v_pk_fma_f32 v[110:111], v[134:135], v[2:3], v[0:1]
	v_and_b32_e32 v27, 0xffff0000, v198
	v_pk_fma_f32 v[118:119], v[178:179], v[26:27], v[118:119]
	ds_read_b128 v[24:27], v250 offset:17680
	s_waitcnt lgkmcnt(0)
	v_lshlrev_b32_e32 v2, 16, v8
	v_and_b32_e32 v3, 0xffff0000, v8
	v_lshlrev_b32_e32 v8, 16, v9
	v_and_b32_e32 v9, 0xffff0000, v9
	s_waitcnt lgkmcnt(0)
	v_lshlrev_b32_e32 v0, 16, v20
	v_and_b32_e32 v1, 0xffff0000, v20
	v_pk_fma_f32 v[0:1], v[86:87], v[0:1], 0 op_sel_hi:[1,1,0]
	v_lshlrev_b32_e32 v20, 16, v21
	v_pk_fma_f32 v[0:1], v[94:95], v[2:3], v[0:1]
	s_waitcnt lgkmcnt(0)
	v_lshlrev_b32_e32 v2, 16, v4
	v_and_b32_e32 v3, 0xffff0000, v4
	v_pk_fma_f32 v[16:17], v[112:113], v[2:3], v[0:1]
	ds_read_b128 v[0:3], v251 offset:784
	v_and_b32_e32 v21, 0xffff0000, v21
	s_waitcnt lgkmcnt(0)
	v_lshlrev_b32_e32 v14, 16, v24
	v_and_b32_e32 v15, 0xffff0000, v24
	v_pk_fma_f32 v[20:21], v[76:77], v[20:21], 0 op_sel_hi:[1,1,0]
	v_lshlrev_b32_e32 v4, 16, v5
	v_pk_fma_f32 v[8:9], v[80:81], v[8:9], v[20:21]
	v_and_b32_e32 v5, 0xffff0000, v5
	v_pk_fma_f32 v[4:5], v[82:83], v[4:5], v[8:9]
	v_lshlrev_b32_e32 v20, 16, v25
	v_and_b32_e32 v21, 0xffff0000, v25
	s_waitcnt lgkmcnt(0)
	v_lshlrev_b32_e32 v18, 16, v0
	v_and_b32_e32 v19, 0xffff0000, v0
	v_pk_fma_f32 v[86:87], v[128:129], v[18:19], v[16:17]
	v_pk_fma_f32 v[16:17], v[84:85], v[14:15], v[12:13]
	ds_read_b128 v[12:15], v250 offset:17936
	v_lshlrev_b32_e32 v0, 16, v1
	v_and_b32_e32 v1, 0xffff0000, v1
	v_pk_fma_f32 v[80:81], v[90:91], v[0:1], v[4:5]
	v_mul_f32_e32 v0, 0xbfb8aa3b, v98
	v_mul_f32_e32 v1, 0xbfb8aa3b, v99
	v_exp_f32_e32 v0, v0
	v_exp_f32_e32 v1, v1
	v_mul_f32_e32 v4, 0xbfb8aa3b, v106
	v_exp_f32_e32 v8, v4
	v_add_f32_e32 v0, 1.0, v0
	v_add_f32_e32 v1, 1.0, v1
	v_mul_f32_e32 v4, 0xbfb8aa3b, v107
	v_rcp_f32_e32 v0, v0
	v_rcp_f32_e32 v1, v1
	v_exp_f32_e32 v9, v4
	v_pk_mul_f32 v[4:5], v[98:99], v[0:1]
	v_add_f32_e32 v0, 1.0, v8
	v_add_f32_e32 v1, 1.0, v9
	v_rcp_f32_e32 v0, v0
	v_rcp_f32_e32 v1, v1
	v_mul_f32_e32 v8, 0xbfb8aa3b, v102
	v_lshlrev_b32_e32 v98, 16, v23
	v_and_b32_e32 v99, 0xffff0000, v23
	v_pk_mul_f32 v[76:77], v[4:5], v[4:5]
	v_pk_fma_f32 v[40:41], v[40:41], v[98:99], 0 op_sel_hi:[1,1,0]
	s_waitcnt lgkmcnt(0)
	v_lshlrev_b32_e32 v18, 16, v12
	v_and_b32_e32 v19, 0xffff0000, v12
	v_pk_fma_f32 v[84:85], v[92:93], v[18:19], v[16:17]
	ds_read_b128 v[16:19], v250 offset:18192
	v_lshlrev_b32_e32 v12, 2, v211
	s_waitcnt lgkmcnt(0)
	s_barrier
; __device__ __forceinline__ float siluf_(float x) { return x * __builtin_amdgcn_rcpf(1.0f + __expf(-x)); }
; __device__ __forceinline__ float bperm(float v, int srclane) { return __builtin_bit_cast(float, __builtin_amdgcn_ds_bpermute(srclane << 2, __builtin_bit_cast(int, v))); }
; #define BAR_LDS() do { asm volatile("s_waitcnt lgkmcnt(0)" ::: "memory"); __builtin_amdgcn_s_barrier(); asm volatile("" ::: "memory"); } while (0)
; __device__ __forceinline__ void conv16(const bf16_t* PROJ, const LAS float* cw, int rowbase, int t, int pcol, float (&y)[16]) {
;     ...
;     for (int j = 0; j < 16; ++j) y[j] = siluf_(y[j]);
; __device__ __forceinline__ void phase_chunk_prep(const Params& p, LAS unsigned char* lds, int wave_s) {
;     ...
;         float sq = 0.f, sk = 0.f;
; #pragma unroll
;         for (int j = 0; j < 16; ++j) { sq += q[j] * q[j]; sk += k[j] * k[j]; }
; #pragma unroll
;         for (int o = 1; o < 8; o <<= 1) { sq += bperm(sq, lane ^ o); sk += bperm(sk, lane ^ o); }
;         const float rq = rsqrtf(sq + EPS) * 0.08838834764831845f, rk = rsqrtf(sk + EPS);
; #pragma unroll
;         for (int j = 0; j < 16; ++j) { q[j] *= rq; k[j] *= rk; }
;         BAR_LDS();
;         const float gc_r = sgc[r], be_r = sbe[r], gc_last = sgc[63];
;         const float eg = __expf(gc_r), et = __expf(gc_last - gc_r);
	s_waitcnt vmcnt(0)
	v_lshlrev_b32_e32 v92, 16, v16
	v_and_b32_e32 v93, 0xffff0000, v16
	v_exp_f32_e32 v16, v8
	v_pk_mul_f32 v[8:9], v[106:107], v[0:1]
	v_mul_f32_e32 v0, 0xbfb8aa3b, v103
	v_pk_fma_f32 v[84:85], v[108:109], v[92:93], v[84:85]
	v_xor_b32_e32 v108, 4, v12
	v_xor_b32_e32 v106, 8, v12
	v_xor_b32_e32 v107, 16, v12
	v_add_f32_e32 v12, 1.0, v16
	v_exp_f32_e32 v16, v0
	v_pk_fma_f32 v[0:1], v[32:33], v[54:55], 0 op_sel_hi:[1,1,0]
	s_nop 0
	v_pk_fma_f32 v[0:1], v[68:69], v[20:21], v[0:1]
	v_rcp_f32_e32 v20, v12
	v_add_f32_e32 v12, 1.0, v16
	v_mul_f32_e32 v16, 0xbfb8aa3b, v120
	v_exp_f32_e32 v16, v16
	v_mul_f32_e32 v21, 0xbfb8aa3b, v121
	v_exp_f32_e32 v24, v21
	v_rcp_f32_e32 v21, v12
	v_add_f32_e32 v12, 1.0, v16
	v_rcp_f32_e32 v32, v12
	v_add_f32_e32 v12, 1.0, v24
	v_rcp_f32_e32 v33, v12
	v_mul_f32_e32 v12, 0xbfb8aa3b, v124
	v_exp_f32_e32 v12, v12
	v_pk_mul_f32 v[24:25], v[102:103], v[20:21]
	v_pk_mul_f32 v[54:55], v[120:121], v[32:33]
	v_pk_mul_f32 v[82:83], v[24:25], v[24:25]
	v_add_f32_e32 v16, 1.0, v12
	v_mul_f32_e32 v12, 0xbfb8aa3b, v125
	v_exp_f32_e32 v20, v12
	v_lshlrev_b32_e32 v12, 16, v13
	v_and_b32_e32 v13, 0xffff0000, v13
	v_pk_fma_f32 v[0:1], v[72:73], v[12:13], v[0:1]
	v_rcp_f32_e32 v12, v16
	v_mul_f32_e32 v16, 0xbfb8aa3b, v138
	v_add_f32_e32 v13, 1.0, v20
	v_exp_f32_e32 v16, v16
	v_mul_f32_e32 v20, 0xbfb8aa3b, v139
	v_exp_f32_e32 v21, v20
	v_rcp_f32_e32 v13, v13
	v_add_f32_e32 v16, 1.0, v16
	v_rcp_f32_e32 v20, v16
	v_add_f32_e32 v16, 1.0, v21
	v_rcp_f32_e32 v21, v16
	v_lshlrev_b32_e32 v16, 16, v17
	v_and_b32_e32 v17, 0xffff0000, v17
	v_pk_fma_f32 v[90:91], v[78:79], v[16:17], v[0:1]
	v_mul_f32_e32 v0, 0xbfb8aa3b, v126
	v_lshlrev_b32_e32 v16, 16, v10
	v_and_b32_e32 v17, 0xffff0000, v10
	v_mul_f32_e32 v10, 0xbfb8aa3b, v127
	v_pk_mul_f32 v[68:69], v[138:139], v[20:21]
	v_exp_f32_e32 v20, v0
	v_exp_f32_e32 v10, v10
	v_lshlrev_b32_e32 v0, 16, v22
	v_and_b32_e32 v1, 0xffff0000, v22
	v_pk_fma_f32 v[0:1], v[60:61], v[0:1], 0 op_sel_hi:[1,1,0]
	v_add_f32_e32 v22, 1.0, v20
	v_pk_fma_f32 v[0:1], v[62:63], v[16:17], v[0:1]
	v_lshlrev_b32_e32 v16, 16, v6
	v_and_b32_e32 v17, 0xffff0000, v6
	v_mul_f32_e32 v6, 0xbfb8aa3b, v144
	v_pk_fma_f32 v[20:21], v[70:71], v[16:17], v[0:1]
	v_add_f32_e32 v1, 1.0, v10
	v_exp_f32_e32 v6, v6
	v_mul_f32_e32 v10, 0xbfb8aa3b, v145
	v_exp_f32_e32 v10, v10
	v_rcp_f32_e32 v0, v22
	v_rcp_f32_e32 v1, v1
	v_add_f32_e32 v6, 1.0, v6
	v_rcp_f32_e32 v32, v6
	v_add_f32_e32 v6, 1.0, v10
	v_rcp_f32_e32 v33, v6
	v_lshl_add_u32 v6, v67, 2, 0
	v_add_u32_e32 v10, 0x1c800, v6
	v_pk_mul_f32 v[16:17], v[126:127], v[0:1]
	v_mov_b32_e32 v1, s51
	v_add_u32_e32 v6, 0x1c900, v6
	ds_read_b32 v10, v10
	ds_read_b32 v0, v6
	ds_read_b32 v1, v1
	v_pk_mul_f32 v[60:61], v[144:145], v[32:33]
	v_lshlrev_b32_e32 v32, 16, v2
	v_and_b32_e32 v33, 0xffff0000, v2
	s_waitcnt lgkmcnt(2)
	v_mul_f32_e32 v2, 0x3fb8aa3b, v10
	s_waitcnt lgkmcnt(0)
	v_sub_f32_e32 v6, v1, v10
	v_mul_lo_u32 v10, v67, s56
	v_add3_u32 v102, 0, v10, v64
	v_mul_f32_e32 v10, 0xbfb8aa3b, v146
	v_exp_f32_e32 v10, v10
	v_mul_f32_e32 v22, 0xbfb8aa3b, v147
	v_exp_f32_e32 v22, v22
	v_pk_fma_f32 v[92:93], v[74:75], v[32:33], v[20:21]
	v_pk_fma_f32 v[20:21], v[28:29], v[30:31], 0 op_sel_hi:[1,1,0]
	v_lshlrev_b32_e32 v28, 16, v26
	v_and_b32_e32 v29, 0xffff0000, v26
	v_pk_fma_f32 v[20:21], v[34:35], v[28:29], v[20:21]
	v_lshlrev_b32_e32 v28, 16, v14
	v_and_b32_e32 v29, 0xffff0000, v14
	v_add_f32_e32 v10, 1.0, v10
	v_mul_f32_e32 v14, 0xbfb8aa3b, v118
	v_pk_fma_f32 v[20:21], v[58:59], v[28:29], v[20:21]
	v_rcp_f32_e32 v28, v10
	v_add_f32_e32 v10, 1.0, v22
	v_exp_f32_e32 v14, v14
	v_mul_f32_e32 v22, 0xbfb8aa3b, v119
	v_exp_f32_e32 v22, v22
	v_rcp_f32_e32 v29, v10
	v_add_f32_e32 v10, 1.0, v14
	v_mul_f32_e32 v14, 0xbfb8aa3b, v122
	v_rcp_f32_e32 v30, v10
	v_add_f32_e32 v10, 1.0, v22
	v_exp_f32_e32 v14, v14
	v_mul_f32_e32 v22, 0xbfb8aa3b, v123
	v_exp_f32_e32 v22, v22
	v_rcp_f32_e32 v31, v10
	v_add_f32_e32 v10, 1.0, v14
	v_rcp_f32_e32 v34, v10
	v_add_f32_e32 v10, 1.0, v22
	v_rcp_f32_e32 v35, v10
	v_mul_f32_e32 v10, 0xbfb8aa3b, v88
	v_exp_f32_e32 v10, v10
	v_mul_f32_e32 v14, 0xbfb8aa3b, v89
	v_exp_f32_e32 v14, v14
	v_pk_mul_f32 v[58:59], v[118:119], v[30:31]
	v_add_f32_e32 v10, 1.0, v10
	v_pk_mul_f32 v[30:31], v[122:123], v[34:35]
	v_rcp_f32_e32 v34, v10
	v_add_f32_e32 v10, 1.0, v14
	v_rcp_f32_e32 v35, v10
	v_mul_f32_e32 v10, 0xbfb8aa3b, v96
	v_exp_f32_e32 v10, v10
	v_mul_f32_e32 v14, 0xbfb8aa3b, v97
	v_exp_f32_e32 v14, v14
	v_pk_mul_f32 v[62:63], v[88:89], v[34:35]
	v_add_f32_e32 v10, 1.0, v10
	v_rcp_f32_e32 v34, v10
	v_add_f32_e32 v10, 1.0, v14
	v_mul_f32_e32 v14, 0xbfb8aa3b, v100
	v_exp_f32_e32 v14, v14
	v_mul_f32_e32 v22, 0xbfb8aa3b, v101
	v_exp_f32_e32 v22, v22
	v_rcp_f32_e32 v35, v10
	v_add_f32_e32 v10, 1.0, v14
	v_mul_f32_e32 v14, 0xbfb8aa3b, v104
	v_rcp_f32_e32 v70, v10
	v_add_f32_e32 v10, 1.0, v22
	v_exp_f32_e32 v14, v14
	v_mul_f32_e32 v22, 0xbfb8aa3b, v105
	v_exp_f32_e32 v22, v22
	v_rcp_f32_e32 v71, v10
	v_add_f32_e32 v10, 1.0, v14
	v_rcp_f32_e32 v74, v10
	v_add_f32_e32 v10, 1.0, v22
	v_rcp_f32_e32 v75, v10
	v_mul_f32_e32 v10, 0xbfb8aa3b, v110
	v_exp_f32_e32 v10, v10
	v_mul_f32_e32 v14, 0xbfb8aa3b, v111
	v_exp_f32_e32 v14, v14
	v_mul_lo_u32 v32, v67, s57
	v_ashrrev_i32_e32 v33, 31, v32
	v_pk_mul_f32 v[34:35], v[96:97], v[34:35]
	v_add_f32_e32 v10, 1.0, v10
	v_lshl_add_u64 v[88:89], v[32:33], 1, s[30:31]
	v_pk_mul_f32 v[32:33], v[34:35], v[0:1] op_sel_hi:[1,0]
	v_pk_mul_f32 v[34:35], v[104:105], v[74:75]
	v_rcp_f32_e32 v74, v10
	v_add_f32_e32 v10, 1.0, v14
	v_mul_f32_e32 v14, 0xbfb8aa3b, v86
	v_exp_f32_e32 v14, v14
	v_mul_f32_e32 v22, 0xbfb8aa3b, v87
	v_exp_f32_e32 v22, v22
; __device__ __forceinline__ float siluf_(float x) { return x * __builtin_amdgcn_rcpf(1.0f + __expf(-x)); }
; __device__ __forceinline__ float bperm(float v, int srclane) { return __builtin_bit_cast(float, __builtin_amdgcn_ds_bpermute(srclane << 2, __builtin_bit_cast(int, v))); }
; __device__ __forceinline__ void conv16(const bf16_t* PROJ, const LAS float* cw, int rowbase, int t, int pcol, float (&y)[16]) {
;     ...
;     for (int j = 0; j < 16; ++j) y[j] = siluf_(y[j]);
; __device__ __forceinline__ void phase_chunk_prep(const Params& p, LAS unsigned char* lds, int wave_s) {
;     ...
;         float sq = 0.f, sk = 0.f;
; #pragma unroll
;         for (int j = 0; j < 16; ++j) { sq += q[j] * q[j]; sk += k[j] * k[j]; }
; #pragma unroll
;         for (int o = 1; o < 8; o <<= 1) { sq += bperm(sq, lane ^ o); sk += bperm(sk, lane ^ o); }
;         const float rq = rsqrtf(sq + EPS) * 0.08838834764831845f, rk = rsqrtf(sk + EPS);
	v_rcp_f32_e32 v75, v10
	v_add_f32_e32 v10, 1.0, v14
	v_mul_f32_e32 v14, 0xbfb8aa3b, v84
	v_rcp_f32_e32 v94, v10
	v_add_f32_e32 v10, 1.0, v22
	v_exp_f32_e32 v14, v14
	v_mul_f32_e32 v22, 0xbfb8aa3b, v85
	v_exp_f32_e32 v22, v22
	v_rcp_f32_e32 v95, v10
	v_add_f32_e32 v10, 1.0, v14
	v_rcp_f32_e32 v96, v10
	v_add_f32_e32 v10, 1.0, v22
	v_rcp_f32_e32 v97, v10
	v_mov_b32_e32 v22, v59
	v_mov_b32_e32 v23, v61
	v_pk_mul_f32 v[22:23], v[22:23], v[22:23]
	v_pk_mul_f32 v[84:85], v[84:85], v[96:97]
	v_lshlrev_b32_e32 v96, 16, v18
	v_and_b32_e32 v97, 0xffff0000, v18
	v_pk_fma_f32 v[56:57], v[56:57], v[96:97], v[20:21]
	v_mov_b32_e32 v20, v58
	v_mov_b32_e32 v21, v60
	v_mul_f32_e32 v10, 0xbfb8aa3b, v80
	v_pk_fma_f32 v[20:21], v[20:21], v[20:21], v[22:23]
	v_mov_b32_e32 v22, v62
	v_mov_b32_e32 v23, v16
	v_exp_f32_e32 v10, v10
	v_mul_f32_e32 v14, 0xbfb8aa3b, v81
	v_pk_mul_f32 v[70:71], v[100:101], v[70:71]
	v_pk_fma_f32 v[20:21], v[22:23], v[22:23], v[20:21]
	v_mov_b32_e32 v22, v63
	v_mov_b32_e32 v23, v17
	v_exp_f32_e32 v14, v14
	v_pk_fma_f32 v[20:21], v[22:23], v[22:23], v[20:21]
	v_mov_b32_e32 v22, v70
	v_mov_b32_e32 v23, v68
	v_pk_mul_f32 v[12:13], v[124:125], v[12:13]
	v_pk_mul_f32 v[74:75], v[110:111], v[74:75]
	v_pk_fma_f32 v[20:21], v[22:23], v[22:23], v[20:21]
	v_mov_b32_e32 v22, v71
	v_mov_b32_e32 v23, v69
	v_pk_fma_f32 v[20:21], v[22:23], v[22:23], v[20:21]
	v_mov_b32_e32 v22, v74
	v_mov_b32_e32 v23, v12
	v_add_f32_e32 v10, 1.0, v10
	v_pk_fma_f32 v[20:21], v[22:23], v[22:23], v[20:21]
	v_rcp_f32_e32 v22, v10
	v_add_f32_e32 v10, 1.0, v14
	v_rcp_f32_e32 v23, v10
	v_mul_f32_e32 v10, 0xbfb8aa3b, v90
	v_exp_f32_e32 v10, v10
	v_mul_f32_e32 v14, 0xbfb8aa3b, v91
	v_exp_f32_e32 v14, v14
	v_pk_mul_f32 v[22:23], v[80:81], v[22:23]
	v_add_f32_e32 v10, 1.0, v10
	v_rcp_f32_e32 v80, v10
	v_add_f32_e32 v10, 1.0, v14
	v_mul_f32_e32 v14, 0xbfb8aa3b, v92
	v_exp_f32_e32 v14, v14
	v_mul_f32_e32 v18, 0xbfb8aa3b, v93
	v_exp_f32_e32 v18, v18
	v_pk_mul_f32 v[78:79], v[54:55], v[54:55]
	v_pk_mul_f32 v[96:97], v[84:85], v[84:85]
	v_mov_b32_e32 v100, v75
	v_mov_b32_e32 v101, v13
	v_pk_mul_f32 v[94:95], v[86:87], v[94:95]
	v_pk_fma_f32 v[20:21], v[100:101], v[100:101], v[20:21]
	v_mov_b32_e32 v100, v96
	v_mov_b32_e32 v101, v78
	v_rcp_f32_e32 v81, v10
	v_add_f32_e32 v10, 1.0, v14
	v_mul_f32_e32 v14, 0xbfb8aa3b, v56
	v_pk_add_f32 v[100:101], v[100:101], v[20:21]
	v_pk_mul_f32 v[20:21], v[94:95], v[0:1] op_sel_hi:[1,0]
	v_rcp_f32_e32 v94, v10
	v_add_f32_e32 v10, 1.0, v18
	v_exp_f32_e32 v14, v14
	v_mul_f32_e32 v18, 0xbfb8aa3b, v57
	v_exp_f32_e32 v18, v18
	v_lshlrev_b32_e32 v26, 16, v27
	v_and_b32_e32 v27, 0xffff0000, v27
	v_rcp_f32_e32 v95, v10
	v_add_f32_e32 v10, 1.0, v14
	v_pk_fma_f32 v[26:27], v[42:43], v[26:27], v[36:37]
	v_lshlrev_b32_e32 v14, 16, v15
	v_and_b32_e32 v15, 0xffff0000, v15
	v_pk_mul_f32 v[80:81], v[90:91], v[80:81]
	v_rcp_f32_e32 v90, v10
	v_add_f32_e32 v10, 1.0, v18
	v_pk_fma_f32 v[14:15], v[48:49], v[14:15], v[26:27]
	v_lshlrev_b32_e32 v18, 16, v19
	v_and_b32_e32 v19, 0xffff0000, v19
	v_pk_fma_f32 v[14:15], v[52:53], v[18:19], v[14:15]
	v_rcp_f32_e32 v91, v10
	v_mul_f32_e32 v18, 0xbfb8aa3b, v14
	v_mul_f32_e32 v19, 0xbfb8aa3b, v15
	v_exp_f32_e32 v18, v18
	v_exp_f32_e32 v19, v19
	v_pk_mul_f32 v[92:93], v[92:93], v[94:95]
	v_pk_mul_f32 v[94:95], v[80:81], v[80:81]
	v_add_f32_e32 v18, 1.0, v18
	v_add_f32_e32 v19, 1.0, v19
	v_rcp_f32_e32 v18, v18
	v_rcp_f32_e32 v19, v19
	v_mov_b32_e32 v78, v97
	v_pk_mul_f32 v[56:57], v[56:57], v[90:91]
	v_pk_add_f32 v[36:37], v[78:79], v[100:101]
	v_mov_b32_e32 v38, v94
	v_mov_b32_e32 v39, v82
	v_pk_mul_f32 v[72:73], v[8:9], v[8:9]
	v_pk_mul_f32 v[90:91], v[56:57], v[56:57]
	v_pk_add_f32 v[36:37], v[38:39], v[36:37]
	v_mov_b32_e32 v82, v95
	v_pk_mul_f32 v[18:19], v[14:15], v[18:19]
	v_pk_add_f32 v[36:37], v[82:83], v[36:37]
	v_mov_b32_e32 v38, v90
	v_mov_b32_e32 v39, v72
	v_pk_mul_f32 v[14:15], v[18:19], v[18:19]
	v_pk_add_f32 v[36:37], v[38:39], v[36:37]
	v_mov_b32_e32 v72, v91
	v_pk_add_f32 v[36:37], v[72:73], v[36:37]
	v_mov_b32_e32 v38, v14
	v_mov_b32_e32 v39, v76
	v_pk_add_f32 v[36:37], v[38:39], v[36:37]
	v_mov_b32_e32 v76, v15
	v_pk_add_f32 v[14:15], v[76:77], v[36:37]
	ds_bpermute_b32 v37, v108, v15
	ds_bpermute_b32 v36, v108, v14
	v_lshlrev_b32_e32 v10, 16, v11
	v_and_b32_e32 v11, 0xffff0000, v11
	v_pk_fma_f32 v[10:11], v[44:45], v[10:11], v[40:41]
	v_lshlrev_b32_e32 v26, 16, v7
	v_and_b32_e32 v27, 0xffff0000, v7
	v_pk_fma_f32 v[10:11], v[46:47], v[26:27], v[10:11]
	v_lshlrev_b32_e32 v26, 16, v3
	v_and_b32_e32 v27, 0xffff0000, v3
	s_waitcnt lgkmcnt(0)
	v_pk_add_f32 v[14:15], v[14:15], v[36:37]
	v_pk_fma_f32 v[10:11], v[50:51], v[26:27], v[10:11]
	ds_bpermute_b32 v27, v106, v15
	ds_bpermute_b32 v26, v106, v14
	v_mul_f32_e32 v3, 0xbfb8aa3b, v10
	v_exp_f32_e32 v3, v3
	v_mul_f32_e32 v7, 0xbfb8aa3b, v11
	v_exp_f32_e32 v7, v7
	s_waitcnt lgkmcnt(0)
	v_pk_add_f32 v[14:15], v[14:15], v[26:27]
	ds_bpermute_b32 v27, v107, v15
	ds_bpermute_b32 v26, v107, v14
	v_add_f32_e32 v3, 1.0, v3
	v_rcp_f32_e32 v38, v3
	v_add_f32_e32 v3, 1.0, v7
	v_rcp_f32_e32 v39, v3
	s_waitcnt lgkmcnt(0)
; #define LAS __attribute__((address_space(3)))
; __device__ __forceinline__ unsigned pk2(float lo, float hi) { const f32x2_t v = {lo, hi}; const bf16x2_t b = __builtin_convertvector(v, bf16x2_t); return __builtin_bit_cast(unsigned, b); }
; __device__ __forceinline__ bf16_t f2bf(float x) { return (bf16_t)(pk2(x, 0.f) & 0xffffu); }
; __device__ __forceinline__ void phase_chunk_prep(const Params& p, LAS unsigned char* lds, int wave_s) {
;     ...
;         const float rq = rsqrtf(sq + EPS) * 0.08838834764831845f, rk = rsqrtf(sk + EPS);
; #pragma unroll
;         for (int j = 0; j < 16; ++j) { q[j] *= rq; k[j] *= rk; }
;         BAR_LDS();
;         const float gc_r = sgc[r], be_r = sbe[r], gc_last = sgc[63];
;         const float eg = __expf(gc_r), et = __expf(gc_last - gc_r);
;         {
;             u32x4 w0, w1;
;             w0.x = pk2(k[0], k[1]); w0.y = pk2(k[2], k[3]); w0.z = pk2(k[4], k[5]); w0.w = pk2(k[6], k[7]);
;             w1.x = pk2(k[8], k[9]); w1.y = pk2(k[10], k[11]); w1.z = pk2(k[12], k[13]); w1.w = pk2(k[14], k[15]);
;             *(LAS u32x4*)(KN + r * 136 + seg * 16) = w0; *(LAS u32x4*)(KN + r * 136 + seg * 16 + 8) = w1;
;             w0.x = pk2(q[0], q[1]); w0.y = pk2(q[2], q[3]); w0.z = pk2(q[4], q[5]); w0.w = pk2(q[6], q[7]);
;             w1.x = pk2(q[8], q[9]); w1.y = pk2(q[10], q[11]); w1.z = pk2(q[12], q[13]); w1.w = pk2(q[14], q[15]);
;             *(LAS u32x4*)(QN + r * 136 + seg * 16) = w0; *(LAS u32x4*)(QN + r * 136 + seg * 16 + 8) = w1;
;             w0.x = pk2(q[0] * eg, q[1] * eg); w0.y = pk2(q[2] * eg, q[3] * eg); w0.z = pk2(q[4] * eg, q[5] * eg); w0.w = pk2(q[6] * eg, q[7] * eg);
;             w1.x = pk2(q[8] * eg, q[9] * eg); w1.y = pk2(q[10] * eg, q[11] * eg); w1.z = pk2(q[12] * eg, q[13] * eg); w1.w = pk2(q[14] * eg, q[15] * eg);
;             { bf16_t* qd = img + IMG_QD + r * SWD + seg * 16;
;               *(u32x2*)(qd) = (u32x2){w0.x, w0.y}; *(u32x2*)(qd + 4) = (u32x2){w0.z, w0.w}; *(u32x2*)(qd + 8) = (u32x2){w1.x, w1.y}; *(u32x2*)(qd + 12) = (u32x2){w1.z, w1.w}; }
;         }
; #pragma unroll
;         for (int j = 0; j < 16; ++j) { RHS[r * 256 + seg * 16 + j] = v[j] * be_r; RHS[r * 256 + 128 + seg * 16 + j] = k[j] * be_r * eg; }
; #pragma unroll
;         for (int j = 0; j < 16; ++j) img[IMG_KT + (seg * 16 + j) * SKT + r] = f2bf(k[j] * et);
;         if (tid == 0) ((float*)(p.ws + WS_GL))[unit] = __expf(gc_last);
	v_pk_add_f32 v[14:15], v[14:15], v[26:27]
	v_exp_f32_e32 v2, v2
	v_pk_add_f32 v[26:27], v[14:15], s[14:15] op_sel_hi:[1,0]
	v_pk_mul_f32 v[10:11], v[10:11], v[38:39]
	v_mul_f32_e32 v3, 0x4b800000, v27
	v_cmp_gt_f32_e32 vcc, s58, v27
	v_pk_mul_f32 v[38:39], v[10:11], v[0:1] op_sel_hi:[1,0]
	v_lshl_add_u64 v[88:89], v[88:89], 0, v[64:65]
	v_cndmask_b32_e32 v3, v27, v3, vcc
	v_rsq_f32_e32 v3, v3
	v_lshl_add_u64 v[86:87], v[88:89], 0, s[12:13]
	v_lshl_add_u32 v64, v67, 10, v210
	v_mul_f32_e32 v6, 0x3fb8aa3b, v6
	v_mul_f32_e32 v7, 0x45800000, v3
	v_cndmask_b32_e32 v3, v3, v7, vcc
	v_mul_f32_e32 v10, 0x3db504f3, v3
	v_pk_mul_f32 v[40:41], v[60:61], v[10:11] op_sel_hi:[1,0]
	v_pk_mul_f32 v[16:17], v[16:17], v[10:11] op_sel_hi:[1,0]
	v_pk_mul_f32 v[42:43], v[68:69], v[10:11] op_sel_hi:[1,0]
	v_pk_mul_f32 v[44:45], v[12:13], v[10:11] op_sel_hi:[1,0]
	v_pk_mul_f32 v[46:47], v[54:55], v[10:11] op_sel_hi:[1,0]
	v_pk_mul_f32 v[24:25], v[24:25], v[10:11] op_sel_hi:[1,0]
	v_pk_mul_f32 v[48:49], v[8:9], v[10:11] op_sel_hi:[1,0]
	v_pk_mul_f32 v[4:5], v[4:5], v[10:11] op_sel_hi:[1,0]
	v_cvt_pk_bf16_f32 v8, v40, v41
	v_cvt_pk_bf16_f32 v9, v16, v17
	v_cvt_pk_bf16_f32 v10, v42, v43
	v_cvt_pk_bf16_f32 v11, v44, v45
	v_cvt_pk_bf16_f32 v12, v46, v47
	v_cvt_pk_bf16_f32 v13, v24, v25
	v_cvt_pk_bf16_f32 v14, v48, v49
	v_cvt_pk_bf16_f32 v15, v4, v5
	ds_write_b128 v102, v[8:11] offset:17408
	ds_write_b128 v102, v[12:15] offset:17424
	v_pk_mul_f32 v[8:9], v[2:3], v[40:41] op_sel_hi:[0,1]
	v_pk_mul_f32 v[10:11], v[2:3], v[16:17] op_sel_hi:[0,1]
	v_cvt_pk_bf16_f32 v8, v8, v9
	v_cvt_pk_bf16_f32 v9, v10, v11
	v_pk_mul_f32 v[10:11], v[2:3], v[42:43] op_sel_hi:[0,1]
	v_pk_mul_f32 v[12:13], v[2:3], v[44:45] op_sel_hi:[0,1]
	v_cvt_pk_bf16_f32 v10, v10, v11
	v_cvt_pk_bf16_f32 v11, v12, v13
	v_pk_mul_f32 v[12:13], v[2:3], v[46:47] op_sel_hi:[0,1]
	v_pk_mul_f32 v[14:15], v[2:3], v[24:25] op_sel_hi:[0,1]
	v_cvt_pk_bf16_f32 v12, v12, v13
	v_cvt_pk_bf16_f32 v13, v14, v15
	v_pk_mul_f32 v[14:15], v[2:3], v[48:49] op_sel_hi:[0,1]
	v_pk_mul_f32 v[4:5], v[2:3], v[4:5] op_sel_hi:[0,1]
	v_mul_f32_e32 v3, 0x4b800000, v26
	v_cmp_gt_f32_e32 vcc, s58, v26
	v_cvt_pk_bf16_f32 v14, v14, v15
	v_cvt_pk_bf16_f32 v15, v4, v5
	v_cndmask_b32_e32 v3, v26, v3, vcc
	v_rsq_f32_e32 v3, v3
	v_add_co_u32_e64 v4, s[4:5], s47, v88
	v_pk_mul_f32 v[28:29], v[146:147], v[28:29]
	s_nop 0
	v_addc_co_u32_e64 v5, s[4:5], 0, v89, s[4:5]
	global_store_dwordx4 v[4:5], v[8:11], off offset:512
	global_store_dwordx4 v[86:87], v[12:15], off offset:16
	v_mul_f32_e32 v4, 0x45800000, v3
	v_cndmask_b32_e32 v4, v3, v4, vcc
	v_pk_mul_f32 v[16:17], v[58:59], v[4:5] op_sel_hi:[1,0]
	v_pk_mul_f32 v[24:25], v[62:63], v[4:5] op_sel_hi:[1,0]
	v_pk_mul_f32 v[26:27], v[70:71], v[4:5] op_sel_hi:[1,0]
	v_pk_mul_f32 v[40:41], v[74:75], v[4:5] op_sel_hi:[1,0]
	v_pk_mul_f32 v[42:43], v[84:85], v[4:5] op_sel_hi:[1,0]
	v_pk_mul_f32 v[44:45], v[80:81], v[4:5] op_sel_hi:[1,0]
	v_pk_mul_f32 v[46:47], v[56:57], v[4:5] op_sel_hi:[1,0]
	v_pk_mul_f32 v[18:19], v[18:19], v[4:5] op_sel_hi:[1,0]
	v_cvt_pk_bf16_f32 v8, v16, v17
	v_cvt_pk_bf16_f32 v9, v24, v25
	v_cvt_pk_bf16_f32 v10, v26, v27
	v_cvt_pk_bf16_f32 v11, v40, v41
	v_pk_mul_f32 v[4:5], v[0:1], v[16:17] op_sel_hi:[0,1]
	v_cvt_pk_bf16_f32 v12, v42, v43
	v_cvt_pk_bf16_f32 v13, v44, v45
	v_cvt_pk_bf16_f32 v14, v46, v47
	v_cvt_pk_bf16_f32 v15, v18, v19
	ds_write_b128 v102, v[8:11]
	ds_write_b128 v102, v[12:15] offset:16
	v_pk_mul_f32 v[8:9], v[2:3], v[4:5] op_sel_hi:[0,1]
	v_pk_mul_f32 v[4:5], v[0:1], v[24:25] op_sel_hi:[0,1]
	v_pk_mul_f32 v[10:11], v[2:3], v[4:5] op_sel_hi:[0,1]
	v_pk_mul_f32 v[4:5], v[0:1], v[26:27] op_sel_hi:[0,1]
	ds_write_b128 v64, v[8:11] offset:51712
	v_pk_mul_f32 v[8:9], v[2:3], v[4:5] op_sel_hi:[0,1]
	v_pk_mul_f32 v[4:5], v[0:1], v[40:41] op_sel_hi:[0,1]
	v_pk_mul_f32 v[10:11], v[2:3], v[4:5] op_sel_hi:[0,1]
	v_pk_mul_f32 v[4:5], v[0:1], v[42:43] op_sel_hi:[0,1]
	ds_write_b128 v64, v[8:11] offset:51728
	v_pk_mul_f32 v[8:9], v[2:3], v[4:5] op_sel_hi:[0,1]
	v_pk_mul_f32 v[4:5], v[0:1], v[44:45] op_sel_hi:[0,1]
	v_pk_mul_f32 v[10:11], v[2:3], v[4:5] op_sel_hi:[0,1]
	ds_write_b128 v64, v[8:11] offset:51744
	v_exp_f32_e32 v8, v6
	v_pk_mul_f32 v[4:5], v[0:1], v[46:47] op_sel_hi:[0,1]
	v_pk_mul_f32 v[6:7], v[0:1], v[18:19] op_sel_hi:[0,1]
	v_pk_mul_f32 v[4:5], v[2:3], v[4:5] op_sel_hi:[0,1]
	v_pk_mul_f32 v[6:7], v[2:3], v[6:7] op_sel_hi:[0,1]
	v_mul_u32_u24_e32 v2, 0x44, v209
	v_add3_u32 v2, v67, v2, s59
	v_pk_mul_f32 v[28:29], v[28:29], v[0:1] op_sel_hi:[1,0]
	v_pk_mul_f32 v[30:31], v[30:31], v[0:1] op_sel_hi:[1,0]
	v_pk_mul_f32 v[34:35], v[34:35], v[0:1] op_sel_hi:[1,0]
	v_pk_mul_f32 v[22:23], v[22:23], v[0:1] op_sel_hi:[1,0]
	v_pk_mul_f32 v[36:37], v[92:93], v[0:1] op_sel_hi:[1,0]
	v_mul_f32_e32 v0, v8, v16
	v_ashrrev_i32_e32 v3, 31, v2
	v_cvt_pk_bf16_f32 v0, v0, s0
	v_lshl_add_u64 v[2:3], v[2:3], 1, s[30:31]
	global_store_short v[2:3], v0, off
	v_mul_f32_e32 v0, v8, v17
	v_cvt_pk_bf16_f32 v0, v0, s0
	global_store_short v[2:3], v0, off offset:136
	v_mul_f32_e32 v0, v8, v24
	v_cvt_pk_bf16_f32 v0, v0, s0
	global_store_short v[2:3], v0, off offset:272
	v_mul_f32_e32 v0, v8, v25
	v_cvt_pk_bf16_f32 v0, v0, s0
	global_store_short v[2:3], v0, off offset:408
	v_mul_f32_e32 v0, v8, v26
	v_cvt_pk_bf16_f32 v0, v0, s0
	global_store_short v[2:3], v0, off offset:544
	v_mul_f32_e32 v0, v8, v27
	v_cvt_pk_bf16_f32 v0, v0, s0
	global_store_short v[2:3], v0, off offset:680
	v_mul_f32_e32 v0, v8, v40
	v_cvt_pk_bf16_f32 v0, v0, s0
	global_store_short v[2:3], v0, off offset:816
	v_mul_f32_e32 v0, v8, v41
	v_cvt_pk_bf16_f32 v0, v0, s0
	global_store_short v[2:3], v0, off offset:952
	v_mul_f32_e32 v0, v8, v42
	v_cvt_pk_bf16_f32 v0, v0, s0
	global_store_short v[2:3], v0, off offset:1088
	v_mul_f32_e32 v0, v8, v43
	v_cvt_pk_bf16_f32 v0, v0, s0
	global_store_short v[2:3], v0, off offset:1224
	v_mul_f32_e32 v0, v8, v44
	v_cvt_pk_bf16_f32 v0, v0, s0
	global_store_short v[2:3], v0, off offset:1360
	v_mul_f32_e32 v0, v8, v45
	v_cvt_pk_bf16_f32 v0, v0, s0
	global_store_short v[2:3], v0, off offset:1496
	v_mul_f32_e32 v0, v8, v46
	v_cvt_pk_bf16_f32 v0, v0, s0
	global_store_short v[2:3], v0, off offset:1632
	v_mul_f32_e32 v0, v8, v47
	v_cvt_pk_bf16_f32 v0, v0, s0
	global_store_short v[2:3], v0, off offset:1768
	v_mul_f32_e32 v0, v8, v18
	v_cvt_pk_bf16_f32 v0, v0, s0
	global_store_short v[2:3], v0, off offset:1904
	v_mul_f32_e32 v0, v8, v19
	v_cvt_pk_bf16_f32 v0, v0, s0
	v_cmp_eq_u32_e32 vcc, 0, v66
	ds_write_b128 v64, v[28:31] offset:51200
	ds_write_b128 v64, v[32:35] offset:51216
	ds_write_b128 v64, v[20:23] offset:51232
	ds_write_b128 v64, v[36:39] offset:51248
	ds_write_b128 v64, v[4:7] offset:51760
	global_store_short v[2:3], v0, off offset:2040
	s_and_saveexec_b64 s[4:5], vcc
	s_cbranch_execz .LBB0_685
	v_mul_f32_e32 v0, 0x3fb8aa3b, v1
	v_exp_f32_e32 v0, v0
	s_lshl_b64 s[34:35], s[16:17], 2
	s_add_u32 s34, s39, s34
	s_addc_u32 s35, s40, s35
	global_store_dword v65, v0, s[34:35]

; #define LAS __attribute__((address_space(3)))
; __device__ __forceinline__ void conv16(const bf16_t* PROJ, const LAS float* cw, int rowbase, int t, int pcol, float (&y)[16]) {
;     u32x4 a[4], b[4];
; #pragma unroll
;     for (int i = 0; i < 4; ++i) {
;         const int tt = t - 3 + i, tc = tt < 0 ? 0 : tt;
;         a[i] = *(const u32x4*)(PROJ + (size_t)(rowbase + tc) * NQ + pcol); b[i] = *(const u32x4*)(PROJ + (size_t)(rowbase + tc) * NQ + pcol + 8);
;     }
; __device__ __forceinline__ void phase_chunk_prep(const Params& p, LAS unsigned char* lds, int wave_s) {
;     ...
;         conv16(PROJ, CW + seg * 16, rowbase, t, 1024 + h * 128 + seg * 16, q);
;         conv16(PROJ, CW + 512 + seg * 16, rowbase, t, 1024 + 2048 + h * 128 + seg * 16, k);
;         conv16(PROJ, CW + 1024 + seg * 16, rowbase, t, 1024 + 4096 + h * 128 + seg * 16, v);
.LBB0_781:
	s_or_b64 exec, exec, s[4:5]
	s_waitcnt lgkmcnt(0)
	s_barrier
	s_lshr_b32 s84, s24, 6
	v_mbcnt_lo_u32_b32 v252, -1, 0
	v_mbcnt_hi_u32_b32 v252, -1, v252
	s_lshl_b32 s85, s16, 2
	s_and_b32 s85, s85, 0xfffff800
	s_lshl_b32 s86, s16, 6
	s_and_b32 s86, s86, 0x7c0
	s_lshl_b32 s94, s78, 8
	s_addk_i32 s94, 0x800
	v_lshrrev_b32_e32 v253, 4, v252
	v_mul_u32_u24_e32 v253, 0x4800, v253
	v_and_b32_e32 v252, 15, v252
	v_lshl_add_u32 v253, v252, 4, v253
	s_add_i32 s85, s85, s86
	s_add_i32 s85, s85, 61
	s_mov_b32 s86, s84
	s_cmp_gt_u32 s86, 16
	s_cselect_b32 s87, 1, 0
	s_cmp_gt_u32 s86, 33
	s_cselect_b32 s88, 1, 0
	s_add_i32 s87, s87, s88
	s_mul_i32 s88, s87, 17
	s_sub_i32 s88, s86, s88
	s_mul_i32 s89, s87, 0x4400
	s_cmp_eq_u32 s87, 2
	s_cselect_b32 s89, 0x1e200, s89
	s_lshl_b32 s90, s88, 10
	s_add_i32 s89, s89, s90
	s_lshl_b32 s91, s87, 12
	s_lshl_b32 s90, s88, 2
	s_add_i32 s90, s90, s85
	s_mul_i32 s90, s90, 0x4800
	s_add_i32 s90, s90, s91
	s_add_i32 s90, s90, s94
	s_add_u32 s92, s28, s90
	s_addc_u32 s93, s29, 0
	s_mov_b32 m0, s89
	s_nop 0
	global_load_lds_dwordx4 v253, s[92:93]
	s_add_i32 s86, s84, 8
	s_cmp_gt_u32 s86, 16
	s_cselect_b32 s87, 1, 0
	s_cmp_gt_u32 s86, 33
	s_cselect_b32 s88, 1, 0
	s_add_i32 s87, s87, s88
	s_mul_i32 s88, s87, 17
	s_sub_i32 s88, s86, s88
	s_mul_i32 s89, s87, 0x4400
	s_cmp_eq_u32 s87, 2
	s_cselect_b32 s89, 0x1e200, s89
	s_lshl_b32 s90, s88, 10
	s_add_i32 s89, s89, s90
	s_lshl_b32 s91, s87, 12
	s_lshl_b32 s90, s88, 2
	s_add_i32 s90, s90, s85
	s_mul_i32 s90, s90, 0x4800
	s_add_i32 s90, s90, s91
	s_add_i32 s90, s90, s94
	s_add_u32 s92, s28, s90
	s_addc_u32 s93, s29, 0
	s_mov_b32 m0, s89
	s_nop 0
	global_load_lds_dwordx4 v253, s[92:93]
	s_add_i32 s86, s84, 16
	s_cmp_gt_u32 s86, 16
	s_cselect_b32 s87, 1, 0
	s_cmp_gt_u32 s86, 33
	s_cselect_b32 s88, 1, 0
	s_add_i32 s87, s87, s88
	s_mul_i32 s88, s87, 17
	s_sub_i32 s88, s86, s88
	s_mul_i32 s89, s87, 0x4400
	s_cmp_eq_u32 s87, 2
	s_cselect_b32 s89, 0x1e200, s89
	s_lshl_b32 s90, s88, 10
	s_add_i32 s89, s89, s90
	s_lshl_b32 s91, s87, 12
	s_lshl_b32 s90, s88, 2
	s_add_i32 s90, s90, s85
	s_mul_i32 s90, s90, 0x4800
	s_add_i32 s90, s90, s91
	s_add_i32 s90, s90, s94
	s_add_u32 s92, s28, s90
	s_addc_u32 s93, s29, 0
	s_mov_b32 m0, s89
	s_nop 0
	global_load_lds_dwordx4 v253, s[92:93]
	s_add_i32 s86, s84, 24
	s_cmp_gt_u32 s86, 16
	s_cselect_b32 s87, 1, 0
	s_cmp_gt_u32 s86, 33
	s_cselect_b32 s88, 1, 0
	s_add_i32 s87, s87, s88
	s_mul_i32 s88, s87, 17
	s_sub_i32 s88, s86, s88
	s_mul_i32 s89, s87, 0x4400
	s_cmp_eq_u32 s87, 2
	s_cselect_b32 s89, 0x1e200, s89
	s_lshl_b32 s90, s88, 10
	s_add_i32 s89, s89, s90
	s_lshl_b32 s91, s87, 12
	s_lshl_b32 s90, s88, 2
	s_add_i32 s90, s90, s85
	s_mul_i32 s90, s90, 0x4800
	s_add_i32 s90, s90, s91
	s_add_i32 s90, s90, s94
	s_add_u32 s92, s28, s90
	s_addc_u32 s93, s29, 0
	s_mov_b32 m0, s89
	s_nop 0
	global_load_lds_dwordx4 v253, s[92:93]
	s_add_i32 s86, s84, 32
	s_cmp_gt_u32 s86, 16
	s_cselect_b32 s87, 1, 0
	s_cmp_gt_u32 s86, 33
	s_cselect_b32 s88, 1, 0
	s_add_i32 s87, s87, s88
	s_mul_i32 s88, s87, 17
	s_sub_i32 s88, s86, s88
	s_mul_i32 s89, s87, 0x4400
	s_cmp_eq_u32 s87, 2
	s_cselect_b32 s89, 0x1e200, s89
	s_lshl_b32 s90, s88, 10
	s_add_i32 s89, s89, s90
	s_lshl_b32 s91, s87, 12
	s_lshl_b32 s90, s88, 2
	s_add_i32 s90, s90, s85
	s_mul_i32 s90, s90, 0x4800
	s_add_i32 s90, s90, s91
	s_add_i32 s90, s90, s94
	s_add_u32 s92, s28, s90
	s_addc_u32 s93, s29, 0
	s_mov_b32 m0, s89
	s_nop 0
	global_load_lds_dwordx4 v253, s[92:93]
	s_add_i32 s86, s84, 40
	s_cmp_gt_u32 s86, 16
	s_cselect_b32 s87, 1, 0
	s_cmp_gt_u32 s86, 33
	s_cselect_b32 s88, 1, 0
	s_add_i32 s87, s87, s88
	s_mul_i32 s88, s87, 17
	s_sub_i32 s88, s86, s88
	s_mul_i32 s89, s87, 0x4400
	s_cmp_eq_u32 s87, 2
	s_cselect_b32 s89, 0x1e200, s89
	s_lshl_b32 s90, s88, 10
	s_add_i32 s89, s89, s90
	s_lshl_b32 s91, s87, 12
	s_lshl_b32 s90, s88, 2
	s_add_i32 s90, s90, s85
	s_mul_i32 s90, s90, 0x4800
	s_add_i32 s90, s90, s91
	s_add_i32 s90, s90, s94
	s_add_u32 s92, s28, s90
	s_addc_u32 s93, s29, 0
	s_mov_b32 m0, s89
	s_nop 0
	global_load_lds_dwordx4 v253, s[92:93]
	s_add_i32 s86, s84, 48
	s_cmp_gt_u32 s86, 50
	s_cbranch_scc1 .Lcpstage_n_end
	s_cmp_gt_u32 s86, 16
	s_cselect_b32 s87, 1, 0
	s_cmp_gt_u32 s86, 33
	s_cselect_b32 s88, 1, 0
	s_add_i32 s87, s87, s88
	s_mul_i32 s88, s87, 17
	s_sub_i32 s88, s86, s88
	s_mul_i32 s89, s87, 0x4400
	s_cmp_eq_u32 s87, 2
	s_cselect_b32 s89, 0x1e200, s89
	s_lshl_b32 s90, s88, 10
	s_add_i32 s89, s89, s90
	s_lshl_b32 s91, s87, 12
	s_lshl_b32 s90, s88, 2
	s_add_i32 s90, s90, s85
	s_mul_i32 s90, s90, 0x4800
	s_add_i32 s90, s90, s91
	s_add_i32 s90, s90, s94
	s_add_u32 s92, s28, s90
	s_addc_u32 s93, s29, 0
	s_mov_b32 m0, s89
	s_nop 0
	global_load_lds_dwordx4 v253, s[92:93]
; #define LAS __attribute__((address_space(3)))
; __device__ __forceinline__ void phase_chunk_prep(const Params& p, LAS unsigned char* lds, int wave_s) {
;     ...
;         if (tid < 256) {
;             const int col = tid; float sol[64];
; #pragma unroll
;             for (int i = 0; i < 64; ++i) sol[i] = 0.f;
; #pragma unroll
;             for (int i = 0; i < 64; ++i) {
;                 float s0 = RHS[i * 256 + col], s1 = 0.f, s2 = 0.f, s3 = 0.f;
; #pragma unroll
;                 for (int j4 = 0; j4 < (i + 3) / 4; ++j4) { const f32x4 a = *(const LAS f32x4*)(AM + i * 64 + 4 * j4);
;                     s0 -= a.x * sol[4 * j4]; s1 -= a.y * sol[4 * j4 + 1]; s2 -= a.z * sol[4 * j4 + 2]; s3 -= a.w * sol[4 * j4 + 3]; }
;                 sol[i] = (s0 + s1) + (s2 + s3);
;             }
.Lcpstage_n_end:
	v_cmp_gt_i32_e32 vcc, s61, v66
	s_and_saveexec_b64 s[4:5], vcc
	s_cbranch_execz .Lcpstage_w47
	v_lshl_add_u32 v30, v66, 2, 0
	s_waitcnt lgkmcnt(0)
	ds_read_b128 v[2:5], v65 offset:35072
	ds_read2st64_b32 v[0:1], v30 offset0:200 offset1:204
	ds_read_b128 v[6:9], v65 offset:35328
	v_add_u32_e32 v62, 0xc800, v30
	v_cmp_lt_i32_e32 vcc, s41, v66
	s_waitcnt lgkmcnt(2)
	v_fma_f32 v3, v3, s66, 0
	s_waitcnt lgkmcnt(1)
	v_add_f32_e32 v0, 0, v0
	v_fma_f32 v1, -v0, v2, v1
	v_add_f32_e32 v1, v1, v3
	ds_read2st64_b32 v[2:3], v30 offset0:208 offset1:212
	v_fma_f32 v5, v5, s66, 0
	v_fma_f32 v4, v4, s66, 0
	v_add_f32_e32 v4, v4, v5
	v_add_f32_e32 v1, v1, v4
	s_waitcnt lgkmcnt(1)
	v_fma_f32 v10, -v7, v1, 0
	s_waitcnt lgkmcnt(0)
	v_fma_f32 v2, -v0, v6, v2
	ds_read_b128 v[4:7], v65 offset:35584
	v_fma_f32 v9, v9, s66, 0
	v_fma_f32 v8, v8, s66, 0
	v_add_f32_e32 v2, v2, v10
	v_add_f32_e32 v8, v8, v9
	v_add_f32_e32 v2, v8, v2
	ds_read_b128 v[8:11], v65 offset:35840
	s_waitcnt lgkmcnt(1)
	v_fma_f32 v5, -v5, v1, 0
	v_fma_f32 v3, -v0, v4, v3
	v_add_f32_e32 v3, v3, v5
	ds_read2st64_b32 v[4:5], v30 offset0:216 offset1:220
	v_fma_f32 v7, v7, s66, 0
	v_fma_f32 v6, -v6, v2, 0
	v_add_f32_e32 v6, v7, v6
	v_add_f32_e32 v3, v3, v6
	s_waitcnt lgkmcnt(1)
	v_fma_f32 v14, -v11, v3, 0
	v_fma_f32 v15, -v10, v2, 0
	v_fma_f32 v16, -v1, v9, 0
	s_waitcnt lgkmcnt(0)
	v_fma_f32 v4, -v0, v8, v4
	ds_read_b128 v[6:9], v65 offset:36096
	ds_read_b128 v[10:13], v65 offset:36112
	v_add_f32_e32 v4, v4, v16
	v_add_f32_e32 v14, v15, v14
	v_add_f32_e32 v4, v4, v14
	s_waitcnt lgkmcnt(1)
	v_fma_f32 v16, -v1, v7, 0
	v_fma_f32 v5, -v0, v6, v5
	v_fma_f32 v14, -v9, v3, 0
	v_fma_f32 v15, -v8, v2, 0
	s_waitcnt lgkmcnt(0)
	v_fmac_f32_e32 v16, 0x80000000, v11
	v_fma_f32 v5, -v10, v4, v5
	v_fmac_f32_e32 v14, 0x80000000, v13
	v_fmac_f32_e32 v15, 0x80000000, v12
	ds_read_b128 v[6:9], v65 offset:36352
	ds_read_b128 v[10:13], v65 offset:36368
	v_add_f32_e32 v5, v16, v5
	ds_read2st64_b32 v[16:17], v30 offset0:224 offset1:228
	v_add_f32_e32 v14, v15, v14
	v_add_f32_e32 v5, v14, v5
	s_waitcnt lgkmcnt(2)
	v_fma_f32 v18, -v9, v3, 0
	v_fma_f32 v19, -v2, v8, 0
	v_fma_f32 v7, -v1, v7, 0
	s_waitcnt lgkmcnt(0)
	v_fma_f32 v6, -v0, v6, v16
	v_fmac_f32_e32 v18, 0x80000000, v13
	v_fmac_f32_e32 v19, 0x80000000, v12
	v_fma_f32 v7, -v11, v5, v7
	v_fma_f32 v6, -v10, v4, v6
	ds_read_b128 v[8:11], v65 offset:36608
	ds_read_b128 v[12:15], v65 offset:36624
	v_add_f32_e32 v6, v6, v7
	v_add_f32_e32 v7, v19, v18
	v_add_f32_e32 v6, v7, v6
	s_waitcnt lgkmcnt(1)
	v_fma_f32 v7, -v3, v11, 0
	v_fma_f32 v10, -v2, v10, 0
	v_fma_f32 v9, -v1, v9, 0
	v_fma_f32 v8, -v0, v8, v17
	s_waitcnt lgkmcnt(0)
	v_fmac_f32_e32 v7, 0x80000000, v15
	v_fma_f32 v16, -v14, v6, v10
	v_fma_f32 v18, -v13, v5, v9
	v_fma_f32 v17, -v12, v4, v8
	ds_read_b128 v[8:11], v65 offset:36864
	ds_read_b128 v[12:15], v65 offset:36880
	ds_read2st64_b32 v[26:27], v30 offset0:232 offset1:236
	v_add_f32_e32 v17, v17, v18
	v_add_f32_e32 v7, v7, v16
	v_add_f32_e32 v7, v17, v7
	s_waitcnt lgkmcnt(2)
	v_fma_f32 v11, -v3, v11, 0
	v_fma_f32 v10, -v2, v10, 0
	v_fma_f32 v9, -v1, v9, 0
	s_waitcnt lgkmcnt(0)
	v_fma_f32 v8, -v0, v8, v26
	v_fma_f32 v18, -v15, v7, v11
	v_fma_f32 v19, -v14, v6, v10
	v_fma_f32 v9, -v13, v5, v9
	v_fma_f32 v8, -v4, v12, v8
	ds_read_b128 v[10:13], v65 offset:37120
	ds_read_b128 v[14:17], v65 offset:37136
	v_add_f32_e32 v8, v8, v9
	v_add_f32_e32 v9, v19, v18
	ds_read_b128 v[18:21], v65 offset:37152
	ds_read_b128 v[22:25], v65 offset:37376
	s_waitcnt lgkmcnt(3)
	v_fma_f32 v11, -v1, v11, 0
	v_fma_f32 v10, -v0, v10, v27
	v_add_f32_e32 v8, v8, v9
	v_fma_f32 v9, -v3, v13, 0
	s_waitcnt lgkmcnt(2)
	v_fma_f32 v11, -v5, v15, v11
	v_fma_f32 v10, -v4, v14, v10
	v_fma_f32 v9, -v17, v7, v9
	v_fma_f32 v12, -v2, v12, 0
	s_waitcnt lgkmcnt(1)
	v_fmac_f32_e32 v11, 0x80000000, v19
	v_fma_f32 v10, -v18, v8, v10
	v_fmac_f32_e32 v9, 0x80000000, v21
	v_fma_f32 v21, -v16, v6, v12
	v_add_f32_e32 v18, v11, v10
	ds_read_b128 v[10:13], v65 offset:37392
	ds_read_b128 v[14:17], v65 offset:37408
	v_fmac_f32_e32 v21, 0x80000000, v20
	ds_read2st64_b32 v[28:29], v30 offset0:240 offset1:244
	v_add_f32_e32 v9, v21, v9
	v_add_f32_e32 v9, v9, v18
	s_waitcnt lgkmcnt(3)
	v_fma_f32 v18, -v3, v25, 0
	s_waitcnt lgkmcnt(2)
	v_fma_f32 v20, -v13, v7, v18
	v_fma_f32 v13, -v2, v24, 0
	v_fma_f32 v21, -v6, v12, v13
	v_fma_f32 v12, -v1, v23, 0
	v_fma_f32 v11, -v5, v11, v12
	s_waitcnt lgkmcnt(0)
	v_fma_f32 v12, -v0, v22, v28
	v_fma_f32 v10, -v4, v10, v12
	v_fmac_f32_e32 v20, 0x80000000, v17
	v_fmac_f32_e32 v21, 0x80000000, v16
	v_fma_f32 v11, -v15, v9, v11
	v_fma_f32 v10, -v14, v8, v10
	ds_read_b128 v[12:15], v65 offset:37632
	ds_read_b128 v[16:19], v65 offset:37648
	v_add_f32_e32 v10, v10, v11
	v_add_f32_e32 v11, v21, v20
	ds_read_b128 v[20:23], v65 offset:37664
	ds_read_b128 v[24:27], v65 offset:37888
	s_waitcnt lgkmcnt(3)
	v_fma_f32 v13, -v1, v13, 0
	v_fma_f32 v12, -v0, v12, v29
	v_fma_f32 v14, -v2, v14, 0
	s_waitcnt lgkmcnt(2)
	v_fma_f32 v13, -v5, v17, v13
	v_fma_f32 v12, -v4, v16, v12
	v_add_f32_e32 v10, v11, v10
	v_fma_f32 v11, -v3, v15, 0
	v_fma_f32 v14, -v6, v18, v14
	s_waitcnt lgkmcnt(1)
	v_fma_f32 v13, -v21, v9, v13
	v_fma_f32 v12, -v20, v8, v12
	v_fma_f32 v11, -v7, v19, v11
	v_fma_f32 v22, -v22, v10, v14
	v_add_f32_e32 v20, v12, v13
	ds_read_b128 v[12:15], v65 offset:37904
	ds_read_b128 v[16:19], v65 offset:37920
	v_fmac_f32_e32 v11, 0x80000000, v23
	v_add_f32_e32 v11, v11, v22
	v_add_f32_e32 v11, v20, v11
	s_waitcnt lgkmcnt(2)
	v_fma_f32 v20, -v3, v27, 0
	s_waitcnt lgkmcnt(1)
	v_fma_f32 v15, -v7, v15, v20
	ds_read2st64_b32 v[30:31], v30 offset0:248 offset1:252
	s_waitcnt lgkmcnt(1)
; #define LAS __attribute__((address_space(3)))
; __device__ __forceinline__ void phase_chunk_prep(const Params& p, LAS unsigned char* lds, int wave_s) {
;     ...
;             for (int i = 0; i < 64; ++i) {
;                 float s0 = RHS[i * 256 + col], s1 = 0.f, s2 = 0.f, s3 = 0.f;
; #pragma unroll
;                 for (int j4 = 0; j4 < (i + 3) / 4; ++j4) { const f32x4 a = *(const LAS f32x4*)(AM + i * 64 + 4 * j4);
;                     s0 -= a.x * sol[4 * j4]; s1 -= a.y * sol[4 * j4 + 1]; s2 -= a.z * sol[4 * j4 + 2]; s3 -= a.w * sol[4 * j4 + 3]; }
;                 sol[i] = (s0 + s1) + (s2 + s3);
	v_fma_f32 v15, -v19, v11, v15
	v_fma_f32 v19, -v2, v26, 0
	v_fma_f32 v14, -v6, v14, v19
	v_fma_f32 v14, -v18, v10, v14
	v_fma_f32 v18, -v1, v25, 0
	v_fma_f32 v13, -v5, v13, v18
	v_fma_f32 v13, -v17, v9, v13
	s_waitcnt lgkmcnt(0)
	v_fma_f32 v17, -v0, v24, v30
	v_fma_f32 v12, -v4, v12, v17
	v_fma_f32 v12, -v8, v16, v12
	v_add_f32_e32 v12, v12, v13
	v_add_f32_e32 v13, v14, v15
	ds_read_b128 v[14:17], v65 offset:38144
	ds_read_b128 v[18:21], v65 offset:38160
	ds_read_b128 v[22:25], v65 offset:38176
	ds_read_b128 v[26:29], v65 offset:38192
	v_add_f32_e32 v12, v12, v13
	s_waitcnt lgkmcnt(3)
	v_fma_f32 v13, -v3, v17, 0
	v_fma_f32 v16, -v2, v16, 0
	v_fma_f32 v15, -v1, v15, 0
	v_fma_f32 v14, -v0, v14, v31
	s_waitcnt lgkmcnt(2)
	v_fma_f32 v13, -v7, v21, v13
	v_fma_f32 v16, -v6, v20, v16
	v_fma_f32 v15, -v5, v19, v15
	v_fma_f32 v14, -v4, v18, v14
	s_waitcnt lgkmcnt(1)
	v_fma_f32 v13, -v25, v11, v13
	v_fma_f32 v16, -v24, v10, v16
	v_fma_f32 v15, -v9, v23, v15
	v_fma_f32 v14, -v8, v22, v14
	s_waitcnt lgkmcnt(0)
	v_fmac_f32_e32 v13, 0x80000000, v29
	v_fmac_f32_e32 v16, 0x80000000, v28
	v_fmac_f32_e32 v15, 0x80000000, v27
	v_fma_f32 v14, -v26, v12, v14
	v_add_f32_e32 v30, v15, v14
	v_add_f32_e32 v13, v16, v13
	ds_read_b128 v[14:17], v65 offset:38400
	ds_read_b128 v[18:21], v65 offset:38416
	ds_read_b128 v[22:25], v65 offset:38432
	ds_read_b128 v[26:29], v65 offset:38448
	ds_read2st64_b32 v[32:33], v62 offset0:56 offset1:60
	s_waitcnt lgkmcnt(4)
	v_fma_f32 v17, -v3, v17, 0
	v_fma_f32 v16, -v2, v16, 0
	v_fma_f32 v15, -v1, v15, 0
	s_waitcnt lgkmcnt(3)
	v_fma_f32 v17, -v7, v21, v17
	s_waitcnt lgkmcnt(0)
	v_fma_f32 v14, -v0, v14, v32
	v_fma_f32 v16, -v6, v20, v16
	v_fma_f32 v15, -v5, v19, v15
	v_fma_f32 v14, -v4, v18, v14
	v_add_f32_e32 v13, v13, v30
	v_fma_f32 v17, -v25, v11, v17
	v_fma_f32 v16, -v10, v24, v16
	v_fma_f32 v15, -v9, v23, v15
	v_fma_f32 v14, -v8, v22, v14
	v_fmac_f32_e32 v17, 0x80000000, v29
	v_fmac_f32_e32 v16, 0x80000000, v28
	v_fma_f32 v15, -v27, v13, v15
	v_fma_f32 v14, -v26, v12, v14
	v_add_f32_e32 v14, v14, v15
	v_add_f32_e32 v15, v16, v17
	ds_read_b128 v[16:19], v65 offset:38656
	ds_read_b128 v[20:23], v65 offset:38672
	ds_read_b128 v[24:27], v65 offset:38688
	ds_read_b128 v[28:31], v65 offset:38704
	v_add_f32_e32 v14, v15, v14
	s_waitcnt lgkmcnt(3)
	v_fma_f32 v15, -v3, v19, 0
	v_fma_f32 v18, -v2, v18, 0
	v_fma_f32 v17, -v1, v17, 0
	v_fma_f32 v16, -v0, v16, v33
	s_waitcnt lgkmcnt(2)
	v_fma_f32 v15, -v7, v23, v15
	v_fma_f32 v18, -v6, v22, v18
	v_fma_f32 v17, -v5, v21, v17
	v_fma_f32 v16, -v4, v20, v16
	s_waitcnt lgkmcnt(1)
	v_fma_f32 v15, -v11, v27, v15
	v_fma_f32 v18, -v10, v26, v18
	v_fma_f32 v17, -v9, v25, v17
	v_fma_f32 v16, -v8, v24, v16
	s_waitcnt lgkmcnt(0)
	v_fmac_f32_e32 v15, 0x80000000, v31
	v_fma_f32 v18, -v30, v14, v18
	v_fma_f32 v17, -v29, v13, v17
	v_fma_f32 v16, -v12, v28, v16
	v_add_f32_e32 v32, v16, v17
	v_add_f32_e32 v15, v15, v18
	ds_read_b128 v[16:19], v65 offset:38912
	ds_read_b128 v[20:23], v65 offset:38928
	ds_read_b128 v[24:27], v65 offset:38944
	ds_read_b128 v[28:31], v65 offset:38960
	ds_read2st64_b32 v[42:43], v62 offset0:64 offset1:68
	s_waitcnt lgkmcnt(4)
	v_fma_f32 v19, -v3, v19, 0
	v_fma_f32 v18, -v2, v18, 0
	v_fma_f32 v17, -v1, v17, 0
	s_waitcnt lgkmcnt(3)
	v_fma_f32 v19, -v7, v23, v19
	s_waitcnt lgkmcnt(0)
	v_fma_f32 v16, -v0, v16, v42
	v_fma_f32 v18, -v6, v22, v18
	v_fma_f32 v17, -v5, v21, v17
	v_fma_f32 v16, -v4, v20, v16
	v_add_f32_e32 v15, v32, v15
	v_fma_f32 v19, -v11, v27, v19
	v_fma_f32 v18, -v10, v26, v18
	v_fma_f32 v17, -v9, v25, v17
	v_fma_f32 v16, -v8, v24, v16
	v_fma_f32 v19, -v31, v15, v19
	v_fma_f32 v18, -v30, v14, v18
	v_fma_f32 v17, -v13, v29, v17
	v_fma_f32 v16, -v12, v28, v16
	v_add_f32_e32 v16, v17, v16
	v_add_f32_e32 v17, v18, v19
	ds_read_b128 v[18:21], v65 offset:39168
	ds_read_b128 v[22:25], v65 offset:39184
	ds_read_b128 v[26:29], v65 offset:39200
	ds_read_b128 v[30:33], v65 offset:39216
	ds_read_b128 v[34:37], v65 offset:39232
	ds_read_b128 v[38:41], v65 offset:39424
	v_add_f32_e32 v16, v16, v17
	s_waitcnt lgkmcnt(5)
	v_fma_f32 v17, -v3, v21, 0
	v_fma_f32 v20, -v2, v20, 0
	v_fma_f32 v19, -v1, v19, 0
	v_fma_f32 v18, -v0, v18, v43
	s_waitcnt lgkmcnt(4)
	v_fma_f32 v17, -v7, v25, v17
	v_fma_f32 v20, -v6, v24, v20
	v_fma_f32 v19, -v5, v23, v19
	v_fma_f32 v18, -v4, v22, v18
	s_waitcnt lgkmcnt(3)
	v_fma_f32 v17, -v11, v29, v17
	v_fma_f32 v20, -v10, v28, v20
	v_fma_f32 v19, -v9, v27, v19
	v_fma_f32 v18, -v8, v26, v18
	s_waitcnt lgkmcnt(2)
	v_fma_f32 v17, -v33, v15, v17
	v_fma_f32 v20, -v14, v32, v20
	v_fma_f32 v19, -v13, v31, v19
	v_fma_f32 v18, -v12, v30, v18
	s_waitcnt lgkmcnt(1)
	v_fmac_f32_e32 v17, 0x80000000, v37
	v_fmac_f32_e32 v20, 0x80000000, v36
	v_fmac_f32_e32 v19, 0x80000000, v35
	v_fma_f32 v18, -v34, v16, v18
	v_add_f32_e32 v18, v19, v18
	v_add_f32_e32 v17, v20, v17
	v_add_f32_e32 v17, v17, v18
	ds_read_b128 v[18:21], v65 offset:39440
	ds_read_b128 v[22:25], v65 offset:39456
	ds_read_b128 v[26:29], v65 offset:39472
	ds_read_b128 v[30:33], v65 offset:39488
	s_waitcnt lgkmcnt(4)
	v_fma_f32 v34, -v3, v41, 0
	s_waitcnt lgkmcnt(3)
	v_fma_f32 v21, -v7, v21, v34
	ds_read2st64_b32 v[44:45], v62 offset0:72 offset1:76
	s_waitcnt lgkmcnt(3)
	v_fma_f32 v21, -v11, v25, v21
	v_fma_f32 v25, -v2, v40, 0
	v_fma_f32 v20, -v6, v20, v25
	v_fma_f32 v20, -v10, v24, v20
	v_fma_f32 v24, -v1, v39, 0
	v_fma_f32 v19, -v5, v19, v24
	v_fma_f32 v19, -v9, v23, v19
	s_waitcnt lgkmcnt(0)
; #define LAS __attribute__((address_space(3)))
; __device__ __forceinline__ void phase_chunk_prep(const Params& p, LAS unsigned char* lds, int wave_s) {
;     ...
;             for (int i = 0; i < 64; ++i) {
;                 float s0 = RHS[i * 256 + col], s1 = 0.f, s2 = 0.f, s3 = 0.f;
; #pragma unroll
;                 for (int j4 = 0; j4 < (i + 3) / 4; ++j4) { const f32x4 a = *(const LAS f32x4*)(AM + i * 64 + 4 * j4);
;                     s0 -= a.x * sol[4 * j4]; s1 -= a.y * sol[4 * j4 + 1]; s2 -= a.z * sol[4 * j4 + 2]; s3 -= a.w * sol[4 * j4 + 3]; }
;                 sol[i] = (s0 + s1) + (s2 + s3);
	v_fma_f32 v23, -v0, v38, v44
	v_fma_f32 v18, -v4, v18, v23
	v_fma_f32 v18, -v8, v22, v18
	v_fma_f32 v21, -v15, v29, v21
	v_fma_f32 v20, -v14, v28, v20
	v_fma_f32 v19, -v13, v27, v19
	v_fma_f32 v18, -v12, v26, v18
	v_fmac_f32_e32 v21, 0x80000000, v33
	v_fmac_f32_e32 v20, 0x80000000, v32
	v_fma_f32 v19, -v31, v17, v19
	v_fma_f32 v18, -v16, v30, v18
	v_add_f32_e32 v18, v19, v18
	v_add_f32_e32 v19, v20, v21
	ds_read_b128 v[20:23], v65 offset:39680
	ds_read_b128 v[24:27], v65 offset:39696
	ds_read_b128 v[28:31], v65 offset:39712
	ds_read_b128 v[32:35], v65 offset:39728
	ds_read_b128 v[36:39], v65 offset:39744
	ds_read_b128 v[40:43], v65 offset:39936
	v_add_f32_e32 v18, v19, v18
	s_waitcnt lgkmcnt(5)
	v_fma_f32 v19, -v3, v23, 0
	v_fma_f32 v22, -v2, v22, 0
	v_fma_f32 v21, -v1, v21, 0
	v_fma_f32 v20, -v0, v20, v45
	s_waitcnt lgkmcnt(4)
	v_fma_f32 v19, -v7, v27, v19
	v_fma_f32 v22, -v6, v26, v22
	v_fma_f32 v21, -v5, v25, v21
	v_fma_f32 v20, -v4, v24, v20
	s_waitcnt lgkmcnt(3)
	v_fma_f32 v19, -v11, v31, v19
	v_fma_f32 v22, -v10, v30, v22
	v_fma_f32 v21, -v9, v29, v21
	v_fma_f32 v20, -v8, v28, v20
	s_waitcnt lgkmcnt(2)
	v_fma_f32 v19, -v15, v35, v19
	v_fma_f32 v22, -v14, v34, v22
	v_fma_f32 v21, -v13, v33, v21
	v_fma_f32 v20, -v12, v32, v20
	s_waitcnt lgkmcnt(1)
	v_fmac_f32_e32 v19, 0x80000000, v39
	v_fma_f32 v22, -v38, v18, v22
	v_fma_f32 v21, -v17, v37, v21
	v_fma_f32 v20, -v16, v36, v20
	v_add_f32_e32 v20, v21, v20
	v_add_f32_e32 v19, v19, v22
	v_add_f32_e32 v19, v19, v20
	ds_read_b128 v[20:23], v65 offset:39952
	ds_read_b128 v[24:27], v65 offset:39968
	ds_read_b128 v[28:31], v65 offset:39984
	ds_read_b128 v[32:35], v65 offset:40000
	s_waitcnt lgkmcnt(4)
	v_fma_f32 v36, -v3, v43, 0
	s_waitcnt lgkmcnt(3)
	v_fma_f32 v23, -v7, v23, v36
	s_waitcnt lgkmcnt(2)
	v_fma_f32 v23, -v11, v27, v23
	s_waitcnt lgkmcnt(1)
	v_fma_f32 v23, -v15, v31, v23
	s_waitcnt lgkmcnt(0)
	v_fma_f32 v27, -v35, v19, v23
	v_fma_f32 v23, -v2, v42, 0
	ds_read2st64_b32 v[46:47], v62 offset0:80 offset1:84
	v_fma_f32 v22, -v6, v22, v23
	v_fma_f32 v22, -v10, v26, v22
	v_fma_f32 v22, -v14, v30, v22
	v_fma_f32 v26, -v18, v34, v22
	v_fma_f32 v22, -v1, v41, 0
	v_fma_f32 v21, -v5, v21, v22
	s_waitcnt lgkmcnt(0)
	v_fma_f32 v22, -v0, v40, v46
	v_fma_f32 v20, -v4, v20, v22
	v_fma_f32 v21, -v9, v25, v21
	v_fma_f32 v20, -v8, v24, v20
	v_fma_f32 v21, -v13, v29, v21
	v_fma_f32 v20, -v12, v28, v20
	v_fma_f32 v21, -v17, v33, v21
	v_fma_f32 v20, -v16, v32, v20
	ds_read_b128 v[22:25], v65 offset:40192
	v_add_f32_e32 v20, v21, v20
	v_add_f32_e32 v21, v26, v27
	ds_read_b128 v[26:29], v65 offset:40208
	v_add_f32_e32 v20, v21, v20
	s_waitcnt lgkmcnt(1)
	v_fma_f32 v21, -v3, v25, 0
	ds_read_b128 v[30:33], v65 offset:40224
	ds_read_b128 v[34:37], v65 offset:40240
	ds_read_b128 v[38:41], v65 offset:40256
	ds_read_b128 v[42:45], v65 offset:40272
	v_fma_f32 v24, -v2, v24, 0
	v_fma_f32 v23, -v1, v23, 0
	v_fma_f32 v22, -v0, v22, v47
	s_waitcnt lgkmcnt(4)
	v_fma_f32 v21, -v7, v29, v21
	v_fma_f32 v24, -v6, v28, v24
	v_fma_f32 v23, -v5, v27, v23
	v_fma_f32 v22, -v4, v26, v22
	s_waitcnt lgkmcnt(3)
	v_fma_f32 v21, -v11, v33, v21
	v_fma_f32 v24, -v10, v32, v24
	v_fma_f32 v23, -v9, v31, v23
	v_fma_f32 v22, -v8, v30, v22
	s_waitcnt lgkmcnt(2)
	v_fma_f32 v21, -v15, v37, v21
	v_fma_f32 v24, -v14, v36, v24
	v_fma_f32 v23, -v13, v35, v23
	v_fma_f32 v22, -v12, v34, v22
	s_waitcnt lgkmcnt(1)
	v_fma_f32 v21, -v19, v41, v21
	v_fma_f32 v28, -v18, v40, v24
	v_fma_f32 v27, -v17, v39, v23
	v_fma_f32 v22, -v16, v38, v22
	s_waitcnt lgkmcnt(0)
	v_fmac_f32_e32 v21, 0x80000000, v45
	v_fmac_f32_e32 v28, 0x80000000, v44
	v_fmac_f32_e32 v27, 0x80000000, v43
	v_fma_f32 v26, -v42, v20, v22
	v_add_f32_e32 v26, v27, v26
	v_add_f32_e32 v21, v28, v21
	ds_read_b128 v[22:25], v65 offset:40448
	v_add_f32_e32 v21, v21, v26
	ds_read_b128 v[26:29], v65 offset:40464
	ds_read_b128 v[30:33], v65 offset:40480
	ds_read_b128 v[34:37], v65 offset:40496
	ds_read_b128 v[38:41], v65 offset:40512
	ds_read_b128 v[42:45], v65 offset:40528
	ds_read2st64_b32 v[48:49], v62 offset0:88 offset1:92
	s_waitcnt lgkmcnt(6)
	v_fma_f32 v25, -v3, v25, 0
	v_fma_f32 v24, -v2, v24, 0
	v_fma_f32 v23, -v1, v23, 0
	s_waitcnt lgkmcnt(5)
	v_fma_f32 v25, -v7, v29, v25
	s_waitcnt lgkmcnt(0)
	v_fma_f32 v22, -v0, v22, v48
	v_fma_f32 v24, -v6, v28, v24
	v_fma_f32 v23, -v5, v27, v23
	v_fma_f32 v22, -v4, v26, v22
	v_fma_f32 v25, -v11, v33, v25
	v_fma_f32 v24, -v10, v32, v24
	v_fma_f32 v23, -v9, v31, v23
	v_fma_f32 v22, -v8, v30, v22
	v_fma_f32 v25, -v15, v37, v25
	v_fma_f32 v24, -v14, v36, v24
	v_fma_f32 v23, -v13, v35, v23
	v_fma_f32 v22, -v12, v34, v22
	v_fma_f32 v29, -v19, v41, v25
	v_fma_f32 v28, -v18, v40, v24
	v_fma_f32 v23, -v17, v39, v23
	v_fma_f32 v22, -v16, v38, v22
	v_fmac_f32_e32 v29, 0x80000000, v45
	v_fmac_f32_e32 v28, 0x80000000, v44
	v_fma_f32 v23, -v43, v21, v23
	v_fma_f32 v22, -v20, v42, v22
	ds_read_b128 v[24:27], v65 offset:40704
	v_add_f32_e32 v22, v23, v22
	v_add_f32_e32 v23, v28, v29
	ds_read_b128 v[28:31], v65 offset:40720
	v_add_f32_e32 v22, v23, v22
	s_waitcnt lgkmcnt(1)
	v_fma_f32 v23, -v3, v27, 0
	ds_read_b128 v[32:35], v65 offset:40736
	ds_read_b128 v[36:39], v65 offset:40752
	ds_read_b128 v[40:43], v65 offset:40768
	ds_read_b128 v[44:47], v65 offset:40784
	v_fma_f32 v26, -v2, v26, 0
	v_fma_f32 v25, -v1, v25, 0
	v_fma_f32 v24, -v0, v24, v49
	s_waitcnt lgkmcnt(4)
	v_fma_f32 v23, -v7, v31, v23
	v_fma_f32 v26, -v6, v30, v26
	v_fma_f32 v25, -v5, v29, v25
	v_fma_f32 v24, -v4, v28, v24
	s_waitcnt lgkmcnt(3)
	v_fma_f32 v23, -v11, v35, v23
	v_fma_f32 v26, -v10, v34, v26
	v_fma_f32 v25, -v9, v33, v25
	v_fma_f32 v24, -v8, v32, v24
	s_waitcnt lgkmcnt(2)
; #define LAS __attribute__((address_space(3)))
; __device__ __forceinline__ void phase_chunk_prep(const Params& p, LAS unsigned char* lds, int wave_s) {
;     ...
;             for (int i = 0; i < 64; ++i) {
;                 float s0 = RHS[i * 256 + col], s1 = 0.f, s2 = 0.f, s3 = 0.f;
; #pragma unroll
;                 for (int j4 = 0; j4 < (i + 3) / 4; ++j4) { const f32x4 a = *(const LAS f32x4*)(AM + i * 64 + 4 * j4);
;                     s0 -= a.x * sol[4 * j4]; s1 -= a.y * sol[4 * j4 + 1]; s2 -= a.z * sol[4 * j4 + 2]; s3 -= a.w * sol[4 * j4 + 3]; }
;                 sol[i] = (s0 + s1) + (s2 + s3);
	v_fma_f32 v23, -v15, v39, v23
	v_fma_f32 v26, -v14, v38, v26
	v_fma_f32 v25, -v13, v37, v25
	v_fma_f32 v24, -v12, v36, v24
	s_waitcnt lgkmcnt(1)
	v_fma_f32 v23, -v19, v43, v23
	v_fma_f32 v26, -v18, v42, v26
	v_fma_f32 v25, -v17, v41, v25
	v_fma_f32 v24, -v16, v40, v24
	s_waitcnt lgkmcnt(0)
	v_fmac_f32_e32 v23, 0x80000000, v47
	v_fma_f32 v30, -v46, v22, v26
	v_fma_f32 v29, -v21, v45, v25
	v_fma_f32 v28, -v20, v44, v24
	ds_read_b128 v[24:27], v65 offset:40960
	v_add_f32_e32 v28, v29, v28
	v_add_f32_e32 v23, v23, v30
	v_add_f32_e32 v23, v23, v28
	ds_read_b128 v[28:31], v65 offset:40976
	ds_read_b128 v[32:35], v65 offset:40992
	ds_read_b128 v[36:39], v65 offset:41008
	ds_read_b128 v[40:43], v65 offset:41024
	ds_read_b128 v[44:47], v65 offset:41040
	ds_read2st64_b32 v[58:59], v62 offset0:96 offset1:100
	s_waitcnt lgkmcnt(6)
	v_fma_f32 v27, -v3, v27, 0
	v_fma_f32 v26, -v2, v26, 0
	s_waitcnt lgkmcnt(5)
	v_fma_f32 v27, -v7, v31, v27
	v_fma_f32 v26, -v6, v30, v26
	v_fma_f32 v25, -v1, v25, 0
	s_waitcnt lgkmcnt(0)
	v_fma_f32 v24, -v0, v24, v58
	v_fma_f32 v27, -v11, v35, v27
	v_fma_f32 v26, -v10, v34, v26
	v_fma_f32 v25, -v5, v29, v25
	v_fma_f32 v24, -v4, v28, v24
	v_fma_f32 v27, -v15, v39, v27
	v_fma_f32 v26, -v14, v38, v26
	v_fma_f32 v25, -v9, v33, v25
	v_fma_f32 v24, -v8, v32, v24
	v_fma_f32 v27, -v19, v43, v27
	v_fma_f32 v26, -v18, v42, v26
	v_fma_f32 v25, -v13, v37, v25
	v_fma_f32 v24, -v12, v36, v24
	v_fma_f32 v35, -v47, v23, v27
	v_fma_f32 v34, -v22, v46, v26
	v_fma_f32 v25, -v17, v41, v25
	v_fma_f32 v24, -v16, v40, v24
	ds_read_b128 v[26:29], v65 offset:41216
	ds_read_b128 v[30:33], v65 offset:41232
	v_fma_f32 v25, -v21, v45, v25
	v_fma_f32 v24, -v20, v44, v24
	v_add_f32_e32 v24, v25, v24
	v_add_f32_e32 v25, v34, v35
	ds_read_b128 v[34:37], v65 offset:41248
	v_add_f32_e32 v24, v25, v24
	s_waitcnt lgkmcnt(2)
	v_fma_f32 v25, -v3, v29, 0
	ds_read_b128 v[38:41], v65 offset:41264
	ds_read_b128 v[42:45], v65 offset:41280
	ds_read_b128 v[46:49], v65 offset:41296
	v_fma_f32 v28, -v2, v28, 0
	v_fma_f32 v27, -v1, v27, 0
	v_fma_f32 v26, -v0, v26, v59
	s_waitcnt lgkmcnt(4)
	v_fma_f32 v25, -v7, v33, v25
	ds_read_b128 v[50:53], v65 offset:41312
	ds_read_b128 v[54:57], v65 offset:41472
	v_fma_f32 v28, -v6, v32, v28
	v_fma_f32 v27, -v5, v31, v27
	v_fma_f32 v26, -v4, v30, v26
	s_waitcnt lgkmcnt(5)
	v_fma_f32 v25, -v11, v37, v25
	v_fma_f32 v28, -v10, v36, v28
	v_fma_f32 v27, -v9, v35, v27
	v_fma_f32 v26, -v8, v34, v26
	s_waitcnt lgkmcnt(4)
	v_fma_f32 v25, -v15, v41, v25
	v_fma_f32 v28, -v14, v40, v28
	v_fma_f32 v27, -v13, v39, v27
	v_fma_f32 v26, -v12, v38, v26
	s_waitcnt lgkmcnt(3)
	v_fma_f32 v25, -v19, v45, v25
	v_fma_f32 v28, -v18, v44, v28
	v_fma_f32 v27, -v17, v43, v27
	v_fma_f32 v26, -v16, v42, v26
	s_waitcnt lgkmcnt(2)
	v_fma_f32 v25, -v23, v49, v25
	v_fma_f32 v32, -v22, v48, v28
	v_fma_f32 v27, -v21, v47, v27
	v_fma_f32 v26, -v20, v46, v26
	s_waitcnt lgkmcnt(1)
	v_fmac_f32_e32 v25, 0x80000000, v53
	v_fmac_f32_e32 v32, 0x80000000, v52
	v_fmac_f32_e32 v27, 0x80000000, v51
	v_fma_f32 v26, -v50, v24, v26
	v_add_f32_e32 v30, v27, v26
	ds_read_b128 v[26:29], v65 offset:41488
	v_add_f32_e32 v25, v32, v25
	v_add_f32_e32 v25, v25, v30
	ds_read_b128 v[30:33], v65 offset:41504
	s_waitcnt lgkmcnt(2)
	v_fma_f32 v34, -v3, v57, 0
	s_waitcnt lgkmcnt(1)
	v_fma_f32 v29, -v7, v29, v34
	ds_read_b128 v[34:37], v65 offset:41520
	ds_read_b128 v[38:41], v65 offset:41536
	ds_read_b128 v[42:45], v65 offset:41552
	ds_read_b128 v[46:49], v65 offset:41568
	ds_read2st64_b32 v[60:61], v62 offset0:104 offset1:108
	s_waitcnt lgkmcnt(5)
	v_fma_f32 v29, -v11, v33, v29
	s_waitcnt lgkmcnt(4)
	v_fma_f32 v29, -v15, v37, v29
	s_waitcnt lgkmcnt(3)
	v_fma_f32 v29, -v19, v41, v29
	s_waitcnt lgkmcnt(2)
	v_fma_f32 v37, -v23, v45, v29
	v_fma_f32 v29, -v2, v56, 0
	v_fma_f32 v28, -v6, v28, v29
	v_fma_f32 v28, -v10, v32, v28
	v_fma_f32 v28, -v14, v36, v28
	v_fma_f32 v28, -v18, v40, v28
	v_fma_f32 v36, -v22, v44, v28
	v_fma_f32 v28, -v1, v55, 0
	v_fma_f32 v27, -v5, v27, v28
	s_waitcnt lgkmcnt(0)
	v_fma_f32 v28, -v0, v54, v60
	v_fma_f32 v26, -v4, v26, v28
	v_fma_f32 v27, -v9, v31, v27
	v_fma_f32 v26, -v8, v30, v26
	v_fma_f32 v27, -v13, v35, v27
	v_fma_f32 v26, -v12, v34, v26
	v_fma_f32 v27, -v17, v39, v27
	v_fma_f32 v26, -v16, v38, v26
	v_fma_f32 v27, -v21, v43, v27
	v_fma_f32 v26, -v20, v42, v26
	ds_read_b128 v[28:31], v65 offset:41728
	ds_read_b128 v[32:35], v65 offset:41744
	v_fmac_f32_e32 v37, 0x80000000, v49
	v_fmac_f32_e32 v36, 0x80000000, v48
	v_fma_f32 v27, -v47, v25, v27
	v_fma_f32 v26, -v24, v46, v26
	v_add_f32_e32 v26, v27, v26
	v_add_f32_e32 v27, v36, v37
	ds_read_b128 v[36:39], v65 offset:41760
	v_add_f32_e32 v26, v27, v26
	s_waitcnt lgkmcnt(2)
	v_fma_f32 v27, -v3, v31, 0
	ds_read_b128 v[40:43], v65 offset:41776
	ds_read_b128 v[44:47], v65 offset:41792
	ds_read_b128 v[48:51], v65 offset:41808
	v_fma_f32 v30, -v2, v30, 0
	v_fma_f32 v29, -v1, v29, 0
	v_fma_f32 v28, -v0, v28, v61
	s_waitcnt lgkmcnt(4)
	v_fma_f32 v27, -v7, v35, v27
	ds_read_b128 v[52:55], v65 offset:41824
	ds_read_b128 v[56:59], v65 offset:41984
	v_fma_f32 v30, -v6, v34, v30
	v_fma_f32 v29, -v5, v33, v29
	v_fma_f32 v28, -v4, v32, v28
	s_waitcnt lgkmcnt(5)
	v_fma_f32 v27, -v11, v39, v27
	v_fma_f32 v30, -v10, v38, v30
	v_fma_f32 v29, -v9, v37, v29
	v_fma_f32 v28, -v8, v36, v28
	s_waitcnt lgkmcnt(4)
	v_fma_f32 v27, -v15, v43, v27
	v_fma_f32 v30, -v14, v42, v30
	v_fma_f32 v29, -v13, v41, v29
	v_fma_f32 v28, -v12, v40, v28
	s_waitcnt lgkmcnt(3)
	v_fma_f32 v27, -v19, v47, v27
	v_fma_f32 v30, -v18, v46, v30
	v_fma_f32 v29, -v17, v45, v29
	v_fma_f32 v28, -v16, v44, v28
	s_waitcnt lgkmcnt(2)
; #define LAS __attribute__((address_space(3)))
; __device__ __forceinline__ void phase_chunk_prep(const Params& p, LAS unsigned char* lds, int wave_s) {
;     ...
;             for (int i = 0; i < 64; ++i) {
;                 float s0 = RHS[i * 256 + col], s1 = 0.f, s2 = 0.f, s3 = 0.f;
; #pragma unroll
;                 for (int j4 = 0; j4 < (i + 3) / 4; ++j4) { const f32x4 a = *(const LAS f32x4*)(AM + i * 64 + 4 * j4);
;                     s0 -= a.x * sol[4 * j4]; s1 -= a.y * sol[4 * j4 + 1]; s2 -= a.z * sol[4 * j4 + 2]; s3 -= a.w * sol[4 * j4 + 3]; }
;                 sol[i] = (s0 + s1) + (s2 + s3);
	v_fma_f32 v27, -v23, v51, v27
	v_fma_f32 v30, -v22, v50, v30
	v_fma_f32 v29, -v21, v49, v29
	v_fma_f32 v28, -v20, v48, v28
	s_waitcnt lgkmcnt(1)
	v_fmac_f32_e32 v27, 0x80000000, v55
	v_fma_f32 v34, -v54, v26, v30
	v_fma_f32 v29, -v25, v53, v29
	v_fma_f32 v28, -v24, v52, v28
	v_add_f32_e32 v32, v29, v28
	ds_read_b128 v[28:31], v65 offset:42000
	v_add_f32_e32 v27, v27, v34
	v_add_f32_e32 v27, v27, v32
	ds_read_b128 v[32:35], v65 offset:42016
	s_waitcnt lgkmcnt(2)
	v_fma_f32 v36, -v3, v59, 0
	s_waitcnt lgkmcnt(1)
	v_fma_f32 v31, -v7, v31, v36
	ds_read_b128 v[36:39], v65 offset:42032
	ds_read_b128 v[40:43], v65 offset:42048
	ds_read_b128 v[44:47], v65 offset:42064
	ds_read_b128 v[48:51], v65 offset:42080
	ds_read2st64_b32 v[68:69], v62 offset0:112 offset1:116
	s_waitcnt lgkmcnt(5)
	v_fma_f32 v31, -v11, v35, v31
	s_waitcnt lgkmcnt(4)
	v_fma_f32 v31, -v15, v39, v31
	s_waitcnt lgkmcnt(3)
	v_fma_f32 v31, -v19, v43, v31
	s_waitcnt lgkmcnt(2)
	v_fma_f32 v31, -v23, v47, v31
	s_waitcnt lgkmcnt(1)
	v_fma_f32 v39, -v51, v27, v31
	v_fma_f32 v31, -v2, v58, 0
	v_fma_f32 v30, -v6, v30, v31
	v_fma_f32 v30, -v10, v34, v30
	v_fma_f32 v30, -v14, v38, v30
	v_fma_f32 v30, -v18, v42, v30
	v_fma_f32 v30, -v22, v46, v30
	v_fma_f32 v38, -v26, v50, v30
	v_fma_f32 v30, -v1, v57, 0
	v_fma_f32 v29, -v5, v29, v30
	s_waitcnt lgkmcnt(0)
	v_fma_f32 v30, -v0, v56, v68
	v_fma_f32 v28, -v4, v28, v30
	v_fma_f32 v29, -v9, v33, v29
	v_fma_f32 v28, -v8, v32, v28
	v_fma_f32 v29, -v13, v37, v29
	v_fma_f32 v28, -v12, v36, v28
	v_fma_f32 v29, -v17, v41, v29
	v_fma_f32 v28, -v16, v40, v28
	v_fma_f32 v29, -v21, v45, v29
	v_fma_f32 v28, -v20, v44, v28
	v_fma_f32 v29, -v25, v49, v29
	v_fma_f32 v28, -v24, v48, v28
	ds_read_b128 v[30:33], v65 offset:42240
	ds_read_b128 v[34:37], v65 offset:42256
	v_add_f32_e32 v28, v29, v28
	v_add_f32_e32 v29, v38, v39
	ds_read_b128 v[38:41], v65 offset:42272
	ds_read_b128 v[42:45], v65 offset:42288
	s_waitcnt lgkmcnt(3)
	v_fma_f32 v31, -v1, v31, 0
	v_fma_f32 v30, -v0, v30, v69
	v_add_f32_e32 v28, v29, v28
	v_fma_f32 v29, -v3, v33, 0
	v_fma_f32 v32, -v2, v32, 0
	s_waitcnt lgkmcnt(2)
	v_fma_f32 v31, -v5, v35, v31
	v_fma_f32 v30, -v4, v34, v30
	v_fma_f32 v29, -v7, v37, v29
	ds_read_b128 v[46:49], v65 offset:42304
	ds_read_b128 v[50:53], v65 offset:42320
	ds_read_b128 v[54:57], v65 offset:42336
	ds_read_b128 v[58:61], v65 offset:42352
	v_fma_f32 v32, -v6, v36, v32
	s_waitcnt lgkmcnt(5)
	v_fma_f32 v31, -v9, v39, v31
	v_fma_f32 v30, -v8, v38, v30
	v_fma_f32 v29, -v11, v41, v29
	v_fma_f32 v32, -v10, v40, v32
	s_waitcnt lgkmcnt(4)
	v_fma_f32 v31, -v13, v43, v31
	v_fma_f32 v30, -v12, v42, v30
	v_fma_f32 v29, -v15, v45, v29
	v_fma_f32 v32, -v14, v44, v32
	s_waitcnt lgkmcnt(3)
	v_fma_f32 v31, -v17, v47, v31
	v_fma_f32 v30, -v16, v46, v30
	v_fma_f32 v29, -v19, v49, v29
	v_fma_f32 v32, -v18, v48, v32
	s_waitcnt lgkmcnt(2)
	v_fma_f32 v31, -v21, v51, v31
	v_fma_f32 v30, -v20, v50, v30
	v_fma_f32 v29, -v23, v53, v29
	v_fma_f32 v32, -v22, v52, v32
	s_waitcnt lgkmcnt(1)
	v_fma_f32 v31, -v25, v55, v31
	v_fma_f32 v30, -v24, v54, v30
	v_fma_f32 v29, -v27, v57, v29
	v_fma_f32 v40, -v26, v56, v32
	s_waitcnt lgkmcnt(0)
	v_fmac_f32_e32 v31, 0x80000000, v59
	v_fma_f32 v30, -v58, v28, v30
	v_fmac_f32_e32 v29, 0x80000000, v61
	v_fmac_f32_e32 v40, 0x80000000, v60
	v_add_f32_e32 v42, v31, v30
	ds_read_b128 v[30:33], v65 offset:42496
	ds_read_b128 v[34:37], v65 offset:42512
	v_add_f32_e32 v29, v40, v29
	ds_read_b128 v[38:41], v65 offset:42528
	v_add_f32_e32 v29, v29, v42
	ds_read_b128 v[42:45], v65 offset:42544
	s_waitcnt lgkmcnt(3)
	v_fma_f32 v33, -v3, v33, 0
	v_fma_f32 v32, -v2, v32, 0
	s_waitcnt lgkmcnt(2)
	v_fma_f32 v33, -v7, v37, v33
	v_fma_f32 v32, -v6, v36, v32
	s_waitcnt lgkmcnt(1)
	v_fma_f32 v33, -v11, v41, v33
	ds_read_b128 v[46:49], v65 offset:42560
	ds_read_b128 v[50:53], v65 offset:42576
	ds_read_b128 v[54:57], v65 offset:42592
	ds_read_b128 v[58:61], v65 offset:42608
	v_fma_f32 v32, -v10, v40, v32
	s_waitcnt lgkmcnt(4)
	v_fma_f32 v33, -v15, v45, v33
	v_fma_f32 v32, -v14, v44, v32
	s_waitcnt lgkmcnt(3)
	v_fma_f32 v33, -v19, v49, v33
	v_fma_f32 v32, -v18, v48, v32
	s_waitcnt lgkmcnt(2)
	v_fma_f32 v33, -v23, v53, v33
	v_fma_f32 v32, -v22, v52, v32
	s_waitcnt lgkmcnt(1)
	v_fma_f32 v41, -v27, v57, v33
	v_fma_f32 v40, -v26, v56, v32
	s_waitcnt lgkmcnt(0)
	v_fmac_f32_e32 v41, 0x80000000, v61
	v_fmac_f32_e32 v40, 0x80000000, v60
	ds_read2st64_b32 v[60:61], v62 offset0:120 offset1:124
	v_fma_f32 v31, -v1, v31, 0
	v_fma_f32 v31, -v5, v35, v31
	v_fma_f32 v31, -v9, v39, v31
	v_fma_f32 v31, -v13, v43, v31
	s_waitcnt lgkmcnt(0)
	v_fma_f32 v30, -v0, v30, v60
	v_fma_f32 v30, -v4, v34, v30
	v_fma_f32 v30, -v8, v38, v30
	v_fma_f32 v30, -v12, v42, v30
	v_fma_f32 v31, -v17, v47, v31
	v_fma_f32 v30, -v16, v46, v30
	v_fma_f32 v31, -v21, v51, v31
	v_fma_f32 v30, -v20, v50, v30
	v_fma_f32 v31, -v25, v55, v31
	v_fma_f32 v30, -v24, v54, v30
	v_fma_f32 v31, -v59, v29, v31
	v_fma_f32 v30, -v28, v58, v30
	ds_read_b128 v[32:35], v65 offset:42752
	ds_read_b128 v[36:39], v65 offset:42768
	v_add_f32_e32 v30, v31, v30
	v_add_f32_e32 v31, v40, v41
	ds_read_b128 v[40:43], v65 offset:42784
	ds_read_b128 v[44:47], v65 offset:42800
	v_add_f32_e32 v30, v31, v30
	s_waitcnt lgkmcnt(3)
	v_fma_f32 v31, -v3, v35, 0
	v_fma_f32 v34, -v2, v34, 0
	v_fma_f32 v33, -v1, v33, 0
	v_fma_f32 v32, -v0, v32, v61
	s_waitcnt lgkmcnt(2)
	v_fma_f32 v31, -v7, v39, v31
	v_fma_f32 v34, -v6, v38, v34
	v_fma_f32 v33, -v5, v37, v33
	v_fma_f32 v32, -v4, v36, v32
	s_waitcnt lgkmcnt(1)
; #define LAS __attribute__((address_space(3)))
; __device__ __forceinline__ void phase_chunk_prep(const Params& p, LAS unsigned char* lds, int wave_s) {
;     ...
;             for (int i = 0; i < 64; ++i) {
;                 float s0 = RHS[i * 256 + col], s1 = 0.f, s2 = 0.f, s3 = 0.f;
; #pragma unroll
;                 for (int j4 = 0; j4 < (i + 3) / 4; ++j4) { const f32x4 a = *(const LAS f32x4*)(AM + i * 64 + 4 * j4);
;                     s0 -= a.x * sol[4 * j4]; s1 -= a.y * sol[4 * j4 + 1]; s2 -= a.z * sol[4 * j4 + 2]; s3 -= a.w * sol[4 * j4 + 3]; }
;                 sol[i] = (s0 + s1) + (s2 + s3);
	v_fma_f32 v31, -v11, v43, v31
	ds_read_b128 v[48:51], v65 offset:42816
	ds_read_b128 v[52:55], v65 offset:42832
	ds_read_b128 v[56:59], v65 offset:42848
	ds_read_b128 v[68:71], v65 offset:42864
	v_fma_f32 v34, -v10, v42, v34
	v_fma_f32 v33, -v9, v41, v33
	v_fma_f32 v32, -v8, v40, v32
	s_waitcnt lgkmcnt(4)
	v_fma_f32 v31, -v15, v47, v31
	v_fma_f32 v34, -v14, v46, v34
	v_fma_f32 v33, -v13, v45, v33
	v_fma_f32 v32, -v12, v44, v32
	s_waitcnt lgkmcnt(3)
	v_fma_f32 v31, -v19, v51, v31
	v_fma_f32 v34, -v18, v50, v34
	v_fma_f32 v33, -v17, v49, v33
	v_fma_f32 v32, -v16, v48, v32
	s_waitcnt lgkmcnt(2)
	v_fma_f32 v31, -v23, v55, v31
	v_fma_f32 v34, -v22, v54, v34
	v_fma_f32 v33, -v21, v53, v33
	v_fma_f32 v32, -v20, v52, v32
	s_waitcnt lgkmcnt(1)
	v_fma_f32 v31, -v27, v59, v31
	v_fma_f32 v34, -v26, v58, v34
	v_fma_f32 v33, -v25, v57, v33
	v_fma_f32 v32, -v24, v56, v32
	s_waitcnt lgkmcnt(0)
	v_fmac_f32_e32 v31, 0x80000000, v71
	v_fma_f32 v42, -v70, v30, v34
	v_fma_f32 v33, -v29, v69, v33
	v_fma_f32 v32, -v28, v68, v32
	v_add_f32_e32 v44, v33, v32
	v_add_f32_e32 v31, v31, v42
	ds_read_b128 v[32:35], v65 offset:43008
	ds_read_b128 v[36:39], v65 offset:43024
	ds_read_b128 v[40:43], v65 offset:43040
	v_add_f32_e32 v31, v31, v44
	ds_read_b128 v[44:47], v65 offset:43056
	ds_read_b128 v[48:51], v65 offset:43072
	ds_read_b128 v[52:55], v65 offset:43088
	ds_read_b128 v[56:59], v65 offset:43104
	ds_read_b128 v[68:71], v65 offset:43120
	ds_read2st64_b32 v[80:81], v62 offset0:128 offset1:132
	s_waitcnt lgkmcnt(8)
	v_fma_f32 v35, -v3, v35, 0
	v_fma_f32 v34, -v2, v34, 0
	v_fma_f32 v33, -v1, v33, 0
	s_waitcnt lgkmcnt(7)
	v_fma_f32 v35, -v7, v39, v35
	s_waitcnt lgkmcnt(0)
	v_fma_f32 v32, -v0, v32, v80
	v_fma_f32 v34, -v6, v38, v34
	v_fma_f32 v33, -v5, v37, v33
	v_fma_f32 v32, -v4, v36, v32
	v_fma_f32 v35, -v11, v43, v35
	v_fma_f32 v34, -v10, v42, v34
	v_fma_f32 v33, -v9, v41, v33
	v_fma_f32 v32, -v8, v40, v32
	v_fma_f32 v35, -v15, v47, v35
	v_fma_f32 v34, -v14, v46, v34
	v_fma_f32 v33, -v13, v45, v33
	v_fma_f32 v32, -v12, v44, v32
	v_fma_f32 v35, -v19, v51, v35
	v_fma_f32 v34, -v18, v50, v34
	v_fma_f32 v33, -v17, v49, v33
	v_fma_f32 v32, -v16, v48, v32
	v_fma_f32 v35, -v23, v55, v35
	v_fma_f32 v34, -v22, v54, v34
	v_fma_f32 v33, -v21, v53, v33
	v_fma_f32 v32, -v20, v52, v32
	v_fma_f32 v35, -v27, v59, v35
	v_fma_f32 v34, -v26, v58, v34
	v_fma_f32 v33, -v25, v57, v33
	v_fma_f32 v32, -v24, v56, v32
	v_fma_f32 v35, -v71, v31, v35
	v_fma_f32 v34, -v30, v70, v34
	v_fma_f32 v33, -v29, v69, v33
	v_fma_f32 v32, -v28, v68, v32
	v_add_f32_e32 v32, v33, v32
	v_add_f32_e32 v33, v34, v35
	ds_read_b128 v[34:37], v65 offset:43264
	ds_read_b128 v[38:41], v65 offset:43280
	ds_read_b128 v[42:45], v65 offset:43296
	ds_read_b128 v[46:49], v65 offset:43312
	ds_read_b128 v[50:53], v65 offset:43328
	v_add_f32_e32 v32, v33, v32
	s_waitcnt lgkmcnt(4)
	v_fma_f32 v33, -v3, v37, 0
	v_fma_f32 v36, -v2, v36, 0
	v_fma_f32 v35, -v1, v35, 0
	v_fma_f32 v34, -v0, v34, v81
	s_waitcnt lgkmcnt(3)
	v_fma_f32 v33, -v7, v41, v33
	v_fma_f32 v36, -v6, v40, v36
	v_fma_f32 v35, -v5, v39, v35
	v_fma_f32 v34, -v4, v38, v34
	s_waitcnt lgkmcnt(2)
	v_fma_f32 v33, -v11, v45, v33
	ds_read_b128 v[54:57], v65 offset:43344
	ds_read_b128 v[58:61], v65 offset:43360
	ds_read_b128 v[68:71], v65 offset:43376
	v_fma_f32 v36, -v10, v44, v36
	v_fma_f32 v35, -v9, v43, v35
	v_fma_f32 v34, -v8, v42, v34
	s_waitcnt lgkmcnt(4)
	v_fma_f32 v33, -v15, v49, v33
	ds_read_b128 v[72:75], v65 offset:43392
	ds_read_b128 v[76:79], v65 offset:43520
	v_fma_f32 v36, -v14, v48, v36
	v_fma_f32 v35, -v13, v47, v35
	v_fma_f32 v34, -v12, v46, v34
	s_waitcnt lgkmcnt(5)
	v_fma_f32 v33, -v19, v53, v33
	v_fma_f32 v36, -v18, v52, v36
	v_fma_f32 v35, -v17, v51, v35
	v_fma_f32 v34, -v16, v50, v34
	s_waitcnt lgkmcnt(4)
	v_fma_f32 v33, -v23, v57, v33
	v_fma_f32 v36, -v22, v56, v36
	v_fma_f32 v35, -v21, v55, v35
	v_fma_f32 v34, -v20, v54, v34
	s_waitcnt lgkmcnt(3)
	v_fma_f32 v33, -v27, v61, v33
	v_fma_f32 v36, -v26, v60, v36
	v_fma_f32 v35, -v25, v59, v35
	v_fma_f32 v34, -v24, v58, v34
	s_waitcnt lgkmcnt(2)
	v_fma_f32 v33, -v31, v71, v33
	v_fma_f32 v36, -v30, v70, v36
	v_fma_f32 v35, -v29, v69, v35
	v_fma_f32 v34, -v28, v68, v34
	s_waitcnt lgkmcnt(1)
	v_fmac_f32_e32 v33, 0x80000000, v75
	v_fmac_f32_e32 v36, 0x80000000, v74
	v_fmac_f32_e32 v35, 0x80000000, v73
	v_fma_f32 v34, -v72, v32, v34
	v_add_f32_e32 v42, v35, v34
	v_add_f32_e32 v33, v36, v33
	ds_read_b128 v[34:37], v65 offset:43536
	ds_read_b128 v[38:41], v65 offset:43552
	v_add_f32_e32 v33, v33, v42
	ds_read_b128 v[42:45], v65 offset:43568
	s_waitcnt lgkmcnt(3)
	v_fma_f32 v46, -v3, v79, 0
	s_waitcnt lgkmcnt(2)
	v_fma_f32 v37, -v7, v37, v46
	ds_read_b128 v[46:49], v65 offset:43584
	s_waitcnt lgkmcnt(2)
	v_fma_f32 v37, -v11, v41, v37
	v_fma_f32 v41, -v2, v78, 0
	v_fma_f32 v36, -v6, v36, v41
	v_fma_f32 v36, -v10, v40, v36
	s_waitcnt lgkmcnt(1)
	v_fma_f32 v37, -v15, v45, v37
	ds_read_b128 v[50:53], v65 offset:43600
	ds_read_b128 v[54:57], v65 offset:43616
	ds_read_b128 v[58:61], v65 offset:43632
	ds_read_b128 v[68:71], v65 offset:43648
	v_fma_f32 v36, -v14, v44, v36
	s_waitcnt lgkmcnt(4)
	v_fma_f32 v37, -v19, v49, v37
	v_fma_f32 v36, -v18, v48, v36
	s_waitcnt lgkmcnt(3)
	v_fma_f32 v37, -v23, v53, v37
	v_fma_f32 v36, -v22, v52, v36
	s_waitcnt lgkmcnt(2)
	v_fma_f32 v37, -v27, v57, v37
	v_fma_f32 v36, -v26, v56, v36
	s_waitcnt lgkmcnt(1)
	v_fma_f32 v37, -v31, v61, v37
	v_fma_f32 v36, -v30, v60, v36
	ds_read2st64_b32 v[60:61], v62 offset0:136 offset1:140
	v_fma_f32 v40, -v1, v77, 0
	v_fma_f32 v35, -v5, v35, v40
	v_fma_f32 v35, -v9, v39, v35
	v_fma_f32 v35, -v13, v43, v35
	s_waitcnt lgkmcnt(0)
; #define LAS __attribute__((address_space(3)))
; __device__ __forceinline__ void phase_chunk_prep(const Params& p, LAS unsigned char* lds, int wave_s) {
;     ...
;             for (int i = 0; i < 64; ++i) {
;                 float s0 = RHS[i * 256 + col], s1 = 0.f, s2 = 0.f, s3 = 0.f;
; #pragma unroll
;                 for (int j4 = 0; j4 < (i + 3) / 4; ++j4) { const f32x4 a = *(const LAS f32x4*)(AM + i * 64 + 4 * j4);
;                     s0 -= a.x * sol[4 * j4]; s1 -= a.y * sol[4 * j4 + 1]; s2 -= a.z * sol[4 * j4 + 2]; s3 -= a.w * sol[4 * j4 + 3]; }
;                 sol[i] = (s0 + s1) + (s2 + s3);
	v_fma_f32 v39, -v0, v76, v60
	v_fma_f32 v34, -v4, v34, v39
	v_fma_f32 v34, -v8, v38, v34
	v_fma_f32 v34, -v12, v42, v34
	v_fma_f32 v35, -v17, v47, v35
	v_fma_f32 v34, -v16, v46, v34
	v_fma_f32 v35, -v21, v51, v35
	v_fma_f32 v34, -v20, v50, v34
	v_fma_f32 v35, -v25, v55, v35
	v_fma_f32 v34, -v24, v54, v34
	v_fma_f32 v35, -v29, v59, v35
	v_fma_f32 v34, -v28, v58, v34
	v_fmac_f32_e32 v37, 0x80000000, v71
	v_fmac_f32_e32 v36, 0x80000000, v70
	v_fma_f32 v35, -v69, v33, v35
	v_fma_f32 v34, -v32, v68, v34
	v_add_f32_e32 v34, v35, v34
	v_add_f32_e32 v35, v36, v37
	ds_read_b128 v[36:39], v65 offset:43776
	ds_read_b128 v[40:43], v65 offset:43792
	ds_read_b128 v[44:47], v65 offset:43808
	ds_read_b128 v[48:51], v65 offset:43824
	ds_read_b128 v[52:55], v65 offset:43840
	v_add_f32_e32 v34, v35, v34
	s_waitcnt lgkmcnt(4)
	v_fma_f32 v35, -v3, v39, 0
	v_fma_f32 v38, -v2, v38, 0
	v_fma_f32 v37, -v1, v37, 0
	v_fma_f32 v36, -v0, v36, v61
	s_waitcnt lgkmcnt(3)
	v_fma_f32 v35, -v7, v43, v35
	v_fma_f32 v38, -v6, v42, v38
	v_fma_f32 v37, -v5, v41, v37
	v_fma_f32 v36, -v4, v40, v36
	s_waitcnt lgkmcnt(2)
	v_fma_f32 v35, -v11, v47, v35
	ds_read_b128 v[56:59], v65 offset:43856
	ds_read_b128 v[68:71], v65 offset:43872
	ds_read_b128 v[72:75], v65 offset:43888
	v_fma_f32 v38, -v10, v46, v38
	v_fma_f32 v37, -v9, v45, v37
	v_fma_f32 v36, -v8, v44, v36
	s_waitcnt lgkmcnt(4)
	v_fma_f32 v35, -v15, v51, v35
	ds_read_b128 v[76:79], v65 offset:43904
	ds_read_b128 v[80:83], v65 offset:44032
	v_fma_f32 v38, -v14, v50, v38
	v_fma_f32 v37, -v13, v49, v37
	v_fma_f32 v36, -v12, v48, v36
	s_waitcnt lgkmcnt(5)
	v_fma_f32 v35, -v19, v55, v35
	v_fma_f32 v38, -v18, v54, v38
	v_fma_f32 v37, -v17, v53, v37
	v_fma_f32 v36, -v16, v52, v36
	s_waitcnt lgkmcnt(4)
	v_fma_f32 v35, -v23, v59, v35
	v_fma_f32 v38, -v22, v58, v38
	v_fma_f32 v37, -v21, v57, v37
	v_fma_f32 v36, -v20, v56, v36
	s_waitcnt lgkmcnt(3)
	v_fma_f32 v35, -v27, v71, v35
	v_fma_f32 v38, -v26, v70, v38
	v_fma_f32 v37, -v25, v69, v37
	v_fma_f32 v36, -v24, v68, v36
	s_waitcnt lgkmcnt(2)
	v_fma_f32 v35, -v31, v75, v35
	v_fma_f32 v38, -v30, v74, v38
	v_fma_f32 v37, -v29, v73, v37
	v_fma_f32 v36, -v28, v72, v36
	s_waitcnt lgkmcnt(1)
	v_fmac_f32_e32 v35, 0x80000000, v79
	v_fma_f32 v38, -v78, v34, v38
	v_fma_f32 v37, -v33, v77, v37
	v_fma_f32 v36, -v32, v76, v36
	v_add_f32_e32 v44, v37, v36
	v_add_f32_e32 v35, v35, v38
	ds_read_b128 v[36:39], v65 offset:44048
	ds_read_b128 v[40:43], v65 offset:44064
	s_waitcnt lgkmcnt(2)
	v_fma_f32 v48, -v3, v83, 0
	v_add_f32_e32 v35, v35, v44
	ds_read_b128 v[44:47], v65 offset:44080
	s_waitcnt lgkmcnt(2)
	v_fma_f32 v39, -v7, v39, v48
	ds_read_b128 v[48:51], v65 offset:44096
	ds_read_b128 v[52:55], v65 offset:44112
	ds_read_b128 v[56:59], v65 offset:44128
	ds_read_b128 v[68:71], v65 offset:44144
	ds_read_b128 v[72:75], v65 offset:44160
	ds_read2st64_b32 v[84:85], v62 offset0:144 offset1:148
	s_waitcnt lgkmcnt(7)
	v_fma_f32 v39, -v11, v43, v39
	v_fma_f32 v43, -v2, v82, 0
	v_fma_f32 v38, -v6, v38, v43
	v_fma_f32 v38, -v10, v42, v38
	v_fma_f32 v42, -v1, v81, 0
	v_fma_f32 v37, -v5, v37, v42
	v_fma_f32 v37, -v9, v41, v37
	s_waitcnt lgkmcnt(0)
	v_fma_f32 v41, -v0, v80, v84
	v_fma_f32 v36, -v4, v36, v41
	v_fma_f32 v36, -v8, v40, v36
	v_fma_f32 v39, -v15, v47, v39
	v_fma_f32 v38, -v14, v46, v38
	v_fma_f32 v37, -v13, v45, v37
	v_fma_f32 v36, -v12, v44, v36
	v_fma_f32 v39, -v19, v51, v39
	v_fma_f32 v38, -v18, v50, v38
	v_fma_f32 v37, -v17, v49, v37
	v_fma_f32 v36, -v16, v48, v36
	v_fma_f32 v39, -v23, v55, v39
	v_fma_f32 v38, -v22, v54, v38
	v_fma_f32 v37, -v21, v53, v37
	v_fma_f32 v36, -v20, v52, v36
	v_fma_f32 v39, -v27, v59, v39
	v_fma_f32 v38, -v26, v58, v38
	v_fma_f32 v37, -v25, v57, v37
	v_fma_f32 v36, -v24, v56, v36
	v_fma_f32 v39, -v31, v71, v39
	v_fma_f32 v38, -v30, v70, v38
	v_fma_f32 v37, -v29, v69, v37
	v_fma_f32 v36, -v28, v68, v36
	v_fma_f32 v39, -v75, v35, v39
	v_fma_f32 v38, -v34, v74, v38
	v_fma_f32 v37, -v33, v73, v37
	v_fma_f32 v36, -v32, v72, v36
	v_add_f32_e32 v36, v37, v36
	v_add_f32_e32 v37, v38, v39
	ds_read_b128 v[38:41], v65 offset:44288
	ds_read_b128 v[42:45], v65 offset:44304
	ds_read_b128 v[46:49], v65 offset:44320
	ds_read_b128 v[50:53], v65 offset:44336
	ds_read_b128 v[54:57], v65 offset:44352
	ds_read_b128 v[58:61], v65 offset:44368
	v_add_f32_e32 v36, v37, v36
	s_waitcnt lgkmcnt(5)
	v_fma_f32 v37, -v3, v41, 0
	v_fma_f32 v40, -v2, v40, 0
	v_fma_f32 v39, -v1, v39, 0
	v_fma_f32 v38, -v0, v38, v85
	s_waitcnt lgkmcnt(4)
	v_fma_f32 v37, -v7, v45, v37
	v_fma_f32 v40, -v6, v44, v40
	v_fma_f32 v39, -v5, v43, v39
	v_fma_f32 v38, -v4, v42, v38
	s_waitcnt lgkmcnt(3)
	v_fma_f32 v37, -v11, v49, v37
	v_fma_f32 v40, -v10, v48, v40
	v_fma_f32 v39, -v9, v47, v39
	v_fma_f32 v38, -v8, v46, v38
	s_waitcnt lgkmcnt(2)
	v_fma_f32 v37, -v15, v53, v37
	v_fma_f32 v40, -v14, v52, v40
	v_fma_f32 v39, -v13, v51, v39
	v_fma_f32 v38, -v12, v50, v38
	s_waitcnt lgkmcnt(1)
	v_fma_f32 v37, -v19, v57, v37
	ds_read_b128 v[68:71], v65 offset:44384
	ds_read_b128 v[72:75], v65 offset:44400
	ds_read_b128 v[76:79], v65 offset:44416
	ds_read_b128 v[80:83], v65 offset:44432
	v_fma_f32 v40, -v18, v56, v40
	v_fma_f32 v39, -v17, v55, v39
	v_fma_f32 v38, -v16, v54, v38
	s_waitcnt lgkmcnt(4)
	v_fma_f32 v37, -v23, v61, v37
	v_fma_f32 v40, -v22, v60, v40
	v_fma_f32 v39, -v21, v59, v39
	v_fma_f32 v38, -v20, v58, v38
	s_waitcnt lgkmcnt(3)
	v_fma_f32 v37, -v27, v71, v37
	v_fma_f32 v40, -v26, v70, v40
	v_fma_f32 v39, -v25, v69, v39
	v_fma_f32 v38, -v24, v68, v38
	s_waitcnt lgkmcnt(2)
	v_fma_f32 v37, -v31, v75, v37
	v_fma_f32 v40, -v30, v74, v40
	v_fma_f32 v39, -v29, v73, v39
	v_fma_f32 v38, -v28, v72, v38
	s_waitcnt lgkmcnt(1)
; #define LAS __attribute__((address_space(3)))
; __device__ __forceinline__ void phase_chunk_prep(const Params& p, LAS unsigned char* lds, int wave_s) {
;     ...
;             for (int i = 0; i < 64; ++i) {
;                 float s0 = RHS[i * 256 + col], s1 = 0.f, s2 = 0.f, s3 = 0.f;
; #pragma unroll
;                 for (int j4 = 0; j4 < (i + 3) / 4; ++j4) { const f32x4 a = *(const LAS f32x4*)(AM + i * 64 + 4 * j4);
;                     s0 -= a.x * sol[4 * j4]; s1 -= a.y * sol[4 * j4 + 1]; s2 -= a.z * sol[4 * j4 + 2]; s3 -= a.w * sol[4 * j4 + 3]; }
;                 sol[i] = (s0 + s1) + (s2 + s3);
	v_fma_f32 v37, -v35, v79, v37
	v_fma_f32 v40, -v34, v78, v40
	v_fma_f32 v39, -v33, v77, v39
	v_fma_f32 v38, -v32, v76, v38
	s_waitcnt lgkmcnt(0)
	v_fmac_f32_e32 v37, 0x80000000, v83
	v_fmac_f32_e32 v40, 0x80000000, v82
	v_fmac_f32_e32 v39, 0x80000000, v81
	v_fma_f32 v38, -v80, v36, v38
	v_add_f32_e32 v42, v39, v38
	v_add_f32_e32 v37, v40, v37
	ds_read_b128 v[38:41], v65 offset:44544
	v_add_f32_e32 v37, v37, v42
	ds_read_b128 v[42:45], v65 offset:44560
	ds_read_b128 v[46:49], v65 offset:44576
	ds_read_b128 v[50:53], v65 offset:44592
	ds_read_b128 v[54:57], v65 offset:44608
	ds_read_b128 v[58:61], v65 offset:44624
	s_waitcnt lgkmcnt(5)
	v_fma_f32 v41, -v3, v41, 0
	v_fma_f32 v40, -v2, v40, 0
	s_waitcnt lgkmcnt(4)
	v_fma_f32 v41, -v7, v45, v41
	v_fma_f32 v40, -v6, v44, v40
	s_waitcnt lgkmcnt(3)
	v_fma_f32 v41, -v11, v49, v41
	v_fma_f32 v40, -v10, v48, v40
	s_waitcnt lgkmcnt(2)
	v_fma_f32 v41, -v15, v53, v41
	v_fma_f32 v40, -v14, v52, v40
	s_waitcnt lgkmcnt(1)
	v_fma_f32 v41, -v19, v57, v41
	v_fma_f32 v40, -v18, v56, v40
	ds_read_b128 v[68:71], v65 offset:44640
	ds_read_b128 v[72:75], v65 offset:44656
	ds_read_b128 v[76:79], v65 offset:44672
	ds_read_b128 v[80:83], v65 offset:44688
	s_waitcnt lgkmcnt(4)
	v_fma_f32 v41, -v23, v61, v41
	v_fma_f32 v40, -v22, v60, v40
	ds_read2st64_b32 v[60:61], v62 offset0:152 offset1:156
	v_fma_f32 v39, -v1, v39, 0
	v_fma_f32 v39, -v5, v43, v39
	v_fma_f32 v39, -v9, v47, v39
	v_fma_f32 v39, -v13, v51, v39
	s_waitcnt lgkmcnt(0)
	v_fma_f32 v38, -v0, v38, v60
	v_fma_f32 v38, -v4, v42, v38
	v_fma_f32 v38, -v8, v46, v38
	v_fma_f32 v38, -v12, v50, v38
	v_fma_f32 v39, -v17, v55, v39
	v_fma_f32 v38, -v16, v54, v38
	v_fma_f32 v39, -v21, v59, v39
	v_fma_f32 v38, -v20, v58, v38
	v_fma_f32 v41, -v27, v71, v41
	v_fma_f32 v40, -v26, v70, v40
	v_fma_f32 v39, -v25, v69, v39
	v_fma_f32 v38, -v24, v68, v38
	v_fma_f32 v41, -v31, v75, v41
	v_fma_f32 v40, -v30, v74, v40
	v_fma_f32 v39, -v29, v73, v39
	v_fma_f32 v38, -v28, v72, v38
	v_fma_f32 v41, -v35, v79, v41
	v_fma_f32 v40, -v34, v78, v40
	v_fma_f32 v39, -v33, v77, v39
	v_fma_f32 v38, -v32, v76, v38
	v_fmac_f32_e32 v41, 0x80000000, v83
	v_fmac_f32_e32 v40, 0x80000000, v82
	v_fma_f32 v39, -v81, v37, v39
	v_fma_f32 v38, -v36, v80, v38
	v_add_f32_e32 v38, v39, v38
	v_add_f32_e32 v39, v40, v41
	ds_read_b128 v[40:43], v65 offset:44800
	ds_read_b128 v[44:47], v65 offset:44816
	ds_read_b128 v[48:51], v65 offset:44832
	ds_read_b128 v[52:55], v65 offset:44848
	ds_read_b128 v[56:59], v65 offset:44864
	ds_read_b128 v[68:71], v65 offset:44880
	v_add_f32_e32 v38, v39, v38
	s_waitcnt lgkmcnt(5)
	v_fma_f32 v39, -v3, v43, 0
	v_fma_f32 v42, -v2, v42, 0
	v_fma_f32 v41, -v1, v41, 0
	v_fma_f32 v40, -v0, v40, v61
	s_waitcnt lgkmcnt(4)
	v_fma_f32 v39, -v7, v47, v39
	v_fma_f32 v42, -v6, v46, v42
	v_fma_f32 v41, -v5, v45, v41
	v_fma_f32 v40, -v4, v44, v40
	s_waitcnt lgkmcnt(3)
	v_fma_f32 v39, -v11, v51, v39
	v_fma_f32 v42, -v10, v50, v42
	v_fma_f32 v41, -v9, v49, v41
	v_fma_f32 v40, -v8, v48, v40
	s_waitcnt lgkmcnt(2)
	v_fma_f32 v39, -v15, v55, v39
	v_fma_f32 v42, -v14, v54, v42
	v_fma_f32 v41, -v13, v53, v41
	v_fma_f32 v40, -v12, v52, v40
	s_waitcnt lgkmcnt(1)
	v_fma_f32 v39, -v19, v59, v39
	ds_read_b128 v[72:75], v65 offset:44896
	ds_read_b128 v[76:79], v65 offset:44912
	ds_read_b128 v[80:83], v65 offset:44928
	ds_read_b128 v[84:87], v65 offset:44944
	v_fma_f32 v42, -v18, v58, v42
	v_fma_f32 v41, -v17, v57, v41
	v_fma_f32 v40, -v16, v56, v40
	s_waitcnt lgkmcnt(4)
	v_fma_f32 v39, -v23, v71, v39
	v_fma_f32 v42, -v22, v70, v42
	v_fma_f32 v41, -v21, v69, v41
	v_fma_f32 v40, -v20, v68, v40
	s_waitcnt lgkmcnt(3)
	v_fma_f32 v39, -v27, v75, v39
	v_fma_f32 v42, -v26, v74, v42
	v_fma_f32 v41, -v25, v73, v41
	v_fma_f32 v40, -v24, v72, v40
	s_waitcnt lgkmcnt(2)
	v_fma_f32 v39, -v31, v79, v39
	v_fma_f32 v42, -v30, v78, v42
	v_fma_f32 v41, -v29, v77, v41
	v_fma_f32 v40, -v28, v76, v40
	s_waitcnt lgkmcnt(1)
	v_fma_f32 v39, -v35, v83, v39
	v_fma_f32 v42, -v34, v82, v42
	v_fma_f32 v41, -v33, v81, v41
	v_fma_f32 v40, -v32, v80, v40
	s_waitcnt lgkmcnt(0)
	v_fmac_f32_e32 v39, 0x80000000, v87
	v_fma_f32 v42, -v86, v38, v42
	v_fma_f32 v41, -v37, v85, v41
	v_fma_f32 v40, -v36, v84, v40
	v_add_f32_e32 v44, v41, v40
	v_add_f32_e32 v39, v39, v42
	ds_read_b128 v[40:43], v65 offset:45056
	v_add_f32_e32 v39, v39, v44
	ds_read_b128 v[44:47], v65 offset:45072
	ds_read_b128 v[48:51], v65 offset:45088
	ds_read_b128 v[52:55], v65 offset:45104
	ds_read_b128 v[56:59], v65 offset:45120
	ds_read_b128 v[68:71], v65 offset:45136
	ds_read_b128 v[72:75], v65 offset:45152
	ds_read_b128 v[76:79], v65 offset:45168
	ds_read_b128 v[80:83], v65 offset:45184
	ds_read_b128 v[84:87], v65 offset:45200
	ds_read2st64_b32 v[96:97], v62 offset0:160 offset1:164
	s_waitcnt lgkmcnt(10)
	v_fma_f32 v43, -v3, v43, 0
	v_fma_f32 v42, -v2, v42, 0
	v_fma_f32 v41, -v1, v41, 0
	s_waitcnt lgkmcnt(9)
	v_fma_f32 v43, -v7, v47, v43
	s_waitcnt lgkmcnt(0)
	v_fma_f32 v40, -v0, v40, v96
	v_fma_f32 v42, -v6, v46, v42
	v_fma_f32 v41, -v5, v45, v41
	v_fma_f32 v40, -v4, v44, v40
	v_fma_f32 v43, -v11, v51, v43
	v_fma_f32 v42, -v10, v50, v42
	v_fma_f32 v41, -v9, v49, v41
	v_fma_f32 v40, -v8, v48, v40
	v_fma_f32 v43, -v15, v55, v43
	v_fma_f32 v42, -v14, v54, v42
	v_fma_f32 v41, -v13, v53, v41
	v_fma_f32 v40, -v12, v52, v40
	v_fma_f32 v43, -v19, v59, v43
	v_fma_f32 v42, -v18, v58, v42
	v_fma_f32 v41, -v17, v57, v41
	v_fma_f32 v40, -v16, v56, v40
	v_fma_f32 v43, -v23, v71, v43
	v_fma_f32 v42, -v22, v70, v42
	v_fma_f32 v41, -v21, v69, v41
	v_fma_f32 v40, -v20, v68, v40
	v_fma_f32 v43, -v27, v75, v43
	v_fma_f32 v42, -v26, v74, v42
	v_fma_f32 v41, -v25, v73, v41
	v_fma_f32 v40, -v24, v72, v40
	v_fma_f32 v43, -v31, v79, v43
	v_fma_f32 v42, -v30, v78, v42
	v_fma_f32 v41, -v29, v77, v41
	v_fma_f32 v40, -v28, v76, v40
	v_fma_f32 v43, -v35, v83, v43
	v_fma_f32 v42, -v34, v82, v42
	v_fma_f32 v41, -v33, v81, v41
	v_fma_f32 v40, -v32, v80, v40
	v_fma_f32 v47, -v87, v39, v43
	v_fma_f32 v46, -v38, v86, v42
	v_fma_f32 v41, -v37, v85, v41
	v_fma_f32 v40, -v36, v84, v40
	ds_read_b128 v[42:45], v65 offset:45312
	v_add_f32_e32 v40, v41, v40
	v_add_f32_e32 v41, v46, v47
	ds_read_b128 v[46:49], v65 offset:45328
	ds_read_b128 v[50:53], v65 offset:45344
	ds_read_b128 v[54:57], v65 offset:45360
	ds_read_b128 v[58:61], v65 offset:45376
	v_add_f32_e32 v40, v41, v40
	s_waitcnt lgkmcnt(4)
; #define LAS __attribute__((address_space(3)))
; __device__ __forceinline__ void phase_chunk_prep(const Params& p, LAS unsigned char* lds, int wave_s) {
;     ...
;             for (int i = 0; i < 64; ++i) {
;                 float s0 = RHS[i * 256 + col], s1 = 0.f, s2 = 0.f, s3 = 0.f;
; #pragma unroll
;                 for (int j4 = 0; j4 < (i + 3) / 4; ++j4) { const f32x4 a = *(const LAS f32x4*)(AM + i * 64 + 4 * j4);
;                     s0 -= a.x * sol[4 * j4]; s1 -= a.y * sol[4 * j4 + 1]; s2 -= a.z * sol[4 * j4 + 2]; s3 -= a.w * sol[4 * j4 + 3]; }
;                 sol[i] = (s0 + s1) + (s2 + s3);
	v_fma_f32 v41, -v3, v45, 0
	ds_read_b128 v[68:71], v65 offset:45392
	ds_read_b128 v[72:75], v65 offset:45408
	v_fma_f32 v44, -v2, v44, 0
	v_fma_f32 v43, -v1, v43, 0
	v_fma_f32 v42, -v0, v42, v97
	s_waitcnt lgkmcnt(5)
	v_fma_f32 v41, -v7, v49, v41
	v_fma_f32 v44, -v6, v48, v44
	v_fma_f32 v43, -v5, v47, v43
	v_fma_f32 v42, -v4, v46, v42
	s_waitcnt lgkmcnt(4)
	v_fma_f32 v41, -v11, v53, v41
	v_fma_f32 v44, -v10, v52, v44
	v_fma_f32 v43, -v9, v51, v43
	v_fma_f32 v42, -v8, v50, v42
	s_waitcnt lgkmcnt(3)
	v_fma_f32 v41, -v15, v57, v41
	v_fma_f32 v44, -v14, v56, v44
	v_fma_f32 v43, -v13, v55, v43
	v_fma_f32 v42, -v12, v54, v42
	s_waitcnt lgkmcnt(2)
	v_fma_f32 v41, -v19, v61, v41
	ds_read_b128 v[76:79], v65 offset:45424
	ds_read_b128 v[80:83], v65 offset:45440
	ds_read_b128 v[84:87], v65 offset:45456
	v_fma_f32 v44, -v18, v60, v44
	v_fma_f32 v43, -v17, v59, v43
	v_fma_f32 v42, -v16, v58, v42
	s_waitcnt lgkmcnt(4)
	v_fma_f32 v41, -v23, v71, v41
	ds_read_b128 v[88:91], v65 offset:45472
	ds_read_b128 v[92:95], v65 offset:45568
	v_fma_f32 v44, -v22, v70, v44
	v_fma_f32 v43, -v21, v69, v43
	v_fma_f32 v42, -v20, v68, v42
	s_waitcnt lgkmcnt(5)
	v_fma_f32 v41, -v27, v75, v41
	v_fma_f32 v44, -v26, v74, v44
	v_fma_f32 v43, -v25, v73, v43
	v_fma_f32 v42, -v24, v72, v42
	s_waitcnt lgkmcnt(4)
	v_fma_f32 v41, -v31, v79, v41
	v_fma_f32 v44, -v30, v78, v44
	v_fma_f32 v43, -v29, v77, v43
	v_fma_f32 v42, -v28, v76, v42
	s_waitcnt lgkmcnt(3)
	v_fma_f32 v41, -v35, v83, v41
	v_fma_f32 v44, -v34, v82, v44
	v_fma_f32 v43, -v33, v81, v43
	v_fma_f32 v42, -v32, v80, v42
	s_waitcnt lgkmcnt(2)
	v_fma_f32 v41, -v39, v87, v41
	v_fma_f32 v44, -v38, v86, v44
	v_fma_f32 v43, -v37, v85, v43
	v_fma_f32 v42, -v36, v84, v42
	s_waitcnt lgkmcnt(1)
	v_fmac_f32_e32 v41, 0x80000000, v91
	v_fmac_f32_e32 v44, 0x80000000, v90
	v_fmac_f32_e32 v43, 0x80000000, v89
	v_fma_f32 v42, -v88, v40, v42
	v_add_f32_e32 v42, v43, v42
	v_add_f32_e32 v41, v44, v41
	v_add_f32_e32 v41, v41, v42
	ds_read_b128 v[42:45], v65 offset:45584
	s_waitcnt lgkmcnt(1)
	v_fma_f32 v58, -v3, v95, 0
	ds_read_b128 v[46:49], v65 offset:45600
	ds_read_b128 v[50:53], v65 offset:45616
	ds_read_b128 v[54:57], v65 offset:45632
	ds_read_b128 v[68:71], v65 offset:45664
	s_waitcnt lgkmcnt(4)
	v_fma_f32 v45, -v7, v45, v58
	ds_read_b128 v[58:61], v65 offset:45648
	s_waitcnt lgkmcnt(4)
	v_fma_f32 v45, -v11, v49, v45
	s_waitcnt lgkmcnt(3)
	v_fma_f32 v45, -v15, v53, v45
	s_waitcnt lgkmcnt(2)
	v_fma_f32 v45, -v19, v57, v45
	ds_read_b128 v[72:75], v65 offset:45680
	ds_read_b128 v[76:79], v65 offset:45696
	ds_read_b128 v[80:83], v65 offset:45712
	ds_read_b128 v[84:87], v65 offset:45728
	s_waitcnt lgkmcnt(4)
	v_fma_f32 v45, -v23, v61, v45
	v_fma_f32 v45, -v27, v71, v45
	s_waitcnt lgkmcnt(3)
	v_fma_f32 v45, -v31, v75, v45
	s_waitcnt lgkmcnt(2)
	v_fma_f32 v45, -v35, v79, v45
	s_waitcnt lgkmcnt(1)
	v_fma_f32 v49, -v39, v83, v45
	v_fma_f32 v45, -v2, v94, 0
	v_fma_f32 v44, -v6, v44, v45
	v_fma_f32 v44, -v10, v48, v44
	v_fma_f32 v44, -v14, v52, v44
	v_fma_f32 v44, -v18, v56, v44
	v_fma_f32 v44, -v22, v60, v44
	ds_read2st64_b32 v[60:61], v62 offset0:168 offset1:172
	v_fma_f32 v44, -v26, v70, v44
	v_fma_f32 v44, -v30, v74, v44
	v_fma_f32 v44, -v34, v78, v44
	v_fma_f32 v48, -v38, v82, v44
	v_fma_f32 v44, -v1, v93, 0
	v_fma_f32 v43, -v5, v43, v44
	s_waitcnt lgkmcnt(0)
	v_fma_f32 v44, -v0, v92, v60
	v_fma_f32 v42, -v4, v42, v44
	v_fma_f32 v43, -v9, v47, v43
	v_fma_f32 v42, -v8, v46, v42
	v_fma_f32 v43, -v13, v51, v43
	v_fma_f32 v42, -v12, v50, v42
	v_fma_f32 v43, -v17, v55, v43
	v_fma_f32 v42, -v16, v54, v42
	v_fma_f32 v43, -v21, v59, v43
	v_fma_f32 v42, -v20, v58, v42
	v_fma_f32 v43, -v25, v69, v43
	v_fma_f32 v42, -v24, v68, v42
	v_fma_f32 v43, -v29, v73, v43
	v_fma_f32 v42, -v28, v72, v42
	v_fma_f32 v43, -v33, v77, v43
	v_fma_f32 v42, -v32, v76, v42
	v_fma_f32 v43, -v37, v81, v43
	v_fma_f32 v42, -v36, v80, v42
	v_fmac_f32_e32 v49, 0x80000000, v87
	v_fmac_f32_e32 v48, 0x80000000, v86
	v_fma_f32 v43, -v85, v41, v43
	v_fma_f32 v42, -v40, v84, v42
	ds_read_b128 v[44:47], v65 offset:45824
	v_add_f32_e32 v42, v43, v42
	v_add_f32_e32 v43, v48, v49
	ds_read_b128 v[48:51], v65 offset:45840
	ds_read_b128 v[52:55], v65 offset:45856
	ds_read_b128 v[56:59], v65 offset:45872
	ds_read_b128 v[68:71], v65 offset:45888
	v_add_f32_e32 v42, v43, v42
	s_waitcnt lgkmcnt(4)
	v_fma_f32 v43, -v3, v47, 0
	ds_read_b128 v[72:75], v65 offset:45904
	ds_read_b128 v[76:79], v65 offset:45920
	v_fma_f32 v46, -v2, v46, 0
	v_fma_f32 v45, -v1, v45, 0
	v_fma_f32 v44, -v0, v44, v61
	s_waitcnt lgkmcnt(5)
	v_fma_f32 v43, -v7, v51, v43
	v_fma_f32 v46, -v6, v50, v46
	v_fma_f32 v45, -v5, v49, v45
	v_fma_f32 v44, -v4, v48, v44
	s_waitcnt lgkmcnt(4)
	v_fma_f32 v43, -v11, v55, v43
	v_fma_f32 v46, -v10, v54, v46
	v_fma_f32 v45, -v9, v53, v45
	v_fma_f32 v44, -v8, v52, v44
	s_waitcnt lgkmcnt(3)
	v_fma_f32 v43, -v15, v59, v43
	v_fma_f32 v46, -v14, v58, v46
	v_fma_f32 v45, -v13, v57, v45
	v_fma_f32 v44, -v12, v56, v44
	s_waitcnt lgkmcnt(2)
	v_fma_f32 v43, -v19, v71, v43
	ds_read_b128 v[80:83], v65 offset:45936
	ds_read_b128 v[84:87], v65 offset:45952
	ds_read_b128 v[88:91], v65 offset:45968
	v_fma_f32 v46, -v18, v70, v46
	v_fma_f32 v45, -v17, v69, v45
	v_fma_f32 v44, -v16, v68, v44
	s_waitcnt lgkmcnt(4)
	v_fma_f32 v43, -v23, v75, v43
	ds_read_b128 v[92:95], v65 offset:45984
	ds_read_b128 v[96:99], v65 offset:46080
	v_fma_f32 v46, -v22, v74, v46
	v_fma_f32 v45, -v21, v73, v45
	v_fma_f32 v44, -v20, v72, v44
	s_waitcnt lgkmcnt(5)
	v_fma_f32 v43, -v27, v79, v43
	v_fma_f32 v46, -v26, v78, v46
	v_fma_f32 v45, -v25, v77, v45
	v_fma_f32 v44, -v24, v76, v44
	s_waitcnt lgkmcnt(4)
; #define LAS __attribute__((address_space(3)))
; __device__ __forceinline__ void phase_chunk_prep(const Params& p, LAS unsigned char* lds, int wave_s) {
;     ...
;             for (int i = 0; i < 64; ++i) {
;                 float s0 = RHS[i * 256 + col], s1 = 0.f, s2 = 0.f, s3 = 0.f;
; #pragma unroll
;                 for (int j4 = 0; j4 < (i + 3) / 4; ++j4) { const f32x4 a = *(const LAS f32x4*)(AM + i * 64 + 4 * j4);
;                     s0 -= a.x * sol[4 * j4]; s1 -= a.y * sol[4 * j4 + 1]; s2 -= a.z * sol[4 * j4 + 2]; s3 -= a.w * sol[4 * j4 + 3]; }
;                 sol[i] = (s0 + s1) + (s2 + s3);
	v_fma_f32 v43, -v31, v83, v43
	v_fma_f32 v46, -v30, v82, v46
	v_fma_f32 v45, -v29, v81, v45
	v_fma_f32 v44, -v28, v80, v44
	s_waitcnt lgkmcnt(3)
	v_fma_f32 v43, -v35, v87, v43
	v_fma_f32 v46, -v34, v86, v46
	v_fma_f32 v45, -v33, v85, v45
	v_fma_f32 v44, -v32, v84, v44
	s_waitcnt lgkmcnt(2)
	v_fma_f32 v43, -v39, v91, v43
	v_fma_f32 v46, -v38, v90, v46
	v_fma_f32 v45, -v37, v89, v45
	v_fma_f32 v44, -v36, v88, v44
	s_waitcnt lgkmcnt(1)
	v_fmac_f32_e32 v43, 0x80000000, v95
	v_fma_f32 v46, -v94, v42, v46
	v_fma_f32 v45, -v41, v93, v45
	v_fma_f32 v44, -v40, v92, v44
	v_add_f32_e32 v44, v45, v44
	v_add_f32_e32 v43, v43, v46
	v_add_f32_e32 v43, v43, v44
	ds_read_b128 v[44:47], v65 offset:46096
	ds_read_b128 v[48:51], v65 offset:46112
	ds_read_b128 v[52:55], v65 offset:46128
	ds_read_b128 v[56:59], v65 offset:46144
	s_waitcnt lgkmcnt(4)
	v_fma_f32 v60, -v3, v99, 0
	ds_read_b128 v[68:71], v65 offset:46160
	ds_read_b128 v[72:75], v65 offset:46176
	s_waitcnt lgkmcnt(5)
	v_fma_f32 v47, -v7, v47, v60
	s_waitcnt lgkmcnt(4)
	v_fma_f32 v47, -v11, v51, v47
	s_waitcnt lgkmcnt(3)
	v_fma_f32 v47, -v15, v55, v47
	s_waitcnt lgkmcnt(2)
	v_fma_f32 v47, -v19, v59, v47
	s_waitcnt lgkmcnt(1)
	v_fma_f32 v47, -v23, v71, v47
	ds_read_b128 v[76:79], v65 offset:46192
	ds_read_b128 v[80:83], v65 offset:46208
	ds_read_b128 v[84:87], v65 offset:46224
	ds_read_b128 v[88:91], v65 offset:46240
	s_waitcnt lgkmcnt(4)
	v_fma_f32 v47, -v27, v75, v47
	s_waitcnt lgkmcnt(3)
	v_fma_f32 v47, -v31, v79, v47
	s_waitcnt lgkmcnt(2)
	v_fma_f32 v47, -v35, v83, v47
	s_waitcnt lgkmcnt(1)
	v_fma_f32 v47, -v39, v87, v47
	s_waitcnt lgkmcnt(0)
	v_fma_f32 v55, -v91, v43, v47
	v_fma_f32 v47, -v2, v98, 0
	v_fma_f32 v46, -v6, v46, v47
	v_fma_f32 v46, -v10, v50, v46
	v_fma_f32 v46, -v14, v54, v46
	v_fma_f32 v46, -v18, v58, v46
	v_fma_f32 v46, -v22, v70, v46
	v_fma_f32 v46, -v26, v74, v46
	ds_read2st64_b32 v[100:101], v62 offset0:176 offset1:180
	v_fma_f32 v46, -v30, v78, v46
	v_fma_f32 v46, -v34, v82, v46
	v_fma_f32 v46, -v38, v86, v46
	v_fma_f32 v54, -v42, v90, v46
	v_fma_f32 v46, -v1, v97, 0
	v_fma_f32 v45, -v5, v45, v46
	s_waitcnt lgkmcnt(0)
	v_fma_f32 v46, -v0, v96, v100
	v_fma_f32 v44, -v4, v44, v46
	v_fma_f32 v45, -v9, v49, v45
	v_fma_f32 v44, -v8, v48, v44
	v_fma_f32 v45, -v13, v53, v45
	v_fma_f32 v44, -v12, v52, v44
	v_fma_f32 v45, -v17, v57, v45
	v_fma_f32 v44, -v16, v56, v44
	v_fma_f32 v45, -v21, v69, v45
	v_fma_f32 v44, -v20, v68, v44
	v_fma_f32 v45, -v25, v73, v45
	v_fma_f32 v44, -v24, v72, v44
	v_fma_f32 v45, -v29, v77, v45
	v_fma_f32 v44, -v28, v76, v44
	v_fma_f32 v45, -v33, v81, v45
	v_fma_f32 v44, -v32, v80, v44
	v_fma_f32 v45, -v37, v85, v45
	v_fma_f32 v44, -v36, v84, v44
	ds_read_b128 v[46:49], v65 offset:46336
	ds_read_b128 v[50:53], v65 offset:46352
	v_fma_f32 v45, -v41, v89, v45
	v_fma_f32 v44, -v40, v88, v44
	v_add_f32_e32 v44, v45, v44
	v_add_f32_e32 v45, v54, v55
	ds_read_b128 v[54:57], v65 offset:46368
	v_add_f32_e32 v44, v45, v44
	s_waitcnt lgkmcnt(2)
	v_fma_f32 v45, -v3, v49, 0
	ds_read_b128 v[58:61], v65 offset:46384
	ds_read_b128 v[68:71], v65 offset:46400
	ds_read_b128 v[72:75], v65 offset:46416
	v_fma_f32 v48, -v2, v48, 0
	v_fma_f32 v47, -v1, v47, 0
	v_fma_f32 v46, -v0, v46, v101
	s_waitcnt lgkmcnt(4)
	v_fma_f32 v45, -v7, v53, v45
	ds_read_b128 v[76:79], v65 offset:46432
	ds_read_b128 v[80:83], v65 offset:46448
	v_fma_f32 v48, -v6, v52, v48
	v_fma_f32 v47, -v5, v51, v47
	v_fma_f32 v46, -v4, v50, v46
	s_waitcnt lgkmcnt(5)
	v_fma_f32 v45, -v11, v57, v45
	v_fma_f32 v48, -v10, v56, v48
	v_fma_f32 v47, -v9, v55, v47
	v_fma_f32 v46, -v8, v54, v46
	s_waitcnt lgkmcnt(4)
	v_fma_f32 v45, -v15, v61, v45
	v_fma_f32 v48, -v14, v60, v48
	v_fma_f32 v47, -v13, v59, v47
	v_fma_f32 v46, -v12, v58, v46
	s_waitcnt lgkmcnt(3)
	v_fma_f32 v45, -v19, v71, v45
	v_fma_f32 v48, -v18, v70, v48
	v_fma_f32 v47, -v17, v69, v47
	v_fma_f32 v46, -v16, v68, v46
	s_waitcnt lgkmcnt(2)
	v_fma_f32 v45, -v23, v75, v45
	v_fma_f32 v48, -v22, v74, v48
	v_fma_f32 v47, -v21, v73, v47
	v_fma_f32 v46, -v20, v72, v46
	s_waitcnt lgkmcnt(1)
	v_fma_f32 v45, -v27, v79, v45
	ds_read_b128 v[84:87], v65 offset:46464
	ds_read_b128 v[88:91], v65 offset:46480
	ds_read_b128 v[92:95], v65 offset:46496
	ds_read_b128 v[96:99], v65 offset:46512
	v_fma_f32 v48, -v26, v78, v48
	v_fma_f32 v47, -v25, v77, v47
	v_fma_f32 v46, -v24, v76, v46
	s_waitcnt lgkmcnt(4)
	v_fma_f32 v45, -v31, v83, v45
	v_fma_f32 v48, -v30, v82, v48
	v_fma_f32 v47, -v29, v81, v47
	v_fma_f32 v46, -v28, v80, v46
	s_waitcnt lgkmcnt(3)
	v_fma_f32 v45, -v35, v87, v45
	v_fma_f32 v48, -v34, v86, v48
	v_fma_f32 v47, -v33, v85, v47
	v_fma_f32 v46, -v32, v84, v46
	s_waitcnt lgkmcnt(2)
	v_fma_f32 v45, -v39, v91, v45
	v_fma_f32 v48, -v38, v90, v48
	v_fma_f32 v47, -v37, v89, v47
	v_fma_f32 v46, -v36, v88, v46
	s_waitcnt lgkmcnt(1)
	v_fma_f32 v45, -v43, v95, v45
	v_fma_f32 v56, -v42, v94, v48
	v_fma_f32 v51, -v41, v93, v47
	v_fma_f32 v46, -v40, v92, v46
	s_waitcnt lgkmcnt(0)
	v_fmac_f32_e32 v45, 0x80000000, v99
	v_fmac_f32_e32 v56, 0x80000000, v98
	v_fmac_f32_e32 v51, 0x80000000, v97
	v_fma_f32 v50, -v96, v44, v46
	ds_read_b128 v[46:49], v65 offset:46592
	v_add_f32_e32 v54, v51, v50
	ds_read_b128 v[50:53], v65 offset:46608
	v_add_f32_e32 v45, v56, v45
	v_add_f32_e32 v45, v45, v54
	ds_read_b128 v[54:57], v65 offset:46624
	s_waitcnt lgkmcnt(2)
	v_fma_f32 v49, -v3, v49, 0
	ds_read_b128 v[58:61], v65 offset:46640
	ds_read_b128 v[68:71], v65 offset:46656
	ds_read_b128 v[72:75], v65 offset:46672
	v_fma_f32 v48, -v2, v48, 0
	s_waitcnt lgkmcnt(4)
	v_fma_f32 v49, -v7, v53, v49
	v_fma_f32 v48, -v6, v52, v48
	s_waitcnt lgkmcnt(3)
; #define LAS __attribute__((address_space(3)))
; __device__ __forceinline__ void phase_chunk_prep(const Params& p, LAS unsigned char* lds, int wave_s) {
;     ...
;             for (int i = 0; i < 64; ++i) {
;                 float s0 = RHS[i * 256 + col], s1 = 0.f, s2 = 0.f, s3 = 0.f;
; #pragma unroll
;                 for (int j4 = 0; j4 < (i + 3) / 4; ++j4) { const f32x4 a = *(const LAS f32x4*)(AM + i * 64 + 4 * j4);
;                     s0 -= a.x * sol[4 * j4]; s1 -= a.y * sol[4 * j4 + 1]; s2 -= a.z * sol[4 * j4 + 2]; s3 -= a.w * sol[4 * j4 + 3]; }
;                 sol[i] = (s0 + s1) + (s2 + s3);
	v_fma_f32 v49, -v11, v57, v49
	v_fma_f32 v48, -v10, v56, v48
	ds_read_b128 v[76:79], v65 offset:46688
	ds_read_b128 v[80:83], v65 offset:46704
	s_waitcnt lgkmcnt(4)
	v_fma_f32 v49, -v15, v61, v49
	ds_read_b128 v[84:87], v65 offset:46720
	ds_read_b128 v[88:91], v65 offset:46736
	ds_read_b128 v[92:95], v65 offset:46752
	ds_read_b128 v[96:99], v65 offset:46768
	v_fma_f32 v48, -v14, v60, v48
	ds_read2st64_b32 v[60:61], v62 offset0:184 offset1:188
	v_fma_f32 v47, -v1, v47, 0
	v_fma_f32 v47, -v5, v51, v47
	v_fma_f32 v47, -v9, v55, v47
	v_fma_f32 v47, -v13, v59, v47
	s_waitcnt lgkmcnt(0)
	v_fma_f32 v46, -v0, v46, v60
	v_fma_f32 v46, -v4, v50, v46
	v_fma_f32 v46, -v8, v54, v46
	v_fma_f32 v46, -v12, v58, v46
	v_fma_f32 v49, -v19, v71, v49
	v_fma_f32 v48, -v18, v70, v48
	v_fma_f32 v47, -v17, v69, v47
	v_fma_f32 v46, -v16, v68, v46
	v_fma_f32 v49, -v23, v75, v49
	v_fma_f32 v48, -v22, v74, v48
	v_fma_f32 v47, -v21, v73, v47
	v_fma_f32 v46, -v20, v72, v46
	v_fma_f32 v49, -v27, v79, v49
	v_fma_f32 v48, -v26, v78, v48
	v_fma_f32 v47, -v25, v77, v47
	v_fma_f32 v46, -v24, v76, v46
	v_fma_f32 v49, -v31, v83, v49
	v_fma_f32 v48, -v30, v82, v48
	v_fma_f32 v47, -v29, v81, v47
	v_fma_f32 v46, -v28, v80, v46
	v_fma_f32 v49, -v35, v87, v49
	v_fma_f32 v48, -v34, v86, v48
	v_fma_f32 v47, -v33, v85, v47
	v_fma_f32 v46, -v32, v84, v46
	v_fma_f32 v49, -v39, v91, v49
	v_fma_f32 v48, -v38, v90, v48
	v_fma_f32 v47, -v37, v89, v47
	v_fma_f32 v46, -v36, v88, v46
	v_fma_f32 v57, -v43, v95, v49
	v_fma_f32 v56, -v42, v94, v48
	v_fma_f32 v47, -v41, v93, v47
	v_fma_f32 v46, -v40, v92, v46
	ds_read_b128 v[48:51], v65 offset:46848
	ds_read_b128 v[52:55], v65 offset:46864
	v_fmac_f32_e32 v57, 0x80000000, v99
	v_fmac_f32_e32 v56, 0x80000000, v98
	v_fma_f32 v47, -v97, v45, v47
	v_fma_f32 v46, -v44, v96, v46
	v_add_f32_e32 v46, v47, v46
	v_add_f32_e32 v47, v56, v57
	ds_read_b128 v[56:59], v65 offset:46880
	v_add_f32_e32 v46, v47, v46
	s_waitcnt lgkmcnt(2)
	v_fma_f32 v47, -v3, v51, 0
	ds_read_b128 v[68:71], v65 offset:46896
	ds_read_b128 v[72:75], v65 offset:46912
	ds_read_b128 v[76:79], v65 offset:46928
	v_fma_f32 v50, -v2, v50, 0
	v_fma_f32 v49, -v1, v49, 0
	v_fma_f32 v48, -v0, v48, v61
	s_waitcnt lgkmcnt(4)
	v_fma_f32 v47, -v7, v55, v47
	ds_read_b128 v[80:83], v65 offset:46944
	ds_read_b128 v[84:87], v65 offset:46960
	v_fma_f32 v50, -v6, v54, v50
	v_fma_f32 v49, -v5, v53, v49
	v_fma_f32 v48, -v4, v52, v48
	s_waitcnt lgkmcnt(5)
	v_fma_f32 v47, -v11, v59, v47
	v_fma_f32 v50, -v10, v58, v50
	v_fma_f32 v49, -v9, v57, v49
	v_fma_f32 v48, -v8, v56, v48
	s_waitcnt lgkmcnt(4)
	v_fma_f32 v47, -v15, v71, v47
	v_fma_f32 v50, -v14, v70, v50
	v_fma_f32 v49, -v13, v69, v49
	v_fma_f32 v48, -v12, v68, v48
	s_waitcnt lgkmcnt(3)
	v_fma_f32 v47, -v19, v75, v47
	v_fma_f32 v50, -v18, v74, v50
	v_fma_f32 v49, -v17, v73, v49
	v_fma_f32 v48, -v16, v72, v48
	s_waitcnt lgkmcnt(2)
	v_fma_f32 v47, -v23, v79, v47
	v_fma_f32 v50, -v22, v78, v50
	v_fma_f32 v49, -v21, v77, v49
	v_fma_f32 v48, -v20, v76, v48
	s_waitcnt lgkmcnt(1)
	v_fma_f32 v47, -v27, v83, v47
	ds_read_b128 v[88:91], v65 offset:46976
	ds_read_b128 v[92:95], v65 offset:46992
	ds_read_b128 v[96:99], v65 offset:47008
	ds_read_b128 v[100:103], v65 offset:47024
	v_fma_f32 v50, -v26, v82, v50
	v_fma_f32 v49, -v25, v81, v49
	v_fma_f32 v48, -v24, v80, v48
	s_waitcnt lgkmcnt(4)
	v_fma_f32 v47, -v31, v87, v47
	v_fma_f32 v50, -v30, v86, v50
	v_fma_f32 v49, -v29, v85, v49
	v_fma_f32 v48, -v28, v84, v48
	s_waitcnt lgkmcnt(3)
	v_fma_f32 v47, -v35, v91, v47
	v_fma_f32 v50, -v34, v90, v50
	v_fma_f32 v49, -v33, v89, v49
	v_fma_f32 v48, -v32, v88, v48
	s_waitcnt lgkmcnt(2)
	v_fma_f32 v47, -v39, v95, v47
	v_fma_f32 v50, -v38, v94, v50
	v_fma_f32 v49, -v37, v93, v49
	v_fma_f32 v48, -v36, v92, v48
	s_waitcnt lgkmcnt(1)
	v_fma_f32 v47, -v43, v99, v47
	v_fma_f32 v50, -v42, v98, v50
	v_fma_f32 v49, -v41, v97, v49
	v_fma_f32 v48, -v40, v96, v48
	s_waitcnt lgkmcnt(0)
	v_fmac_f32_e32 v47, 0x80000000, v103
	v_fma_f32 v58, -v102, v46, v50
	v_fma_f32 v53, -v45, v101, v49
	v_fma_f32 v52, -v44, v100, v48
	v_add_f32_e32 v56, v53, v52
	v_add_f32_e32 v47, v47, v58
	ds_read_b128 v[48:51], v65 offset:47104
	ds_read_b128 v[52:55], v65 offset:47120
	v_add_f32_e32 v47, v47, v56
	ds_read_b128 v[56:59], v65 offset:47136
	ds_read_b128 v[68:71], v65 offset:47152
	ds_read_b128 v[72:75], v65 offset:47168
	ds_read_b128 v[76:79], v65 offset:47184
	ds_read_b128 v[80:83], v65 offset:47200
	ds_read_b128 v[84:87], v65 offset:47216
	ds_read_b128 v[88:91], v65 offset:47232
	ds_read_b128 v[92:95], v65 offset:47248
	ds_read_b128 v[96:99], v65 offset:47264
	ds_read_b128 v[100:103], v65 offset:47280
	ds_read2st64_b32 v[112:113], v62 offset0:192 offset1:196
	s_waitcnt lgkmcnt(12)
	v_fma_f32 v51, -v3, v51, 0
	v_fma_f32 v50, -v2, v50, 0
	v_fma_f32 v49, -v1, v49, 0
	s_waitcnt lgkmcnt(11)
	v_fma_f32 v51, -v7, v55, v51
	s_waitcnt lgkmcnt(0)
; #define LAS __attribute__((address_space(3)))
; __device__ __forceinline__ void phase_chunk_prep(const Params& p, LAS unsigned char* lds, int wave_s) {
;     ...
;             for (int i = 0; i < 64; ++i) {
;                 float s0 = RHS[i * 256 + col], s1 = 0.f, s2 = 0.f, s3 = 0.f;
; #pragma unroll
;                 for (int j4 = 0; j4 < (i + 3) / 4; ++j4) { const f32x4 a = *(const LAS f32x4*)(AM + i * 64 + 4 * j4);
;                     s0 -= a.x * sol[4 * j4]; s1 -= a.y * sol[4 * j4 + 1]; s2 -= a.z * sol[4 * j4 + 2]; s3 -= a.w * sol[4 * j4 + 3]; }
;                 sol[i] = (s0 + s1) + (s2 + s3);
	v_fma_f32 v48, -v0, v48, v112
	v_fma_f32 v50, -v6, v54, v50
	v_fma_f32 v49, -v5, v53, v49
	v_fma_f32 v48, -v4, v52, v48
	v_fma_f32 v51, -v11, v59, v51
	v_fma_f32 v50, -v10, v58, v50
	v_fma_f32 v49, -v9, v57, v49
	v_fma_f32 v48, -v8, v56, v48
	v_fma_f32 v51, -v15, v71, v51
	v_fma_f32 v50, -v14, v70, v50
	v_fma_f32 v49, -v13, v69, v49
	v_fma_f32 v48, -v12, v68, v48
	v_fma_f32 v51, -v19, v75, v51
	v_fma_f32 v50, -v18, v74, v50
	v_fma_f32 v49, -v17, v73, v49
	v_fma_f32 v48, -v16, v72, v48
	v_fma_f32 v51, -v23, v79, v51
	v_fma_f32 v50, -v22, v78, v50
	v_fma_f32 v49, -v21, v77, v49
	v_fma_f32 v48, -v20, v76, v48
	v_fma_f32 v51, -v27, v83, v51
	v_fma_f32 v50, -v26, v82, v50
	v_fma_f32 v49, -v25, v81, v49
	v_fma_f32 v48, -v24, v80, v48
	v_fma_f32 v51, -v31, v87, v51
	v_fma_f32 v50, -v30, v86, v50
	v_fma_f32 v49, -v29, v85, v49
	v_fma_f32 v48, -v28, v84, v48
	v_fma_f32 v51, -v35, v91, v51
	v_fma_f32 v50, -v34, v90, v50
	v_fma_f32 v49, -v33, v89, v49
	v_fma_f32 v48, -v32, v88, v48
	v_fma_f32 v51, -v39, v95, v51
	v_fma_f32 v50, -v38, v94, v50
	v_fma_f32 v49, -v37, v93, v49
	v_fma_f32 v48, -v36, v92, v48
	v_fma_f32 v51, -v43, v99, v51
	v_fma_f32 v50, -v42, v98, v50
	v_fma_f32 v49, -v41, v97, v49
	v_fma_f32 v48, -v40, v96, v48
	v_fma_f32 v59, -v103, v47, v51
	v_fma_f32 v58, -v46, v102, v50
	v_fma_f32 v49, -v45, v101, v49
	v_fma_f32 v48, -v44, v100, v48
	ds_read_b128 v[50:53], v65 offset:47360
	ds_read_b128 v[54:57], v65 offset:47376
	v_add_f32_e32 v48, v49, v48
	v_add_f32_e32 v49, v58, v59
	ds_read_b128 v[58:61], v65 offset:47392
	ds_read_b128 v[68:71], v65 offset:47408
	s_waitcnt lgkmcnt(3)
	v_fma_f32 v51, -v1, v51, 0
	v_fma_f32 v50, -v0, v50, v113
	ds_read_b128 v[72:75], v65 offset:47424
	ds_read_b128 v[76:79], v65 offset:47440
	ds_read_b128 v[80:83], v65 offset:47456
	s_waitcnt lgkmcnt(5)
	v_fma_f32 v51, -v5, v55, v51
	v_fma_f32 v50, -v4, v54, v50
	ds_read_b128 v[84:87], v65 offset:47472
	ds_read_b128 v[88:91], v65 offset:47488
	v_fma_f32 v52, -v2, v52, 0
	s_waitcnt lgkmcnt(6)
	v_fma_f32 v51, -v9, v59, v51
	v_fma_f32 v50, -v8, v58, v50
	v_add_f32_e32 v48, v49, v48
	v_fma_f32 v49, -v3, v53, 0
	v_fma_f32 v52, -v6, v56, v52
	s_waitcnt lgkmcnt(5)
	v_fma_f32 v51, -v13, v69, v51
	v_fma_f32 v50, -v12, v68, v50
	v_fma_f32 v49, -v7, v57, v49
	v_fma_f32 v52, -v10, v60, v52
	s_waitcnt lgkmcnt(4)
	v_fma_f32 v51, -v17, v73, v51
	v_fma_f32 v50, -v16, v72, v50
	v_fma_f32 v49, -v11, v61, v49
	v_fma_f32 v52, -v14, v70, v52
	s_waitcnt lgkmcnt(3)
	v_fma_f32 v51, -v21, v77, v51
	v_fma_f32 v50, -v20, v76, v50
	v_fma_f32 v49, -v15, v71, v49
	ds_read_b128 v[92:95], v65 offset:47504
	ds_read_b128 v[96:99], v65 offset:47520
	ds_read_b128 v[100:103], v65 offset:47536
	v_fma_f32 v52, -v18, v74, v52
	s_waitcnt lgkmcnt(5)
	v_fma_f32 v51, -v25, v81, v51
	v_fma_f32 v50, -v24, v80, v50
	v_fma_f32 v49, -v19, v75, v49
	ds_read_b128 v[104:107], v65 offset:47552
	ds_read_b128 v[108:111], v65 offset:47616
	v_fma_f32 v52, -v22, v78, v52
	s_waitcnt lgkmcnt(6)
	v_fma_f32 v51, -v29, v85, v51
	v_fma_f32 v50, -v28, v84, v50
	v_fma_f32 v49, -v23, v79, v49
	v_fma_f32 v52, -v26, v82, v52
	s_waitcnt lgkmcnt(5)
	v_fma_f32 v51, -v33, v89, v51
	v_fma_f32 v50, -v32, v88, v50
	v_fma_f32 v49, -v27, v83, v49
	v_fma_f32 v52, -v30, v86, v52
	s_waitcnt lgkmcnt(4)
	v_fma_f32 v51, -v37, v93, v51
	v_fma_f32 v50, -v36, v92, v50
	v_fma_f32 v49, -v31, v87, v49
	v_fma_f32 v52, -v34, v90, v52
	s_waitcnt lgkmcnt(3)
	v_fma_f32 v51, -v41, v97, v51
	v_fma_f32 v50, -v40, v96, v50
	v_fma_f32 v49, -v35, v91, v49
	v_fma_f32 v52, -v38, v94, v52
	s_waitcnt lgkmcnt(2)
	v_fma_f32 v51, -v45, v101, v51
	v_fma_f32 v50, -v44, v100, v50
	v_fma_f32 v49, -v39, v95, v49
	v_fma_f32 v52, -v42, v98, v52
	s_waitcnt lgkmcnt(1)
	v_fmac_f32_e32 v51, 0x80000000, v105
	v_fma_f32 v50, -v104, v48, v50
	v_fma_f32 v49, -v43, v99, v49
	v_fma_f32 v56, -v46, v102, v52
	v_add_f32_e32 v58, v51, v50
	ds_read_b128 v[50:53], v65 offset:47632
	v_fma_f32 v49, -v47, v103, v49
	v_fmac_f32_e32 v49, 0x80000000, v107
	v_fmac_f32_e32 v56, 0x80000000, v106
	v_add_f32_e32 v49, v56, v49
	ds_read_b128 v[54:57], v65 offset:47648
	v_add_f32_e32 v49, v49, v58
	s_waitcnt lgkmcnt(2)
	v_fma_f32 v58, -v3, v111, 0
	s_waitcnt lgkmcnt(1)
	v_fma_f32 v53, -v7, v53, v58
	ds_read_b128 v[58:61], v65 offset:47664
	ds_read_b128 v[68:71], v65 offset:47680
	ds_read_b128 v[72:75], v65 offset:47696
	ds_read_b128 v[76:79], v65 offset:47712
	s_waitcnt lgkmcnt(4)
	v_fma_f32 v53, -v11, v57, v53
	ds_read_b128 v[80:83], v65 offset:47728
	ds_read_b128 v[84:87], v65 offset:47744
	s_waitcnt lgkmcnt(5)
	v_fma_f32 v53, -v15, v61, v53
	s_waitcnt lgkmcnt(4)
	v_fma_f32 v53, -v19, v71, v53
	s_waitcnt lgkmcnt(3)
	v_fma_f32 v53, -v23, v75, v53
	s_waitcnt lgkmcnt(2)
	v_fma_f32 v53, -v27, v79, v53
	s_waitcnt lgkmcnt(1)
	v_fma_f32 v53, -v31, v83, v53
	ds_read_b128 v[88:91], v65 offset:47760
	ds_read_b128 v[92:95], v65 offset:47776
	ds_read_b128 v[96:99], v65 offset:47792
	ds_read_b128 v[100:103], v65 offset:47808
	s_waitcnt lgkmcnt(4)
	v_fma_f32 v53, -v35, v87, v53
	s_waitcnt lgkmcnt(3)
	v_fma_f32 v53, -v39, v91, v53
	s_waitcnt lgkmcnt(2)
	v_fma_f32 v53, -v43, v95, v53
	s_waitcnt lgkmcnt(1)
	v_fma_f32 v63, -v47, v99, v53
	v_fma_f32 v53, -v2, v110, 0
	v_fma_f32 v52, -v6, v52, v53
	v_fma_f32 v52, -v10, v56, v52
	v_fma_f32 v52, -v14, v60, v52
	v_fma_f32 v52, -v18, v70, v52
	v_fma_f32 v52, -v22, v74, v52
	v_fma_f32 v52, -v26, v78, v52
	v_fma_f32 v52, -v30, v82, v52
	ds_read2st64_b32 v[60:61], v62 offset0:200 offset1:204
	v_fma_f32 v52, -v34, v86, v52
	v_fma_f32 v52, -v38, v90, v52
	v_fma_f32 v52, -v42, v94, v52
	v_fma_f32 v70, -v46, v98, v52
	v_fma_f32 v52, -v1, v109, 0
	v_fma_f32 v51, -v5, v51, v52
	s_waitcnt lgkmcnt(0)
; #define LAS __attribute__((address_space(3)))
; __device__ __forceinline__ void phase_chunk_prep(const Params& p, LAS unsigned char* lds, int wave_s) {
;     ...
;             for (int i = 0; i < 64; ++i) {
;                 float s0 = RHS[i * 256 + col], s1 = 0.f, s2 = 0.f, s3 = 0.f;
; #pragma unroll
;                 for (int j4 = 0; j4 < (i + 3) / 4; ++j4) { const f32x4 a = *(const LAS f32x4*)(AM + i * 64 + 4 * j4);
;                     s0 -= a.x * sol[4 * j4]; s1 -= a.y * sol[4 * j4 + 1]; s2 -= a.z * sol[4 * j4 + 2]; s3 -= a.w * sol[4 * j4 + 3]; }
;                 sol[i] = (s0 + s1) + (s2 + s3);
	v_fma_f32 v52, -v0, v108, v60
	v_fma_f32 v50, -v4, v50, v52
	v_fma_f32 v51, -v9, v55, v51
	v_fma_f32 v50, -v8, v54, v50
	v_fma_f32 v51, -v13, v59, v51
	v_fma_f32 v50, -v12, v58, v50
	v_fma_f32 v51, -v17, v69, v51
	v_fma_f32 v50, -v16, v68, v50
	v_fma_f32 v51, -v21, v73, v51
	v_fma_f32 v50, -v20, v72, v50
	v_fma_f32 v51, -v25, v77, v51
	v_fma_f32 v50, -v24, v76, v50
	v_fma_f32 v51, -v29, v81, v51
	v_fma_f32 v50, -v28, v80, v50
	v_fma_f32 v51, -v33, v85, v51
	v_fma_f32 v50, -v32, v84, v50
	v_fma_f32 v51, -v37, v89, v51
	v_fma_f32 v50, -v36, v88, v50
	v_fma_f32 v51, -v41, v93, v51
	v_fma_f32 v50, -v40, v92, v50
	v_fma_f32 v51, -v45, v97, v51
	v_fma_f32 v50, -v44, v96, v50
	v_fmac_f32_e32 v63, 0x80000000, v103
	v_fmac_f32_e32 v70, 0x80000000, v102
	v_fma_f32 v51, -v101, v49, v51
	v_fma_f32 v50, -v48, v100, v50
	ds_read_b128 v[52:55], v65 offset:47872
	ds_read_b128 v[56:59], v65 offset:47888
	v_add_f32_e32 v50, v51, v50
	v_add_f32_e32 v51, v70, v63
	ds_read_b128 v[68:71], v65 offset:47904
	ds_read_b128 v[72:75], v65 offset:47920
	s_waitcnt lgkmcnt(3)
	v_fma_f32 v53, -v1, v53, 0
	v_fma_f32 v52, -v0, v52, v61
	v_add_f32_e32 v50, v51, v50
	v_fma_f32 v51, -v3, v55, 0
	ds_read_b128 v[76:79], v65 offset:47936
	ds_read_b128 v[80:83], v65 offset:47952
	ds_read_b128 v[84:87], v65 offset:47968
	v_fma_f32 v54, -v2, v54, 0
	s_waitcnt lgkmcnt(5)
	v_fma_f32 v53, -v5, v57, v53
	v_fma_f32 v52, -v4, v56, v52
	v_fma_f32 v51, -v7, v59, v51
	ds_read_b128 v[88:91], v65 offset:47984
	ds_read_b128 v[92:95], v65 offset:48000
	v_fma_f32 v54, -v6, v58, v54
	s_waitcnt lgkmcnt(6)
	v_fma_f32 v53, -v9, v69, v53
	v_fma_f32 v52, -v8, v68, v52
	v_fma_f32 v51, -v11, v71, v51
	v_fma_f32 v54, -v10, v70, v54
	s_waitcnt lgkmcnt(5)
	v_fma_f32 v53, -v13, v73, v53
	v_fma_f32 v52, -v12, v72, v52
	v_fma_f32 v51, -v15, v75, v51
	v_fma_f32 v54, -v14, v74, v54
	s_waitcnt lgkmcnt(4)
	v_fma_f32 v53, -v17, v77, v53
	v_fma_f32 v52, -v16, v76, v52
	v_fma_f32 v51, -v19, v79, v51
	v_fma_f32 v54, -v18, v78, v54
	s_waitcnt lgkmcnt(3)
	v_fma_f32 v53, -v21, v81, v53
	v_fma_f32 v52, -v20, v80, v52
	v_fma_f32 v51, -v23, v83, v51
	ds_read_b128 v[96:99], v65 offset:48016
	ds_read_b128 v[100:103], v65 offset:48032
	ds_read_b128 v[104:107], v65 offset:48048
	v_fma_f32 v54, -v22, v82, v54
	s_waitcnt lgkmcnt(5)
	v_fma_f32 v53, -v25, v85, v53
	v_fma_f32 v52, -v24, v84, v52
	v_fma_f32 v51, -v27, v87, v51
	ds_read_b128 v[108:111], v65 offset:48064
	ds_read_b128 v[112:115], v65 offset:48128
	v_fma_f32 v54, -v26, v86, v54
	s_waitcnt lgkmcnt(6)
	v_fma_f32 v53, -v29, v89, v53
	v_fma_f32 v52, -v28, v88, v52
	v_fma_f32 v51, -v31, v91, v51
	v_fma_f32 v54, -v30, v90, v54
	s_waitcnt lgkmcnt(5)
	v_fma_f32 v53, -v33, v93, v53
	v_fma_f32 v52, -v32, v92, v52
	v_fma_f32 v51, -v35, v95, v51
	v_fma_f32 v54, -v34, v94, v54
	s_waitcnt lgkmcnt(4)
	v_fma_f32 v53, -v37, v97, v53
	v_fma_f32 v52, -v36, v96, v52
	v_fma_f32 v51, -v39, v99, v51
	v_fma_f32 v54, -v38, v98, v54
	s_waitcnt lgkmcnt(3)
	v_fma_f32 v53, -v41, v101, v53
	v_fma_f32 v52, -v40, v100, v52
	v_fma_f32 v51, -v43, v103, v51
	v_fma_f32 v54, -v42, v102, v54
	s_waitcnt lgkmcnt(2)
	v_fma_f32 v53, -v45, v105, v53
	v_fma_f32 v52, -v44, v104, v52
	v_fma_f32 v51, -v47, v107, v51
	v_fma_f32 v54, -v46, v106, v54
	s_waitcnt lgkmcnt(1)
	v_fma_f32 v53, -v49, v109, v53
	v_fma_f32 v52, -v48, v108, v52
	v_fmac_f32_e32 v51, 0x80000000, v111
	v_fma_f32 v58, -v110, v50, v54
	v_add_f32_e32 v60, v53, v52
	ds_read_b128 v[52:55], v65 offset:48144
	v_add_f32_e32 v51, v51, v58
	ds_read_b128 v[56:59], v65 offset:48160
	v_add_f32_e32 v51, v51, v60
	s_waitcnt lgkmcnt(2)
	v_fma_f32 v60, -v3, v115, 0
	s_waitcnt lgkmcnt(1)
	v_fma_f32 v55, -v7, v55, v60
	ds_read_b128 v[68:71], v65 offset:48176
	ds_read_b128 v[72:75], v65 offset:48192
	ds_read_b128 v[76:79], v65 offset:48208
	ds_read_b128 v[80:83], v65 offset:48224
	ds_read_b128 v[84:87], v65 offset:48240
	ds_read_b128 v[88:91], v65 offset:48256
	ds_read_b128 v[92:95], v65 offset:48272
	ds_read_b128 v[96:99], v65 offset:48288
	ds_read_b128 v[100:103], v65 offset:48304
	ds_read_b128 v[104:107], v65 offset:48320
	ds_read2st64_b32 v[116:117], v62 offset0:208 offset1:212
	s_waitcnt lgkmcnt(11)
	v_fma_f32 v55, -v11, v59, v55
	v_fma_f32 v59, -v2, v114, 0
	v_fma_f32 v54, -v6, v54, v59
	v_fma_f32 v54, -v10, v58, v54
	v_fma_f32 v58, -v1, v113, 0
	v_fma_f32 v53, -v5, v53, v58
	v_fma_f32 v53, -v9, v57, v53
	s_waitcnt lgkmcnt(0)
	v_fma_f32 v57, -v0, v112, v116
	v_fma_f32 v52, -v4, v52, v57
	v_fma_f32 v52, -v8, v56, v52
	v_fma_f32 v55, -v15, v71, v55
	v_fma_f32 v54, -v14, v70, v54
	v_fma_f32 v53, -v13, v69, v53
	v_fma_f32 v52, -v12, v68, v52
	v_fma_f32 v55, -v19, v75, v55
	v_fma_f32 v54, -v18, v74, v54
	v_fma_f32 v53, -v17, v73, v53
	v_fma_f32 v52, -v16, v72, v52
	v_fma_f32 v55, -v23, v79, v55
	v_fma_f32 v54, -v22, v78, v54
	v_fma_f32 v53, -v21, v77, v53
	v_fma_f32 v52, -v20, v76, v52
	v_fma_f32 v55, -v27, v83, v55
	v_fma_f32 v54, -v26, v82, v54
	v_fma_f32 v53, -v25, v81, v53
	v_fma_f32 v52, -v24, v80, v52
	v_fma_f32 v55, -v31, v87, v55
	v_fma_f32 v54, -v30, v86, v54
	v_fma_f32 v53, -v29, v85, v53
	v_fma_f32 v52, -v28, v84, v52
	v_fma_f32 v55, -v35, v91, v55
	v_fma_f32 v54, -v34, v90, v54
	v_fma_f32 v53, -v33, v89, v53
	v_fma_f32 v52, -v32, v88, v52
	v_fma_f32 v55, -v39, v95, v55
	v_fma_f32 v54, -v38, v94, v54
	v_fma_f32 v53, -v37, v93, v53
	v_fma_f32 v52, -v36, v92, v52
	v_fma_f32 v55, -v43, v99, v55
	v_fma_f32 v54, -v42, v98, v54
	v_fma_f32 v53, -v41, v97, v53
	v_fma_f32 v52, -v40, v96, v52
	v_fma_f32 v55, -v47, v103, v55
	v_fma_f32 v54, -v46, v102, v54
	v_fma_f32 v53, -v45, v101, v53
	v_fma_f32 v52, -v44, v100, v52
	v_fma_f32 v55, -v107, v51, v55
	v_fma_f32 v54, -v50, v106, v54
	v_fma_f32 v53, -v49, v105, v53
	v_fma_f32 v52, -v48, v104, v52
	v_add_f32_e32 v52, v53, v52
	v_add_f32_e32 v53, v54, v55
	ds_read_b128 v[54:57], v65 offset:48384
	ds_read_b128 v[58:61], v65 offset:48400
	ds_read_b128 v[68:71], v65 offset:48416
	ds_read_b128 v[72:75], v65 offset:48432
	ds_read_b128 v[76:79], v65 offset:48448
	v_add_f32_e32 v52, v53, v52
	s_waitcnt lgkmcnt(4)
; #define LAS __attribute__((address_space(3)))
; __device__ __forceinline__ void phase_chunk_prep(const Params& p, LAS unsigned char* lds, int wave_s) {
;     ...
;             for (int i = 0; i < 64; ++i) {
;                 float s0 = RHS[i * 256 + col], s1 = 0.f, s2 = 0.f, s3 = 0.f;
; #pragma unroll
;                 for (int j4 = 0; j4 < (i + 3) / 4; ++j4) { const f32x4 a = *(const LAS f32x4*)(AM + i * 64 + 4 * j4);
;                     s0 -= a.x * sol[4 * j4]; s1 -= a.y * sol[4 * j4 + 1]; s2 -= a.z * sol[4 * j4 + 2]; s3 -= a.w * sol[4 * j4 + 3]; }
;                 sol[i] = (s0 + s1) + (s2 + s3);
	v_fma_f32 v53, -v3, v57, 0
	v_fma_f32 v56, -v2, v56, 0
	v_fma_f32 v55, -v1, v55, 0
	v_fma_f32 v54, -v0, v54, v117
	s_waitcnt lgkmcnt(3)
	v_fma_f32 v53, -v7, v61, v53
	v_fma_f32 v56, -v6, v60, v56
	v_fma_f32 v55, -v5, v59, v55
	v_fma_f32 v54, -v4, v58, v54
	s_waitcnt lgkmcnt(2)
	v_fma_f32 v53, -v11, v71, v53
	ds_read_b128 v[80:83], v65 offset:48464
	ds_read_b128 v[84:87], v65 offset:48480
	ds_read_b128 v[88:91], v65 offset:48496
	v_fma_f32 v56, -v10, v70, v56
	v_fma_f32 v55, -v9, v69, v55
	v_fma_f32 v54, -v8, v68, v54
	s_waitcnt lgkmcnt(4)
	v_fma_f32 v53, -v15, v75, v53
	ds_read_b128 v[92:95], v65 offset:48512
	ds_read_b128 v[96:99], v65 offset:48528
	v_fma_f32 v56, -v14, v74, v56
	v_fma_f32 v55, -v13, v73, v55
	v_fma_f32 v54, -v12, v72, v54
	s_waitcnt lgkmcnt(5)
	v_fma_f32 v53, -v19, v79, v53
	v_fma_f32 v56, -v18, v78, v56
	v_fma_f32 v55, -v17, v77, v55
	v_fma_f32 v54, -v16, v76, v54
	s_waitcnt lgkmcnt(4)
	v_fma_f32 v53, -v23, v83, v53
	v_fma_f32 v56, -v22, v82, v56
	v_fma_f32 v55, -v21, v81, v55
	v_fma_f32 v54, -v20, v80, v54
	s_waitcnt lgkmcnt(3)
	v_fma_f32 v53, -v27, v87, v53
	v_fma_f32 v56, -v26, v86, v56
	v_fma_f32 v55, -v25, v85, v55
	v_fma_f32 v54, -v24, v84, v54
	s_waitcnt lgkmcnt(2)
	v_fma_f32 v53, -v31, v91, v53
	v_fma_f32 v56, -v30, v90, v56
	v_fma_f32 v55, -v29, v89, v55
	v_fma_f32 v54, -v28, v88, v54
	s_waitcnt lgkmcnt(1)
	v_fma_f32 v53, -v35, v95, v53
	ds_read_b128 v[100:103], v65 offset:48544
	ds_read_b128 v[104:107], v65 offset:48560
	ds_read_b128 v[108:111], v65 offset:48576
	ds_read_b128 v[112:115], v65 offset:48592
	v_fma_f32 v56, -v34, v94, v56
	v_fma_f32 v55, -v33, v93, v55
	v_fma_f32 v54, -v32, v92, v54
	s_waitcnt lgkmcnt(4)
	v_fma_f32 v53, -v39, v99, v53
	v_fma_f32 v56, -v38, v98, v56
	v_fma_f32 v55, -v37, v97, v55
	v_fma_f32 v54, -v36, v96, v54
	s_waitcnt lgkmcnt(3)
	v_fma_f32 v53, -v43, v103, v53
	v_fma_f32 v56, -v42, v102, v56
	v_fma_f32 v55, -v41, v101, v55
	v_fma_f32 v54, -v40, v100, v54
	s_waitcnt lgkmcnt(2)
	v_fma_f32 v53, -v47, v107, v53
	v_fma_f32 v56, -v46, v106, v56
	v_fma_f32 v55, -v45, v105, v55
	v_fma_f32 v54, -v44, v104, v54
	s_waitcnt lgkmcnt(1)
	v_fma_f32 v53, -v51, v111, v53
	v_fma_f32 v56, -v50, v110, v56
	v_fma_f32 v55, -v49, v109, v55
	v_fma_f32 v54, -v48, v108, v54
	s_waitcnt lgkmcnt(0)
	v_fmac_f32_e32 v53, 0x80000000, v115
	v_fmac_f32_e32 v56, 0x80000000, v114
	v_fmac_f32_e32 v55, 0x80000000, v113
	v_fma_f32 v54, -v112, v52, v54
	v_add_f32_e32 v63, v55, v54
	v_add_f32_e32 v53, v56, v53
	ds_read_b128 v[54:57], v65 offset:48640
	ds_read_b128 v[58:61], v65 offset:48656
	ds_read_b128 v[68:71], v65 offset:48672
	ds_read_b128 v[72:75], v65 offset:48688
	ds_read_b128 v[76:79], v65 offset:48704
	s_waitcnt lgkmcnt(4)
	v_fma_f32 v57, -v3, v57, 0
	v_fma_f32 v56, -v2, v56, 0
	s_waitcnt lgkmcnt(3)
	v_fma_f32 v57, -v7, v61, v57
	ds_read_b128 v[80:83], v65 offset:48720
	ds_read_b128 v[84:87], v65 offset:48736
	ds_read_b128 v[88:91], v65 offset:48752
	ds_read_b128 v[92:95], v65 offset:48768
	ds_read_b128 v[96:99], v65 offset:48784
	ds_read_b128 v[100:103], v65 offset:48800
	ds_read_b128 v[104:107], v65 offset:48816
	ds_read_b128 v[108:111], v65 offset:48832
	ds_read_b128 v[112:115], v65 offset:48848
	v_fma_f32 v56, -v6, v60, v56
	ds_read2st64_b32 v[60:61], v62 offset0:216 offset1:220
	v_fma_f32 v55, -v1, v55, 0
	v_fma_f32 v55, -v5, v59, v55
	s_waitcnt lgkmcnt(12)
	v_fma_f32 v57, -v11, v71, v57
	v_fma_f32 v56, -v10, v70, v56
	s_waitcnt lgkmcnt(0)
	v_fma_f32 v54, -v0, v54, v60
	v_fma_f32 v54, -v4, v58, v54
	v_fma_f32 v55, -v9, v69, v55
	v_fma_f32 v54, -v8, v68, v54
	v_fma_f32 v57, -v15, v75, v57
	v_fma_f32 v56, -v14, v74, v56
	v_fma_f32 v55, -v13, v73, v55
	v_fma_f32 v54, -v12, v72, v54
	v_fma_f32 v57, -v19, v79, v57
	v_fma_f32 v56, -v18, v78, v56
	v_fma_f32 v55, -v17, v77, v55
	v_fma_f32 v54, -v16, v76, v54
	v_fma_f32 v57, -v23, v83, v57
	v_fma_f32 v56, -v22, v82, v56
	v_fma_f32 v55, -v21, v81, v55
	v_fma_f32 v54, -v20, v80, v54
	v_fma_f32 v57, -v27, v87, v57
	v_fma_f32 v56, -v26, v86, v56
	v_fma_f32 v55, -v25, v85, v55
	v_fma_f32 v54, -v24, v84, v54
	v_fma_f32 v57, -v31, v91, v57
	v_fma_f32 v56, -v30, v90, v56
	v_fma_f32 v55, -v29, v89, v55
	v_fma_f32 v54, -v28, v88, v54
	v_fma_f32 v57, -v35, v95, v57
	v_fma_f32 v56, -v34, v94, v56
	v_fma_f32 v55, -v33, v93, v55
	v_fma_f32 v54, -v32, v92, v54
	v_fma_f32 v57, -v39, v99, v57
	v_fma_f32 v56, -v38, v98, v56
	v_fma_f32 v55, -v37, v97, v55
	v_fma_f32 v54, -v36, v96, v54
	v_fma_f32 v57, -v43, v103, v57
	v_fma_f32 v56, -v42, v102, v56
	v_fma_f32 v55, -v41, v101, v55
	v_fma_f32 v54, -v40, v100, v54
	v_fma_f32 v57, -v47, v107, v57
	v_fma_f32 v56, -v46, v106, v56
	v_fma_f32 v55, -v45, v105, v55
	v_fma_f32 v54, -v44, v104, v54
	v_add_f32_e32 v53, v53, v63
	v_fma_f32 v57, -v51, v111, v57
	v_fma_f32 v56, -v50, v110, v56
	v_fma_f32 v55, -v49, v109, v55
	v_fma_f32 v54, -v48, v108, v54
	v_fmac_f32_e32 v57, 0x80000000, v115
	v_fmac_f32_e32 v56, 0x80000000, v114
	v_fma_f32 v55, -v113, v53, v55
	v_fma_f32 v54, -v52, v112, v54
	v_add_f32_e32 v54, v55, v54
	v_add_f32_e32 v55, v56, v57
	ds_read_b128 v[56:59], v65 offset:48896
	ds_read_b128 v[68:71], v65 offset:48912
	ds_read_b128 v[72:75], v65 offset:48928
	ds_read_b128 v[76:79], v65 offset:48944
	ds_read_b128 v[80:83], v65 offset:48960
	v_add_f32_e32 v54, v55, v54
	s_waitcnt lgkmcnt(4)
	v_fma_f32 v55, -v3, v59, 0
	v_fma_f32 v58, -v2, v58, 0
	v_fma_f32 v57, -v1, v57, 0
	v_fma_f32 v56, -v0, v56, v61
	s_waitcnt lgkmcnt(3)
	v_fma_f32 v55, -v7, v71, v55
	v_fma_f32 v58, -v6, v70, v58
	v_fma_f32 v57, -v5, v69, v57
	v_fma_f32 v56, -v4, v68, v56
	s_waitcnt lgkmcnt(2)
; #define LAS __attribute__((address_space(3)))
; __device__ __forceinline__ void phase_chunk_prep(const Params& p, LAS unsigned char* lds, int wave_s) {
;     ...
;             for (int i = 0; i < 64; ++i) {
;                 float s0 = RHS[i * 256 + col], s1 = 0.f, s2 = 0.f, s3 = 0.f;
; #pragma unroll
;                 for (int j4 = 0; j4 < (i + 3) / 4; ++j4) { const f32x4 a = *(const LAS f32x4*)(AM + i * 64 + 4 * j4);
;                     s0 -= a.x * sol[4 * j4]; s1 -= a.y * sol[4 * j4 + 1]; s2 -= a.z * sol[4 * j4 + 2]; s3 -= a.w * sol[4 * j4 + 3]; }
;                 sol[i] = (s0 + s1) + (s2 + s3);
	v_fma_f32 v55, -v11, v75, v55
	ds_read_b128 v[84:87], v65 offset:48976
	ds_read_b128 v[88:91], v65 offset:48992
	ds_read_b128 v[92:95], v65 offset:49008
	v_fma_f32 v58, -v10, v74, v58
	v_fma_f32 v57, -v9, v73, v57
	v_fma_f32 v56, -v8, v72, v56
	s_waitcnt lgkmcnt(4)
	v_fma_f32 v55, -v15, v79, v55
	ds_read_b128 v[96:99], v65 offset:49024
	ds_read_b128 v[100:103], v65 offset:49040
	v_fma_f32 v58, -v14, v78, v58
	v_fma_f32 v57, -v13, v77, v57
	v_fma_f32 v56, -v12, v76, v56
	s_waitcnt lgkmcnt(5)
	v_fma_f32 v55, -v19, v83, v55
	v_fma_f32 v58, -v18, v82, v58
	v_fma_f32 v57, -v17, v81, v57
	v_fma_f32 v56, -v16, v80, v56
	s_waitcnt lgkmcnt(4)
	v_fma_f32 v55, -v23, v87, v55
	v_fma_f32 v58, -v22, v86, v58
	v_fma_f32 v57, -v21, v85, v57
	v_fma_f32 v56, -v20, v84, v56
	s_waitcnt lgkmcnt(3)
	v_fma_f32 v55, -v27, v91, v55
	v_fma_f32 v58, -v26, v90, v58
	v_fma_f32 v57, -v25, v89, v57
	v_fma_f32 v56, -v24, v88, v56
	s_waitcnt lgkmcnt(2)
	v_fma_f32 v55, -v31, v95, v55
	v_fma_f32 v58, -v30, v94, v58
	v_fma_f32 v57, -v29, v93, v57
	v_fma_f32 v56, -v28, v92, v56
	s_waitcnt lgkmcnt(1)
	v_fma_f32 v55, -v35, v99, v55
	ds_read_b128 v[104:107], v65 offset:49056
	ds_read_b128 v[108:111], v65 offset:49072
	ds_read_b128 v[112:115], v65 offset:49088
	ds_read_b128 v[116:119], v65 offset:49104
	v_fma_f32 v58, -v34, v98, v58
	v_fma_f32 v57, -v33, v97, v57
	v_fma_f32 v56, -v32, v96, v56
	s_waitcnt lgkmcnt(4)
	v_fma_f32 v55, -v39, v103, v55
	v_fma_f32 v58, -v38, v102, v58
	v_fma_f32 v57, -v37, v101, v57
	v_fma_f32 v56, -v36, v100, v56
	s_waitcnt lgkmcnt(3)
	v_fma_f32 v55, -v43, v107, v55
	v_fma_f32 v58, -v42, v106, v58
	v_fma_f32 v57, -v41, v105, v57
	v_fma_f32 v56, -v40, v104, v56
	s_waitcnt lgkmcnt(2)
	v_fma_f32 v55, -v47, v111, v55
	v_fma_f32 v58, -v46, v110, v58
	v_fma_f32 v57, -v45, v109, v57
	v_fma_f32 v56, -v44, v108, v56
	s_waitcnt lgkmcnt(1)
	v_fma_f32 v55, -v51, v115, v55
	v_fma_f32 v58, -v50, v114, v58
	v_fma_f32 v57, -v49, v113, v57
	v_fma_f32 v56, -v48, v112, v56
	s_waitcnt lgkmcnt(0)
	v_fmac_f32_e32 v55, 0x80000000, v119
	v_fma_f32 v58, -v118, v54, v58
	v_fma_f32 v57, -v53, v117, v57
	v_fma_f32 v56, -v52, v116, v56
	v_add_f32_e32 v60, v57, v56
	v_add_f32_e32 v55, v55, v58
	ds_read_b128 v[56:59], v65 offset:49152
	ds_read_b128 v[68:71], v65 offset:49168
	ds_read_b128 v[72:75], v65 offset:49184
	ds_read_b128 v[76:79], v65 offset:49200
	ds_read_b128 v[80:83], v65 offset:49216
	ds_read_b128 v[84:87], v65 offset:49232
	ds_read_b128 v[88:91], v65 offset:49248
	ds_read_b128 v[92:95], v65 offset:49264
	ds_read_b128 v[96:99], v65 offset:49280
	ds_read_b128 v[100:103], v65 offset:49296
	ds_read_b128 v[104:107], v65 offset:49312
	ds_read_b128 v[108:111], v65 offset:49328
	ds_read_b128 v[112:115], v65 offset:49344
	ds_read_b128 v[116:119], v65 offset:49360
	ds_read2st64_b32 v[128:129], v62 offset0:224 offset1:228
	s_waitcnt lgkmcnt(14)
	v_fma_f32 v59, -v3, v59, 0
	v_fma_f32 v58, -v2, v58, 0
	v_fma_f32 v57, -v1, v57, 0
	s_waitcnt lgkmcnt(13)
	v_fma_f32 v59, -v7, v71, v59
	s_waitcnt lgkmcnt(0)
	v_fma_f32 v56, -v0, v56, v128
	v_fma_f32 v58, -v6, v70, v58
	v_fma_f32 v57, -v5, v69, v57
	v_fma_f32 v56, -v4, v68, v56
	v_fma_f32 v59, -v11, v75, v59
	v_fma_f32 v58, -v10, v74, v58
	v_fma_f32 v57, -v9, v73, v57
	v_fma_f32 v56, -v8, v72, v56
	v_fma_f32 v59, -v15, v79, v59
	v_fma_f32 v58, -v14, v78, v58
	v_fma_f32 v57, -v13, v77, v57
	v_fma_f32 v56, -v12, v76, v56
	v_fma_f32 v59, -v19, v83, v59
	v_fma_f32 v58, -v18, v82, v58
	v_fma_f32 v57, -v17, v81, v57
	v_fma_f32 v56, -v16, v80, v56
	v_fma_f32 v59, -v23, v87, v59
	v_fma_f32 v58, -v22, v86, v58
	v_fma_f32 v57, -v21, v85, v57
	v_fma_f32 v56, -v20, v84, v56
	v_fma_f32 v59, -v27, v91, v59
	v_fma_f32 v58, -v26, v90, v58
	v_fma_f32 v57, -v25, v89, v57
	v_fma_f32 v56, -v24, v88, v56
	v_fma_f32 v59, -v31, v95, v59
	v_fma_f32 v58, -v30, v94, v58
	v_fma_f32 v57, -v29, v93, v57
	v_fma_f32 v56, -v28, v92, v56
	v_fma_f32 v59, -v35, v99, v59
	v_fma_f32 v58, -v34, v98, v58
	v_fma_f32 v57, -v33, v97, v57
	v_fma_f32 v56, -v32, v96, v56
	v_fma_f32 v59, -v39, v103, v59
	v_fma_f32 v58, -v38, v102, v58
	v_fma_f32 v57, -v37, v101, v57
	v_fma_f32 v56, -v36, v100, v56
	v_fma_f32 v59, -v43, v107, v59
	v_fma_f32 v58, -v42, v106, v58
	v_fma_f32 v57, -v41, v105, v57
	v_fma_f32 v56, -v40, v104, v56
	v_fma_f32 v59, -v47, v111, v59
	v_fma_f32 v58, -v46, v110, v58
	v_fma_f32 v57, -v45, v109, v57
	v_fma_f32 v56, -v44, v108, v56
	v_add_f32_e32 v55, v55, v60
	v_fma_f32 v59, -v51, v115, v59
	v_fma_f32 v58, -v50, v114, v58
	v_fma_f32 v57, -v49, v113, v57
	v_fma_f32 v56, -v48, v112, v56
	v_fma_f32 v59, -v119, v55, v59
	v_fma_f32 v58, -v54, v118, v58
	v_fma_f32 v57, -v53, v117, v57
	v_fma_f32 v56, -v52, v116, v56
	v_add_f32_e32 v56, v57, v56
	v_add_f32_e32 v57, v58, v59
	ds_read_b128 v[58:61], v65 offset:49408
	ds_read_b128 v[68:71], v65 offset:49424
	ds_read_b128 v[72:75], v65 offset:49440
	ds_read_b128 v[76:79], v65 offset:49456
	ds_read_b128 v[80:83], v65 offset:49472
	ds_read_b128 v[84:87], v65 offset:49488
	v_add_f32_e32 v56, v57, v56
	s_waitcnt lgkmcnt(5)
	v_fma_f32 v57, -v3, v61, 0
	v_fma_f32 v60, -v2, v60, 0
	v_fma_f32 v59, -v1, v59, 0
	v_fma_f32 v58, -v0, v58, v129
	s_waitcnt lgkmcnt(4)
	v_fma_f32 v57, -v7, v71, v57
	v_fma_f32 v60, -v6, v70, v60
	v_fma_f32 v59, -v5, v69, v59
	v_fma_f32 v58, -v4, v68, v58
	s_waitcnt lgkmcnt(3)
	v_fma_f32 v57, -v11, v75, v57
	v_fma_f32 v60, -v10, v74, v60
	v_fma_f32 v59, -v9, v73, v59
	v_fma_f32 v58, -v8, v72, v58
	s_waitcnt lgkmcnt(2)
	v_fma_f32 v57, -v15, v79, v57
	ds_read_b128 v[88:91], v65 offset:49504
	ds_read_b128 v[92:95], v65 offset:49520
	ds_read_b128 v[96:99], v65 offset:49536
	v_fma_f32 v60, -v14, v78, v60
	v_fma_f32 v59, -v13, v77, v59
	v_fma_f32 v58, -v12, v76, v58
	s_waitcnt lgkmcnt(4)
; #define LAS __attribute__((address_space(3)))
; __device__ __forceinline__ void phase_chunk_prep(const Params& p, LAS unsigned char* lds, int wave_s) {
;     ...
;             for (int i = 0; i < 64; ++i) {
;                 float s0 = RHS[i * 256 + col], s1 = 0.f, s2 = 0.f, s3 = 0.f;
; #pragma unroll
;                 for (int j4 = 0; j4 < (i + 3) / 4; ++j4) { const f32x4 a = *(const LAS f32x4*)(AM + i * 64 + 4 * j4);
;                     s0 -= a.x * sol[4 * j4]; s1 -= a.y * sol[4 * j4 + 1]; s2 -= a.z * sol[4 * j4 + 2]; s3 -= a.w * sol[4 * j4 + 3]; }
;                 sol[i] = (s0 + s1) + (s2 + s3);
	v_fma_f32 v57, -v19, v83, v57
	ds_read_b128 v[100:103], v65 offset:49552
	ds_read_b128 v[104:107], v65 offset:49568
	v_fma_f32 v60, -v18, v82, v60
	v_fma_f32 v59, -v17, v81, v59
	v_fma_f32 v58, -v16, v80, v58
	s_waitcnt lgkmcnt(5)
	v_fma_f32 v57, -v23, v87, v57
	v_fma_f32 v60, -v22, v86, v60
	v_fma_f32 v59, -v21, v85, v59
	v_fma_f32 v58, -v20, v84, v58
	s_waitcnt lgkmcnt(4)
	v_fma_f32 v57, -v27, v91, v57
	v_fma_f32 v60, -v26, v90, v60
	v_fma_f32 v59, -v25, v89, v59
	v_fma_f32 v58, -v24, v88, v58
	s_waitcnt lgkmcnt(3)
	v_fma_f32 v57, -v31, v95, v57
	v_fma_f32 v60, -v30, v94, v60
	v_fma_f32 v59, -v29, v93, v59
	v_fma_f32 v58, -v28, v92, v58
	s_waitcnt lgkmcnt(2)
	v_fma_f32 v57, -v35, v99, v57
	ds_read_b128 v[108:111], v65 offset:49584
	ds_read_b128 v[112:115], v65 offset:49600
	ds_read_b128 v[116:119], v65 offset:49616
	v_fma_f32 v60, -v34, v98, v60
	v_fma_f32 v59, -v33, v97, v59
	v_fma_f32 v58, -v32, v96, v58
	s_waitcnt lgkmcnt(4)
	v_fma_f32 v57, -v39, v103, v57
	ds_read_b128 v[120:123], v65 offset:49632
	ds_read_b128 v[124:127], v65 offset:49664
	v_fma_f32 v60, -v38, v102, v60
	v_fma_f32 v59, -v37, v101, v59
	v_fma_f32 v58, -v36, v100, v58
	s_waitcnt lgkmcnt(5)
	v_fma_f32 v57, -v43, v107, v57
	v_fma_f32 v60, -v42, v106, v60
	v_fma_f32 v59, -v41, v105, v59
	v_fma_f32 v58, -v40, v104, v58
	s_waitcnt lgkmcnt(4)
	v_fma_f32 v57, -v47, v111, v57
	v_fma_f32 v60, -v46, v110, v60
	v_fma_f32 v59, -v45, v109, v59
	v_fma_f32 v58, -v44, v108, v58
	s_waitcnt lgkmcnt(3)
	v_fma_f32 v57, -v51, v115, v57
	v_fma_f32 v60, -v50, v114, v60
	v_fma_f32 v59, -v49, v113, v59
	v_fma_f32 v58, -v48, v112, v58
	s_waitcnt lgkmcnt(2)
	v_fma_f32 v57, -v55, v119, v57
	v_fma_f32 v60, -v54, v118, v60
	v_fma_f32 v59, -v53, v117, v59
	v_fma_f32 v58, -v52, v116, v58
	s_waitcnt lgkmcnt(1)
	v_fmac_f32_e32 v57, 0x80000000, v123
	v_fmac_f32_e32 v60, 0x80000000, v122
	v_fmac_f32_e32 v59, 0x80000000, v121
	v_fma_f32 v58, -v120, v56, v58
	v_add_f32_e32 v58, v59, v58
	v_add_f32_e32 v57, v60, v57
	v_add_f32_e32 v57, v57, v58
	ds_read_b128 v[58:61], v65 offset:49680
	ds_read_b128 v[68:71], v65 offset:49696
	ds_read_b128 v[72:75], v65 offset:49712
	ds_read_b128 v[76:79], v65 offset:49728
	ds_read_b128 v[80:83], v65 offset:49744
	s_waitcnt lgkmcnt(5)
	v_fma_f32 v63, -v3, v127, 0
	s_waitcnt lgkmcnt(4)
	v_fma_f32 v61, -v7, v61, v63
	s_waitcnt lgkmcnt(3)
	v_fma_f32 v61, -v11, v71, v61
	s_waitcnt lgkmcnt(2)
	v_fma_f32 v61, -v15, v75, v61
	ds_read_b128 v[84:87], v65 offset:49760
	ds_read_b128 v[88:91], v65 offset:49776
	ds_read_b128 v[92:95], v65 offset:49792
	s_waitcnt lgkmcnt(4)
	v_fma_f32 v61, -v19, v79, v61
	ds_read_b128 v[96:99], v65 offset:49808
	ds_read_b128 v[100:103], v65 offset:49824
	s_waitcnt lgkmcnt(5)
	v_fma_f32 v61, -v23, v83, v61
	s_waitcnt lgkmcnt(4)
	v_fma_f32 v61, -v27, v87, v61
	s_waitcnt lgkmcnt(3)
	v_fma_f32 v61, -v31, v91, v61
	s_waitcnt lgkmcnt(2)
	v_fma_f32 v61, -v35, v95, v61
	s_waitcnt lgkmcnt(1)
	v_fma_f32 v61, -v39, v99, v61
	ds_read_b128 v[104:107], v65 offset:49840
	ds_read_b128 v[108:111], v65 offset:49856
	ds_read_b128 v[112:115], v65 offset:49872
	ds_read_b128 v[116:119], v65 offset:49888
	s_waitcnt lgkmcnt(4)
	v_fma_f32 v61, -v43, v103, v61
	s_waitcnt lgkmcnt(3)
	v_fma_f32 v61, -v47, v107, v61
	s_waitcnt lgkmcnt(2)
	v_fma_f32 v61, -v51, v111, v61
	s_waitcnt lgkmcnt(1)
	v_fma_f32 v63, -v55, v115, v61
	v_fma_f32 v61, -v2, v126, 0
	v_fma_f32 v60, -v6, v60, v61
	v_fma_f32 v60, -v10, v70, v60
	v_fma_f32 v60, -v14, v74, v60
	v_fma_f32 v60, -v18, v78, v60
	v_fma_f32 v60, -v22, v82, v60
	v_fma_f32 v60, -v26, v86, v60
	v_fma_f32 v60, -v30, v90, v60
	v_fma_f32 v60, -v34, v94, v60
	v_fma_f32 v60, -v38, v98, v60
	v_fma_f32 v60, -v42, v102, v60
	v_fma_f32 v60, -v46, v106, v60
	v_fma_f32 v60, -v50, v110, v60
	v_fma_f32 v70, -v54, v114, v60
	v_fma_f32 v60, -v1, v125, 0
	v_fma_f32 v59, -v5, v59, v60
	ds_read2st64_b32 v[60:61], v62 offset0:232 offset1:236
	v_fma_f32 v59, -v9, v69, v59
	v_fma_f32 v59, -v13, v73, v59
	v_fma_f32 v59, -v17, v77, v59
	v_fma_f32 v59, -v21, v81, v59
	s_waitcnt lgkmcnt(0)
	v_fma_f32 v60, -v0, v124, v60
	v_fma_f32 v58, -v4, v58, v60
	v_fma_f32 v58, -v8, v68, v58
	v_fma_f32 v58, -v12, v72, v58
	v_fma_f32 v58, -v16, v76, v58
	v_fma_f32 v58, -v20, v80, v58
	v_fma_f32 v59, -v25, v85, v59
	v_fma_f32 v58, -v24, v84, v58
	v_fma_f32 v59, -v29, v89, v59
	v_fma_f32 v58, -v28, v88, v58
	v_fma_f32 v59, -v33, v93, v59
	v_fma_f32 v58, -v32, v92, v58
	v_fma_f32 v59, -v37, v97, v59
	v_fma_f32 v58, -v36, v96, v58
	v_fma_f32 v59, -v41, v101, v59
	v_fma_f32 v58, -v40, v100, v58
	v_fma_f32 v59, -v45, v105, v59
	v_fma_f32 v58, -v44, v104, v58
	v_fma_f32 v59, -v49, v109, v59
	v_fma_f32 v58, -v48, v108, v58
	v_fma_f32 v59, -v53, v113, v59
	v_fma_f32 v58, -v52, v112, v58
	v_fmac_f32_e32 v63, 0x80000000, v119
	v_fmac_f32_e32 v70, 0x80000000, v118
	v_fma_f32 v59, -v117, v57, v59
	v_fma_f32 v58, -v56, v116, v58
	v_add_f32_e32 v58, v59, v58
	v_add_f32_e32 v59, v70, v63
	ds_read_b128 v[68:71], v65 offset:49920
	ds_read_b128 v[72:75], v65 offset:49936
	ds_read_b128 v[76:79], v65 offset:49952
	ds_read_b128 v[80:83], v65 offset:49968
	ds_read_b128 v[84:87], v65 offset:49984
	ds_read_b128 v[88:91], v65 offset:50000
	v_add_f32_e32 v58, v59, v58
	s_waitcnt lgkmcnt(5)
	v_fma_f32 v59, -v3, v71, 0
	v_fma_f32 v60, -v2, v70, 0
	s_waitcnt lgkmcnt(4)
	v_fma_f32 v59, -v7, v75, v59
	v_fma_f32 v60, -v6, v74, v60
	s_waitcnt lgkmcnt(3)
	v_fma_f32 v59, -v11, v79, v59
	v_fma_f32 v60, -v10, v78, v60
	s_waitcnt lgkmcnt(2)
	v_fma_f32 v59, -v15, v83, v59
	ds_read_b128 v[92:95], v65 offset:50016
	ds_read_b128 v[96:99], v65 offset:50032
	ds_read_b128 v[100:103], v65 offset:50048
	v_fma_f32 v60, -v14, v82, v60
	s_waitcnt lgkmcnt(4)
; #define LAS __attribute__((address_space(3)))
; __device__ __forceinline__ void phase_chunk_prep(const Params& p, LAS unsigned char* lds, int wave_s) {
;     ...
;             for (int i = 0; i < 64; ++i) {
;                 float s0 = RHS[i * 256 + col], s1 = 0.f, s2 = 0.f, s3 = 0.f;
; #pragma unroll
;                 for (int j4 = 0; j4 < (i + 3) / 4; ++j4) { const f32x4 a = *(const LAS f32x4*)(AM + i * 64 + 4 * j4);
;                     s0 -= a.x * sol[4 * j4]; s1 -= a.y * sol[4 * j4 + 1]; s2 -= a.z * sol[4 * j4 + 2]; s3 -= a.w * sol[4 * j4 + 3]; }
;                 sol[i] = (s0 + s1) + (s2 + s3);
	v_fma_f32 v59, -v19, v87, v59
	ds_read_b128 v[104:107], v65 offset:50064
	ds_read_b128 v[108:111], v65 offset:50080
	v_fma_f32 v60, -v18, v86, v60
	s_waitcnt lgkmcnt(5)
	v_fma_f32 v59, -v23, v91, v59
	v_fma_f32 v60, -v22, v90, v60
	s_waitcnt lgkmcnt(4)
	v_fma_f32 v59, -v27, v95, v59
	v_fma_f32 v60, -v26, v94, v60
	s_waitcnt lgkmcnt(3)
	v_fma_f32 v59, -v31, v99, v59
	v_fma_f32 v60, -v30, v98, v60
	s_waitcnt lgkmcnt(2)
	v_fma_f32 v59, -v35, v103, v59
	ds_read_b128 v[112:115], v65 offset:50096
	ds_read_b128 v[116:119], v65 offset:50112
	ds_read_b128 v[120:123], v65 offset:50128
	v_fma_f32 v60, -v34, v102, v60
	s_waitcnt lgkmcnt(4)
	v_fma_f32 v59, -v39, v107, v59
	ds_read_b128 v[124:127], v65 offset:50144
	ds_read_b128 v[128:131], v65 offset:50176
	v_fma_f32 v60, -v38, v106, v60
	s_waitcnt lgkmcnt(5)
	v_fma_f32 v59, -v43, v111, v59
	v_fma_f32 v60, -v42, v110, v60
	s_waitcnt lgkmcnt(4)
	v_fma_f32 v59, -v47, v115, v59
	v_fma_f32 v60, -v46, v114, v60
	v_fma_f32 v63, -v1, v69, 0
	v_fma_f32 v61, -v0, v68, v61
	s_waitcnt lgkmcnt(3)
	v_fma_f32 v59, -v51, v119, v59
	v_fma_f32 v60, -v50, v118, v60
	v_fma_f32 v63, -v5, v73, v63
	v_fma_f32 v61, -v4, v72, v61
	s_waitcnt lgkmcnt(2)
	v_fma_f32 v59, -v55, v123, v59
	v_fma_f32 v60, -v54, v122, v60
	v_fma_f32 v63, -v9, v77, v63
	v_fma_f32 v61, -v8, v76, v61
	ds_read_b128 v[68:71], v65 offset:50192
	ds_read_b128 v[72:75], v65 offset:50208
	ds_read_b128 v[76:79], v65 offset:50224
	s_waitcnt lgkmcnt(4)
	v_fmac_f32_e32 v59, 0x80000000, v127
	v_fma_f32 v60, -v126, v58, v60
	v_fma_f32 v63, -v13, v81, v63
	v_fma_f32 v61, -v12, v80, v61
	ds_read_b128 v[80:83], v65 offset:50240
	v_fma_f32 v63, -v17, v85, v63
	v_fma_f32 v61, -v16, v84, v61
	v_add_f32_e32 v59, v59, v60
	s_waitcnt lgkmcnt(4)
	v_fma_f32 v60, -v3, v131, 0
	ds_read_b128 v[84:87], v65 offset:50256
	v_fma_f32 v63, -v21, v89, v63
	v_fma_f32 v61, -v20, v88, v61
	s_waitcnt lgkmcnt(4)
	v_fma_f32 v60, -v7, v71, v60
	v_fma_f32 v63, -v25, v93, v63
	v_fma_f32 v61, -v24, v92, v61
	s_waitcnt lgkmcnt(3)
	v_fma_f32 v60, -v11, v75, v60
	v_fma_f32 v63, -v29, v97, v63
	v_fma_f32 v61, -v28, v96, v61
	s_waitcnt lgkmcnt(2)
	v_fma_f32 v60, -v15, v79, v60
	ds_read_b128 v[88:91], v65 offset:50272
	ds_read_b128 v[92:95], v65 offset:50288
	ds_read_b128 v[96:99], v65 offset:50304
	v_fma_f32 v63, -v33, v101, v63
	v_fma_f32 v61, -v32, v100, v61
	s_waitcnt lgkmcnt(4)
	v_fma_f32 v60, -v19, v83, v60
	ds_read_b128 v[100:103], v65 offset:50320
	v_fma_f32 v63, -v37, v105, v63
	v_fma_f32 v61, -v36, v104, v61
	s_waitcnt lgkmcnt(4)
	v_fma_f32 v60, -v23, v87, v60
	ds_read_b128 v[104:107], v65 offset:50336
	v_fma_f32 v63, -v41, v109, v63
	v_fma_f32 v61, -v40, v108, v61
	s_waitcnt lgkmcnt(4)
	v_fma_f32 v60, -v27, v91, v60
	v_fma_f32 v63, -v45, v113, v63
	v_fma_f32 v61, -v44, v112, v61
	s_waitcnt lgkmcnt(3)
	v_fma_f32 v60, -v31, v95, v60
	v_fma_f32 v63, -v49, v117, v63
	v_fma_f32 v61, -v48, v116, v61
	s_waitcnt lgkmcnt(2)
	v_fma_f32 v60, -v35, v99, v60
	v_fma_f32 v63, -v53, v121, v63
	v_fma_f32 v61, -v52, v120, v61
	s_waitcnt lgkmcnt(1)
	v_fma_f32 v60, -v39, v103, v60
	ds_read_b128 v[108:111], v65 offset:50352
	ds_read_b128 v[112:115], v65 offset:50368
	ds_read_b128 v[116:119], v65 offset:50384
	ds_read_b128 v[120:123], v65 offset:50400
	s_waitcnt lgkmcnt(4)
	v_fma_f32 v60, -v43, v107, v60
	v_fma_f32 v63, -v57, v125, v63
	v_fma_f32 v61, -v56, v124, v61
	s_waitcnt lgkmcnt(3)
	v_fma_f32 v60, -v47, v111, v60
	v_add_f32_e32 v61, v63, v61
	s_waitcnt lgkmcnt(2)
	v_fma_f32 v60, -v51, v115, v60
	v_add_f32_e32 v59, v59, v61
	s_waitcnt lgkmcnt(1)
	v_fma_f32 v60, -v55, v119, v60
	s_waitcnt lgkmcnt(0)
	v_fma_f32 v63, -v123, v59, v60
	v_fma_f32 v60, -v2, v130, 0
	v_fma_f32 v60, -v6, v70, v60
	v_fma_f32 v60, -v10, v74, v60
	v_fma_f32 v60, -v14, v78, v60
	v_fma_f32 v60, -v18, v82, v60
	v_fma_f32 v60, -v22, v86, v60
	v_fma_f32 v60, -v26, v90, v60
	v_fma_f32 v60, -v30, v94, v60
	v_fma_f32 v60, -v34, v98, v60
	v_fma_f32 v60, -v38, v102, v60
	v_fma_f32 v60, -v42, v106, v60
	v_fma_f32 v60, -v46, v110, v60
	v_fma_f32 v60, -v50, v114, v60
	v_fma_f32 v60, -v54, v118, v60
	v_fma_f32 v74, -v58, v122, v60
	v_fma_f32 v60, -v1, v129, 0
	v_fma_f32 v60, -v5, v69, v60
	v_fma_f32 v60, -v9, v73, v60
	v_fma_f32 v60, -v13, v77, v60
	v_fma_f32 v60, -v17, v81, v60
	v_fma_f32 v60, -v21, v85, v60
	v_fma_f32 v60, -v25, v89, v60
	v_fma_f32 v60, -v29, v93, v60
	v_fma_f32 v60, -v33, v97, v60
	v_fma_f32 v60, -v37, v101, v60
	v_fma_f32 v69, -v41, v105, v60
	ds_read2st64_b32 v[60:61], v62 offset0:240 offset1:244
	v_fma_f32 v69, -v45, v109, v69
	v_fma_f32 v69, -v49, v113, v69
	v_fma_f32 v69, -v53, v117, v69
	v_fma_f32 v73, -v57, v121, v69
	s_waitcnt lgkmcnt(0)
	v_fma_f32 v60, -v0, v128, v60
	v_fma_f32 v60, -v4, v68, v60
	v_fma_f32 v60, -v8, v72, v60
	v_fma_f32 v60, -v12, v76, v60
	v_fma_f32 v60, -v16, v80, v60
	v_fma_f32 v60, -v20, v84, v60
	v_fma_f32 v60, -v24, v88, v60
	v_fma_f32 v60, -v28, v92, v60
	v_fma_f32 v60, -v32, v96, v60
	v_fma_f32 v60, -v36, v100, v60
	v_fma_f32 v60, -v40, v104, v60
	v_fma_f32 v60, -v44, v108, v60
	v_fma_f32 v60, -v48, v112, v60
	v_fma_f32 v60, -v52, v116, v60
	v_fma_f32 v60, -v56, v120, v60
	ds_read_b128 v[68:71], v65 offset:50432
	v_add_f32_e32 v60, v73, v60
	v_add_f32_e32 v63, v74, v63
	ds_read_b128 v[72:75], v65 offset:50448
	ds_read_b128 v[76:79], v65 offset:50464
	ds_read_b128 v[80:83], v65 offset:50480
	ds_read_b128 v[84:87], v65 offset:50496
	v_add_f32_e32 v60, v63, v60
	s_waitcnt lgkmcnt(4)
	v_fma_f32 v63, -v3, v71, 0
	ds_read_b128 v[88:91], v65 offset:50512
	ds_read_b128 v[92:95], v65 offset:50528
	v_fma_f32 v70, -v2, v70, 0
	v_fma_f32 v69, -v1, v69, 0
	v_fma_f32 v61, -v0, v68, v61
	s_waitcnt lgkmcnt(5)
; #define LAS __attribute__((address_space(3)))
; __device__ __forceinline__ void phase_chunk_prep(const Params& p, LAS unsigned char* lds, int wave_s) {
;     ...
;             for (int i = 0; i < 64; ++i) {
;                 float s0 = RHS[i * 256 + col], s1 = 0.f, s2 = 0.f, s3 = 0.f;
; #pragma unroll
;                 for (int j4 = 0; j4 < (i + 3) / 4; ++j4) { const f32x4 a = *(const LAS f32x4*)(AM + i * 64 + 4 * j4);
;                     s0 -= a.x * sol[4 * j4]; s1 -= a.y * sol[4 * j4 + 1]; s2 -= a.z * sol[4 * j4 + 2]; s3 -= a.w * sol[4 * j4 + 3]; }
;                 sol[i] = (s0 + s1) + (s2 + s3);
	v_fma_f32 v63, -v7, v75, v63
	v_fma_f32 v70, -v6, v74, v70
	v_fma_f32 v69, -v5, v73, v69
	v_fma_f32 v61, -v4, v72, v61
	s_waitcnt lgkmcnt(4)
	v_fma_f32 v63, -v11, v79, v63
	v_fma_f32 v70, -v10, v78, v70
	v_fma_f32 v69, -v9, v77, v69
	v_fma_f32 v61, -v8, v76, v61
	s_waitcnt lgkmcnt(3)
	v_fma_f32 v63, -v15, v83, v63
	v_fma_f32 v70, -v14, v82, v70
	v_fma_f32 v69, -v13, v81, v69
	v_fma_f32 v61, -v12, v80, v61
	s_waitcnt lgkmcnt(2)
	v_fma_f32 v63, -v19, v87, v63
	ds_read_b128 v[96:99], v65 offset:50544
	ds_read_b128 v[100:103], v65 offset:50560
	ds_read_b128 v[104:107], v65 offset:50576
	v_fma_f32 v70, -v18, v86, v70
	v_fma_f32 v69, -v17, v85, v69
	v_fma_f32 v61, -v16, v84, v61
	s_waitcnt lgkmcnt(4)
	v_fma_f32 v63, -v23, v91, v63
	ds_read_b128 v[108:111], v65 offset:50592
	ds_read_b128 v[112:115], v65 offset:50608
	v_fma_f32 v70, -v22, v90, v70
	v_fma_f32 v69, -v21, v89, v69
	v_fma_f32 v61, -v20, v88, v61
	s_waitcnt lgkmcnt(5)
	v_fma_f32 v63, -v27, v95, v63
	v_fma_f32 v70, -v26, v94, v70
	v_fma_f32 v69, -v25, v93, v69
	v_fma_f32 v61, -v24, v92, v61
	s_waitcnt lgkmcnt(4)
	v_fma_f32 v63, -v31, v99, v63
	v_fma_f32 v70, -v30, v98, v70
	v_fma_f32 v69, -v29, v97, v69
	v_fma_f32 v61, -v28, v96, v61
	s_waitcnt lgkmcnt(3)
	v_fma_f32 v63, -v35, v103, v63
	v_fma_f32 v70, -v34, v102, v70
	v_fma_f32 v69, -v33, v101, v69
	v_fma_f32 v61, -v32, v100, v61
	s_waitcnt lgkmcnt(2)
	v_fma_f32 v63, -v39, v107, v63
	v_fma_f32 v70, -v38, v106, v70
	v_fma_f32 v69, -v37, v105, v69
	v_fma_f32 v61, -v36, v104, v61
	s_waitcnt lgkmcnt(1)
	v_fma_f32 v63, -v43, v111, v63
	ds_read_b128 v[116:119], v65 offset:50624
	ds_read_b128 v[120:123], v65 offset:50640
	ds_read_b128 v[124:127], v65 offset:50656
	ds_read_b128 v[128:131], v65 offset:50672
	v_fma_f32 v70, -v42, v110, v70
	v_fma_f32 v69, -v41, v109, v69
	v_fma_f32 v61, -v40, v108, v61
	s_waitcnt lgkmcnt(4)
	v_fma_f32 v63, -v47, v115, v63
	v_fma_f32 v70, -v46, v114, v70
	v_fma_f32 v69, -v45, v113, v69
	v_fma_f32 v61, -v44, v112, v61
	s_waitcnt lgkmcnt(3)
	v_fma_f32 v63, -v51, v119, v63
	v_fma_f32 v70, -v50, v118, v70
	v_fma_f32 v69, -v49, v117, v69
	v_fma_f32 v61, -v48, v116, v61
	s_waitcnt lgkmcnt(2)
	v_fma_f32 v63, -v55, v123, v63
	v_fma_f32 v70, -v54, v122, v70
	v_fma_f32 v69, -v53, v121, v69
	v_fma_f32 v61, -v52, v120, v61
	s_waitcnt lgkmcnt(1)
	v_fma_f32 v63, -v59, v127, v63
	v_fma_f32 v74, -v58, v126, v70
	v_fma_f32 v73, -v57, v125, v69
	v_fma_f32 v61, -v56, v124, v61
	s_waitcnt lgkmcnt(0)
	v_fmac_f32_e32 v63, 0x80000000, v131
	v_fmac_f32_e32 v74, 0x80000000, v130
	v_fmac_f32_e32 v73, 0x80000000, v129
	v_fma_f32 v61, -v128, v60, v61
	ds_read_b128 v[68:71], v65 offset:50688
	v_add_f32_e32 v61, v73, v61
	v_add_f32_e32 v63, v74, v63
	ds_read_b128 v[72:75], v65 offset:50704
	ds_read_b128 v[76:79], v65 offset:50720
	ds_read_b128 v[80:83], v65 offset:50736
	ds_read_b128 v[84:87], v65 offset:50752
	v_add_f32_e32 v61, v63, v61
	s_waitcnt lgkmcnt(4)
	v_fma_f32 v63, -v3, v71, 0
	ds_read_b128 v[88:91], v65 offset:50768
	ds_read_b128 v[92:95], v65 offset:50784
	s_waitcnt lgkmcnt(5)
	v_fma_f32 v63, -v7, v75, v63
	s_waitcnt lgkmcnt(4)
	v_fma_f32 v63, -v11, v79, v63
	s_waitcnt lgkmcnt(3)
	v_fma_f32 v63, -v15, v83, v63
	s_waitcnt lgkmcnt(2)
	v_fma_f32 v63, -v19, v87, v63
	ds_read_b128 v[96:99], v65 offset:50800
	ds_read_b128 v[100:103], v65 offset:50816
	ds_read_b128 v[104:107], v65 offset:50832
	s_waitcnt lgkmcnt(4)
	v_fma_f32 v63, -v23, v91, v63
	ds_read_b128 v[108:111], v65 offset:50848
	ds_read_b128 v[112:115], v65 offset:50864
	s_waitcnt lgkmcnt(5)
	v_fma_f32 v63, -v27, v95, v63
	s_waitcnt lgkmcnt(4)
	v_fma_f32 v63, -v31, v99, v63
	s_waitcnt lgkmcnt(3)
	v_fma_f32 v63, -v35, v103, v63
	s_waitcnt lgkmcnt(2)
	v_fma_f32 v63, -v39, v107, v63
	s_waitcnt lgkmcnt(1)
	v_fma_f32 v63, -v43, v111, v63
	ds_read_b128 v[116:119], v65 offset:50880
	ds_read_b128 v[120:123], v65 offset:50896
	ds_read_b128 v[124:127], v65 offset:50912
	ds_read_b128 v[128:131], v65 offset:50928
	s_waitcnt lgkmcnt(4)
	v_fma_f32 v63, -v47, v115, v63
	s_waitcnt lgkmcnt(3)
	v_fma_f32 v63, -v51, v119, v63
	s_waitcnt lgkmcnt(2)
	v_fma_f32 v63, -v55, v123, v63
	s_waitcnt lgkmcnt(1)
	v_fma_f32 v75, -v59, v127, v63
	v_fma_f32 v63, -v2, v70, 0
	v_fma_f32 v63, -v6, v74, v63
	v_fma_f32 v63, -v10, v78, v63
	v_fma_f32 v63, -v14, v82, v63
	v_fma_f32 v63, -v18, v86, v63
	v_fma_f32 v63, -v22, v90, v63
	v_fma_f32 v63, -v26, v94, v63
	v_fma_f32 v63, -v30, v98, v63
	v_fma_f32 v63, -v34, v102, v63
	v_fma_f32 v63, -v38, v106, v63
	v_fma_f32 v63, -v42, v110, v63
	v_fma_f32 v63, -v46, v114, v63
	v_fma_f32 v63, -v50, v118, v63
	v_fma_f32 v63, -v54, v122, v63
	v_fma_f32 v74, -v58, v126, v63
	v_fma_f32 v63, -v1, v69, 0
	v_fma_f32 v63, -v5, v73, v63
	v_fma_f32 v63, -v9, v77, v63
	v_fma_f32 v63, -v13, v81, v63
	v_fma_f32 v63, -v17, v85, v63
	v_fma_f32 v63, -v21, v89, v63
	v_fma_f32 v63, -v25, v93, v63
	v_fma_f32 v63, -v29, v97, v63
	v_fma_f32 v63, -v33, v101, v63
	v_fma_f32 v63, -v37, v105, v63
	v_fma_f32 v63, -v41, v109, v63
	v_fma_f32 v69, -v45, v113, v63
	ds_read2st64_b32 v[62:63], v62 offset0:248 offset1:252
	v_fma_f32 v69, -v49, v117, v69
	v_fma_f32 v69, -v53, v121, v69
	v_fma_f32 v69, -v57, v125, v69
	s_waitcnt lgkmcnt(1)
	v_fmac_f32_e32 v75, 0x80000000, v131
	s_waitcnt lgkmcnt(0)
; #define LAS __attribute__((address_space(3)))
; __device__ __forceinline__ void phase_chunk_prep(const Params& p, LAS unsigned char* lds, int wave_s) {
;     ...
;             for (int i = 0; i < 64; ++i) {
;                 float s0 = RHS[i * 256 + col], s1 = 0.f, s2 = 0.f, s3 = 0.f;
; #pragma unroll
;                 for (int j4 = 0; j4 < (i + 3) / 4; ++j4) { const f32x4 a = *(const LAS f32x4*)(AM + i * 64 + 4 * j4);
;                     s0 -= a.x * sol[4 * j4]; s1 -= a.y * sol[4 * j4 + 1]; s2 -= a.z * sol[4 * j4 + 2]; s3 -= a.w * sol[4 * j4 + 3]; }
;                 sol[i] = (s0 + s1) + (s2 + s3);
;             }
;             if (col < 128) {
	v_fma_f32 v62, -v0, v68, v62
	v_fma_f32 v62, -v4, v72, v62
	v_fma_f32 v62, -v8, v76, v62
	v_fma_f32 v62, -v12, v80, v62
	v_fma_f32 v62, -v16, v84, v62
	v_fma_f32 v62, -v20, v88, v62
	v_fma_f32 v62, -v24, v92, v62
	v_fma_f32 v62, -v28, v96, v62
	v_fma_f32 v62, -v32, v100, v62
	v_fma_f32 v62, -v36, v104, v62
	v_fma_f32 v62, -v40, v108, v62
	v_fma_f32 v62, -v44, v112, v62
	v_fma_f32 v62, -v48, v116, v62
	v_fma_f32 v62, -v52, v120, v62
	v_fma_f32 v62, -v56, v124, v62
	v_fmac_f32_e32 v74, 0x80000000, v130
	v_fma_f32 v73, -v129, v61, v69
	v_fma_f32 v62, -v60, v128, v62
	ds_read_b128 v[68:71], v65 offset:50944
	v_add_f32_e32 v62, v73, v62
	v_add_f32_e32 v72, v74, v75
	v_add_f32_e32 v62, v72, v62
	ds_read_b128 v[72:75], v65 offset:50960
	ds_read_b128 v[76:79], v65 offset:50976
	ds_read_b128 v[80:83], v65 offset:50992
	ds_read_b128 v[84:87], v65 offset:51008
	s_waitcnt lgkmcnt(4)
	v_fma_f32 v71, -v3, v71, 0
	ds_read_b128 v[88:91], v65 offset:51024
	ds_read_b128 v[92:95], v65 offset:51040
	v_fma_f32 v70, -v2, v70, 0
	v_fma_f32 v69, -v1, v69, 0
	v_fma_f32 v63, -v0, v68, v63
	s_waitcnt lgkmcnt(5)
	v_fma_f32 v71, -v7, v75, v71
	v_fma_f32 v70, -v6, v74, v70
	v_fma_f32 v69, -v5, v73, v69
	v_fma_f32 v63, -v4, v72, v63
	s_waitcnt lgkmcnt(4)
	v_fma_f32 v71, -v11, v79, v71
	v_fma_f32 v70, -v10, v78, v70
	v_fma_f32 v69, -v9, v77, v69
	v_fma_f32 v63, -v8, v76, v63
	s_waitcnt lgkmcnt(3)
	v_fma_f32 v71, -v15, v83, v71
	v_fma_f32 v70, -v14, v82, v70
	v_fma_f32 v69, -v13, v81, v69
	v_fma_f32 v63, -v12, v80, v63
	s_waitcnt lgkmcnt(2)
	v_fma_f32 v71, -v19, v87, v71
	ds_read_b128 v[96:99], v65 offset:51056
	ds_read_b128 v[100:103], v65 offset:51072
	ds_read_b128 v[104:107], v65 offset:51088
	v_fma_f32 v70, -v18, v86, v70
	v_fma_f32 v69, -v17, v85, v69
	v_fma_f32 v63, -v16, v84, v63
	s_waitcnt lgkmcnt(4)
	v_fma_f32 v71, -v23, v91, v71
	ds_read_b128 v[108:111], v65 offset:51104
	ds_read_b128 v[112:115], v65 offset:51120
	v_fma_f32 v70, -v22, v90, v70
	v_fma_f32 v69, -v21, v89, v69
	v_fma_f32 v63, -v20, v88, v63
	s_waitcnt lgkmcnt(5)
	v_fma_f32 v71, -v27, v95, v71
	v_fma_f32 v70, -v26, v94, v70
	v_fma_f32 v69, -v25, v93, v69
	v_fma_f32 v63, -v24, v92, v63
	s_waitcnt lgkmcnt(4)
	v_fma_f32 v71, -v31, v99, v71
	v_fma_f32 v70, -v30, v98, v70
	v_fma_f32 v69, -v29, v97, v69
	v_fma_f32 v63, -v28, v96, v63
	s_waitcnt lgkmcnt(3)
	v_fma_f32 v71, -v35, v103, v71
	v_fma_f32 v70, -v34, v102, v70
	v_fma_f32 v69, -v33, v101, v69
	v_fma_f32 v63, -v32, v100, v63
	s_waitcnt lgkmcnt(2)
	v_fma_f32 v71, -v39, v107, v71
	v_fma_f32 v70, -v38, v106, v70
	v_fma_f32 v69, -v37, v105, v69
	v_fma_f32 v63, -v36, v104, v63
	s_waitcnt lgkmcnt(1)
	v_fma_f32 v71, -v43, v111, v71
	ds_read_b128 v[116:119], v65 offset:51136
	ds_read_b128 v[120:123], v65 offset:51152
	ds_read_b128 v[124:127], v65 offset:51168
	ds_read_b128 v[128:131], v65 offset:51184
	v_fma_f32 v70, -v42, v110, v70
	v_fma_f32 v69, -v41, v109, v69
	v_fma_f32 v63, -v40, v108, v63
	s_waitcnt lgkmcnt(4)
	v_fma_f32 v71, -v47, v115, v71
	v_fma_f32 v70, -v46, v114, v70
	v_fma_f32 v69, -v45, v113, v69
	v_fma_f32 v63, -v44, v112, v63
	s_waitcnt lgkmcnt(3)
	v_fma_f32 v71, -v51, v119, v71
	v_fma_f32 v70, -v50, v118, v70
	v_fma_f32 v69, -v49, v117, v69
	v_fma_f32 v63, -v48, v116, v63
	s_waitcnt lgkmcnt(2)
	v_fma_f32 v71, -v55, v123, v71
	v_fma_f32 v70, -v54, v122, v70
	v_fma_f32 v69, -v53, v121, v69
	v_fma_f32 v63, -v52, v120, v63
	s_waitcnt lgkmcnt(1)
	v_fma_f32 v71, -v59, v127, v71
	v_fma_f32 v70, -v58, v126, v70
	v_fma_f32 v69, -v57, v125, v69
	v_fma_f32 v63, -v56, v124, v63
	s_waitcnt lgkmcnt(0)
	v_fmac_f32_e32 v71, 0x80000000, v131
	v_fma_f32 v70, -v130, v62, v70
	v_fma_f32 v69, -v61, v129, v69
	v_fma_f32 v63, -v60, v128, v63
	v_add_f32_e32 v63, v69, v63
	v_add_f32_e32 v68, v71, v70
	v_add_f32_e32 v63, v68, v63
	s_and_saveexec_b64 s[34:35], vcc
	s_xor_b64 s[34:35], exec, s[34:35]
	s_cbranch_execz .LBB0_784
; __device__ __forceinline__ bf16_t f2bf(float x) { return (bf16_t)(pk2(x, 0.f) & 0xffffu); }
; __device__ __forceinline__ void phase_chunk_prep(const Params& p, LAS unsigned char* lds, int wave_s) {
;     ...
;             if (col < 128) {
; #pragma unroll
;                 for (int mm = 0; mm < 4; ++mm)
; #pragma unroll
;                     for (int q4 = 0; q4 < 4; ++q4)
;                         *(f32x4*)(U + ((((col >> 4) * 4 + mm) * 64 + q4 * 16 + (col & 15)) << 2)) = (f32x4){sol[16 * mm + 4 * q4], sol[16 * mm + 4 * q4 + 1], sol[16 * mm + 4 * q4 + 2], sol[16 * mm + 4 * q4 + 3]};
;             } else {
; #pragma unroll
;                 for (int i = 0; i < 64; ++i) img[IMG_WD + i * SWD + (col - 128)] = f2bf(sol[i]);
;             }
	v_mov_b32_e32 v67, v65
	v_cvt_pk_bf16_f32 v0, v0, s0
	v_lshl_add_u64 v[66:67], v[66:67], 1, s[30:31]
	global_store_short v[66:67], v0, off offset:-256
	v_cvt_pk_bf16_f32 v0, v1, s0
	global_store_short v[66:67], v0, off offset:8
	v_cvt_pk_bf16_f32 v0, v2, s0
	global_store_short v[66:67], v0, off offset:272
	v_cvt_pk_bf16_f32 v0, v3, s0
	global_store_short v[66:67], v0, off offset:536
	v_cvt_pk_bf16_f32 v0, v4, s0
	global_store_short v[66:67], v0, off offset:800
	v_cvt_pk_bf16_f32 v0, v5, s0
	global_store_short v[66:67], v0, off offset:1064
	v_cvt_pk_bf16_f32 v0, v6, s0
	global_store_short v[66:67], v0, off offset:1328
	v_cvt_pk_bf16_f32 v0, v7, s0
	global_store_short v[66:67], v0, off offset:1592
	v_cvt_pk_bf16_f32 v0, v8, s0
	global_store_short v[66:67], v0, off offset:1856
	v_cvt_pk_bf16_f32 v0, v9, s0
	global_store_short v[66:67], v0, off offset:2120
	v_cvt_pk_bf16_f32 v0, v10, s0
	global_store_short v[66:67], v0, off offset:2384
	v_cvt_pk_bf16_f32 v0, v11, s0
	global_store_short v[66:67], v0, off offset:2648
	v_cvt_pk_bf16_f32 v0, v12, s0
	global_store_short v[66:67], v0, off offset:2912
	v_cvt_pk_bf16_f32 v0, v13, s0
	global_store_short v[66:67], v0, off offset:3176
	v_cvt_pk_bf16_f32 v0, v14, s0
	global_store_short v[66:67], v0, off offset:3440
	v_cvt_pk_bf16_f32 v0, v15, s0
	global_store_short v[66:67], v0, off offset:3704
	v_cvt_pk_bf16_f32 v0, v16, s0
	global_store_short v[66:67], v0, off offset:3968
	v_add_co_u32_e32 v0, vcc, s44, v66
	v_cvt_pk_bf16_f32 v2, v17, s0
	s_nop 0
	v_addc_co_u32_e32 v1, vcc, 0, v67, vcc
	global_store_short v[0:1], v2, off offset:136
	v_cvt_pk_bf16_f32 v2, v18, s0
	global_store_short v[0:1], v2, off offset:400
	v_cvt_pk_bf16_f32 v2, v19, s0
	global_store_short v[0:1], v2, off offset:664
	v_cvt_pk_bf16_f32 v2, v20, s0
	global_store_short v[0:1], v2, off offset:928
	v_cvt_pk_bf16_f32 v2, v21, s0
	global_store_short v[0:1], v2, off offset:1192
	v_cvt_pk_bf16_f32 v2, v22, s0
	global_store_short v[0:1], v2, off offset:1456
	v_cvt_pk_bf16_f32 v2, v23, s0
	global_store_short v[0:1], v2, off offset:1720
	v_cvt_pk_bf16_f32 v2, v24, s0
	global_store_short v[0:1], v2, off offset:1984
	v_cvt_pk_bf16_f32 v2, v25, s0
	global_store_short v[0:1], v2, off offset:2248
	v_cvt_pk_bf16_f32 v2, v26, s0
	global_store_short v[0:1], v2, off offset:2512
	v_cvt_pk_bf16_f32 v2, v27, s0
	global_store_short v[0:1], v2, off offset:2776
	v_cvt_pk_bf16_f32 v2, v28, s0
	global_store_short v[0:1], v2, off offset:3040
	v_cvt_pk_bf16_f32 v2, v29, s0
	global_store_short v[0:1], v2, off offset:3304
	v_cvt_pk_bf16_f32 v2, v30, s0
	global_store_short v[0:1], v2, off offset:3568
	v_cvt_pk_bf16_f32 v2, v31, s0
	global_store_short v[0:1], v2, off offset:3832
	v_add_co_u32_e32 v0, vcc, s45, v66
	v_cvt_pk_bf16_f32 v2, v32, s0
	s_nop 0
	v_addc_co_u32_e32 v1, vcc, 0, v67, vcc
	global_store_short v[0:1], v2, off
	v_cvt_pk_bf16_f32 v2, v33, s0
	global_store_short v[0:1], v2, off offset:264
	v_cvt_pk_bf16_f32 v2, v34, s0
	global_store_short v[0:1], v2, off offset:528
	v_cvt_pk_bf16_f32 v2, v35, s0
	global_store_short v[0:1], v2, off offset:792
	v_cvt_pk_bf16_f32 v2, v36, s0
	global_store_short v[0:1], v2, off offset:1056
	v_cvt_pk_bf16_f32 v2, v37, s0
	global_store_short v[0:1], v2, off offset:1320
	v_cvt_pk_bf16_f32 v2, v38, s0
	global_store_short v[0:1], v2, off offset:1584
	v_cvt_pk_bf16_f32 v2, v39, s0
	global_store_short v[0:1], v2, off offset:1848
	v_cvt_pk_bf16_f32 v2, v40, s0
	global_store_short v[0:1], v2, off offset:2112
	v_cvt_pk_bf16_f32 v2, v41, s0
	global_store_short v[0:1], v2, off offset:2376
	v_cvt_pk_bf16_f32 v2, v42, s0
	global_store_short v[0:1], v2, off offset:2640
	v_cvt_pk_bf16_f32 v2, v43, s0
	global_store_short v[0:1], v2, off offset:2904
	v_cvt_pk_bf16_f32 v2, v44, s0
	global_store_short v[0:1], v2, off offset:3168
	v_cvt_pk_bf16_f32 v2, v45, s0
	global_store_short v[0:1], v2, off offset:3432
	v_cvt_pk_bf16_f32 v2, v46, s0
	global_store_short v[0:1], v2, off offset:3696
	v_cvt_pk_bf16_f32 v2, v47, s0
	global_store_short v[0:1], v2, off offset:3960
	v_add_co_u32_e32 v0, vcc, s46, v66
	v_cvt_pk_bf16_f32 v2, v48, s0
	s_nop 0
	v_addc_co_u32_e32 v1, vcc, 0, v67, vcc
	global_store_short v[0:1], v2, off offset:128
	v_cvt_pk_bf16_f32 v2, v49, s0
	global_store_short v[0:1], v2, off offset:392
	v_cvt_pk_bf16_f32 v2, v50, s0
	global_store_short v[0:1], v2, off offset:656
	v_cvt_pk_bf16_f32 v2, v51, s0
	global_store_short v[0:1], v2, off offset:920
	v_cvt_pk_bf16_f32 v2, v52, s0
	global_store_short v[0:1], v2, off offset:1184
	v_cvt_pk_bf16_f32 v2, v53, s0
	global_store_short v[0:1], v2, off offset:1448
	v_cvt_pk_bf16_f32 v2, v54, s0
	global_store_short v[0:1], v2, off offset:1712
	v_cvt_pk_bf16_f32 v2, v55, s0
	global_store_short v[0:1], v2, off offset:1976
	v_cvt_pk_bf16_f32 v2, v56, s0
	global_store_short v[0:1], v2, off offset:2240
	v_cvt_pk_bf16_f32 v2, v57, s0
	global_store_short v[0:1], v2, off offset:2504
	v_cvt_pk_bf16_f32 v2, v58, s0
	global_store_short v[0:1], v2, off offset:2768
	v_cvt_pk_bf16_f32 v2, v59, s0
	global_store_short v[0:1], v2, off offset:3032
	v_cvt_pk_bf16_f32 v2, v60, s0
	global_store_short v[0:1], v2, off offset:3296
	v_cvt_pk_bf16_f32 v2, v61, s0
	global_store_short v[0:1], v2, off offset:3560
	v_cvt_pk_bf16_f32 v2, v62, s0
	global_store_short v[0:1], v2, off offset:3824
	v_cvt_pk_bf16_f32 v2, v63, s0
	global_store_short v[0:1], v2, off offset:4088
	s_waitcnt vmcnt(63)
.LBB0_784:
	s_andn2_saveexec_b64 s[30:31], s[34:35]
	s_cbranch_execz .LBB0_663
	s_lshl_b64 s[16:17], s[16:17], 15
	v_lshlrev_b32_e32 v64, 8, v64
	s_add_u32 s16, s20, s16
	v_and_or_b32 v66, v64, s67, v67
	s_addc_u32 s17, s21, s17
	v_ashrrev_i32_e32 v67, 31, v66
	v_lshl_add_u64 v[66:67], v[66:67], 2, s[16:17]
	global_store_dwordx4 v[66:67], v[0:3], off
	global_store_dwordx4 v[66:67], v[4:7], off offset:256
	global_store_dwordx4 v[66:67], v[8:11], off offset:512
	global_store_dwordx4 v[66:67], v[12:15], off offset:768
	global_store_dwordx4 v[66:67], v[16:19], off offset:1024
	global_store_dwordx4 v[66:67], v[20:23], off offset:1280
	global_store_dwordx4 v[66:67], v[24:27], off offset:1536
	global_store_dwordx4 v[66:67], v[28:31], off offset:1792
	global_store_dwordx4 v[66:67], v[32:35], off offset:2048
	global_store_dwordx4 v[66:67], v[36:39], off offset:2304
	global_store_dwordx4 v[66:67], v[40:43], off offset:2560
	global_store_dwordx4 v[66:67], v[44:47], off offset:2816
	global_store_dwordx4 v[66:67], v[48:51], off offset:3072
	global_store_dwordx4 v[66:67], v[52:55], off offset:3328
	global_store_dwordx4 v[66:67], v[56:59], off offset:3584
	global_store_dwordx4 v[66:67], v[60:63], off offset:3840
	s_waitcnt vmcnt(16)
	s_branch .LBB0_663
.Lcpstage_w47:
	s_waitcnt vmcnt(0)
	s_branch .LBB0_663
